# v21: v20 + second-K-tile LDS read bases folded into ds_read offsets (last 2 per-iteration VALU adds removed from all 10 K-loops)
# baseline (speedup 1.0000x reference)
; #define PG8_STAGE(bufoff, gbase, voff) do { _Pragma("unroll") for (int _i = 0; _i < 2; ++_i) \
;         __builtin_amdgcn_global_load_lds((const unsigned*)((const char*)(gbase) + (voff)[_i]), (PG8_LAS unsigned*)(lds + (bufoff) + ldsw + _i * 8192), 16, 0, 0); } while (0)
; #define PG8_LDA(dst, b, h) do { _Pragma("unroll") for (int m = 0; m < 4; ++m) _Pragma("unroll") for (int k = 0; k < 2; ++k) dst[m][k] = *(const PG8_LAS bf16x8*)(lds + PG8_SA(b, h) + aoff + m * 2048 + k * 1024); } while (0)
; #define PG8_LDB(dst, b, h) do { _Pragma("unroll") for (int n = 0; n < 2; ++n) _Pragma("unroll") for (int k = 0; k < 2; ++k) dst[n][k] = *(const PG8_LAS bf16x8*)(lds + PG8_SB(b, h) + boff + n * 2048 + k * 1024); } while (0)
; #define PG8_MMA(ai, bj, At, Bt) do { __builtin_amdgcn_s_setprio(1); _Pragma("unroll") for (int m = 0; m < 4; ++m) _Pragma("unroll") for (int n = 0; n < 2; ++n) _Pragma("unroll") for (int k = 0; k < 2; ++k) \
;         acc[ai][bj][m][n] = mma_<I8>(Bt[n][k], At[m][k], acc[ai][bj][m][n]); __builtin_amdgcn_s_setprio(0); } while (0)
; #define PG8_WAIT_V(n) asm volatile("s_waitcnt vmcnt(" #n ")" ::: "memory")
; #define PG8_WAIT_L(n) asm volatile("s_waitcnt lgkmcnt(" #n ")" ::: "memory")
; #define PG8_BAR __builtin_amdgcn_s_barrier()
; template <class Epi, class Sched, bool ALIGN_EPI = false, bool SP2 = false, bool I8 = false>
; __device__ __forceinline__ void gemm_phase(PG8_LAS unsigned char* lds, const Gemm g, const Sched& S, const Epi& E) {
;     ...
;             const bool last = (t == nt - 2);
;             const char* a1 = cA + (size_t)(t + 1) * kstep;
;             const char* a2 = last ? nA : cA + (size_t)(t + 2) * kstep; const char* b2 = last ? nB : cB + (size_t)(t + 2) * kstep;
;             const char* a3 = a2 + kstep; const char* b3 = b2 + kstep;
;             if (last && has_next) S.a_ready(nxt);
;             if constexpr (SP2) {
;             PG8_LDB(B0, 0, 0); PG8_LDB(B1, 0, 1); PG8_SCHED; PG8_LDA(At, 0, 0); PG8_STAGE(PG8_SA(1, 1), a1 + hstepA, voffA);
;             PG8_WAIT_V(8); PG8_WAIT_L(0); PG8_BAR; PG8_MMA(0, 0, At, B0); PG8_MMA(0, 1, At, B1); PG8_BAR; PG8_SCHED;
;             PG8_LDA(At, 0, 1); PG8_STAGE(PG8_SB(0, 0), b2, voffB); PG8_STAGE(PG8_SB(0, 1), b2 + hstepB, voffB); PG8_STAGE(PG8_SA(0, 0), a2, voffA);
;             PG8_WAIT_V(8); PG8_WAIT_L(0); PG8_BAR; PG8_MMA(1, 0, At, B0); PG8_MMA(1, 1, At, B1); PG8_BAR; PG8_SCHED;
.LBB0_483:
	ds_read_b128 v[58:61], v187
	ds_read_b128 v[62:65], v187 offset:1024
	ds_read_b128 v[74:77], v187 offset:2048
	ds_read_b128 v[78:81], v187 offset:3072
	ds_read_b128 v[162:165], v188
	ds_read_b128 v[166:169], v188 offset:1024
	ds_read_b128 v[170:173], v188 offset:2048
	ds_read_b128 v[190:193], v188 offset:3072
	s_add_u32 s34, s2, 0xfff80080
	s_addc_u32 s35, s3, -1
	s_cmp_eq_u32 s40, 28
	s_cselect_b32 s37, s7, s35
	s_cselect_b32 s36, s25, s34
	s_cselect_b32 s35, s23, s39
	s_cselect_b32 s34, s33, s38
	s_add_i32 m0, s31, 0xc000
	ds_read_b128 v[194:197], v189
	ds_read_b128 v[198:201], v189 offset:1024
	ds_read_b128 v[202:205], v189 offset:2048
	ds_read_b128 v[206:209], v189 offset:3072
	ds_read_b128 v[210:213], v189 offset:4096
	ds_read_b128 v[214:217], v189 offset:5120
	ds_read_b128 v[218:221], v189 offset:6144
	ds_read_b128 v[222:225], v189 offset:7168
	global_load_lds_dwordx4 v154, s[2:3]
	s_add_i32 m0, s31, 0xe000
	s_nop 0
	global_load_lds_dwordx4 v156, s[2:3]
	s_waitcnt vmcnt(8)
	s_waitcnt lgkmcnt(0)
	s_barrier
	s_waitcnt lgkmcnt(0)
	v_mfma_i32_16x16x64_i8 v[142:145], v[58:61], v[194:197], v[142:145]
	v_mfma_i32_16x16x64_i8 v[138:141], v[74:77], v[194:197], v[138:141]
	v_mfma_i32_16x16x64_i8 v[126:129], v[58:61], v[202:205], v[126:129]
	v_mfma_i32_16x16x64_i8 v[122:125], v[74:77], v[202:205], v[122:125]
	v_mfma_i32_16x16x64_i8 v[110:113], v[58:61], v[210:213], v[110:113]
	v_mfma_i32_16x16x64_i8 v[106:109], v[74:77], v[210:213], v[106:109]
	v_mfma_i32_16x16x64_i8 v[94:97], v[58:61], v[218:221], v[94:97]
	v_mfma_i32_16x16x64_i8 v[90:93], v[74:77], v[218:221], v[90:93]
	v_mfma_i32_16x16x64_i8 v[142:145], v[62:65], v[198:201], v[142:145]
	v_mfma_i32_16x16x64_i8 v[138:141], v[78:81], v[198:201], v[138:141]
	v_mfma_i32_16x16x64_i8 v[126:129], v[62:65], v[206:209], v[126:129]
	v_mfma_i32_16x16x64_i8 v[122:125], v[78:81], v[206:209], v[122:125]
	v_mfma_i32_16x16x64_i8 v[110:113], v[62:65], v[214:217], v[110:113]
	v_mfma_i32_16x16x64_i8 v[106:109], v[78:81], v[214:217], v[106:109]
	v_mfma_i32_16x16x64_i8 v[94:97], v[62:65], v[222:225], v[94:97]
	v_mfma_i32_16x16x64_i8 v[90:93], v[78:81], v[222:225], v[90:93]
	v_mfma_i32_16x16x64_i8 v[134:137], v[162:165], v[194:197], v[134:137]
	v_mfma_i32_16x16x64_i8 v[130:133], v[170:173], v[194:197], v[130:133]
	v_mfma_i32_16x16x64_i8 v[118:121], v[162:165], v[202:205], v[118:121]
	v_mfma_i32_16x16x64_i8 v[114:117], v[170:173], v[202:205], v[114:117]
	v_mfma_i32_16x16x64_i8 v[102:105], v[162:165], v[210:213], v[102:105]
	v_mfma_i32_16x16x64_i8 v[98:101], v[170:173], v[210:213], v[98:101]
	v_mfma_i32_16x16x64_i8 v[86:89], v[162:165], v[218:221], v[86:89]
	v_mfma_i32_16x16x64_i8 v[82:85], v[170:173], v[218:221], v[82:85]
	v_mfma_i32_16x16x64_i8 v[134:137], v[166:169], v[198:201], v[134:137]
	v_mfma_i32_16x16x64_i8 v[130:133], v[190:193], v[198:201], v[130:133]
	v_mfma_i32_16x16x64_i8 v[118:121], v[166:169], v[206:209], v[118:121]
	v_mfma_i32_16x16x64_i8 v[114:117], v[190:193], v[206:209], v[114:117]
	v_mfma_i32_16x16x64_i8 v[102:105], v[166:169], v[214:217], v[102:105]
	v_mfma_i32_16x16x64_i8 v[98:101], v[190:193], v[214:217], v[98:101]
	v_mfma_i32_16x16x64_i8 v[86:89], v[166:169], v[222:225], v[86:89]
	v_mfma_i32_16x16x64_i8 v[82:85], v[190:193], v[222:225], v[82:85]
	s_barrier
	s_add_i32 s41, s8, s68
	s_mov_b64 s[98:99], s[34:35]
	s_mov_b32 m0, s41
	ds_read_b128 v[194:197], v189 offset:16384
	ds_read_b128 v[198:201], v189 offset:17408
	ds_read_b128 v[202:205], v189 offset:18432
	ds_read_b128 v[206:209], v189 offset:19456
	ds_read_b128 v[210:213], v189 offset:20480
	ds_read_b128 v[214:217], v189 offset:21504
	ds_read_b128 v[218:221], v189 offset:22528
	ds_read_b128 v[222:225], v189 offset:23552
	global_load_lds_dwordx4 v148, s[34:35]
	s_add_i32 m0, s41, 0x2000
	s_add_u32 vcc_lo, s34, 0x80000
	s_mov_b64 s[98:99], s[34:35]
	s_addc_u32 vcc_hi, s35, 0
	s_add_i32 s41, s9, s68
	global_load_lds_dwordx4 v152, s[34:35]
	s_mov_b32 m0, s41
	s_mov_b64 s[100:101], s[36:37]
	global_load_lds_dwordx4 v148, vcc
	s_add_i32 m0, s41, 0x2000
	s_nop 0
	global_load_lds_dwordx4 v152, vcc
	s_mov_b64 s[100:101], s[36:37]
	s_mov_b32 m0, s31
	s_nop 0
	global_load_lds_dwordx4 v146, s[36:37]
	s_mov_b32 m0, s69
	s_nop 0
	global_load_lds_dwordx4 v150, s[36:37]
	s_waitcnt vmcnt(8)
	s_waitcnt lgkmcnt(0)
	s_barrier
	s_waitcnt lgkmcnt(0)
	v_mfma_i32_16x16x64_i8 v[70:73], v[58:61], v[194:197], v[70:73]
	v_mfma_i32_16x16x64_i8 v[66:69], v[74:77], v[194:197], v[66:69]
	v_mfma_i32_16x16x64_i8 v[46:49], v[58:61], v[202:205], v[46:49]
	v_mfma_i32_16x16x64_i8 v[42:45], v[74:77], v[202:205], v[42:45]
	v_mfma_i32_16x16x64_i8 v[30:33], v[58:61], v[210:213], v[30:33]
	v_mfma_i32_16x16x64_i8 v[26:29], v[74:77], v[210:213], v[26:29]
	v_mfma_i32_16x16x64_i8 v[14:17], v[58:61], v[218:221], v[14:17]
	v_mfma_i32_16x16x64_i8 v[10:13], v[74:77], v[218:221], v[10:13]
	v_mfma_i32_16x16x64_i8 v[70:73], v[62:65], v[198:201], v[70:73]
	v_mfma_i32_16x16x64_i8 v[66:69], v[78:81], v[198:201], v[66:69]
	v_mfma_i32_16x16x64_i8 v[46:49], v[62:65], v[206:209], v[46:49]
	v_mfma_i32_16x16x64_i8 v[42:45], v[78:81], v[206:209], v[42:45]
	v_mfma_i32_16x16x64_i8 v[30:33], v[62:65], v[214:217], v[30:33]
	v_mfma_i32_16x16x64_i8 v[26:29], v[78:81], v[214:217], v[26:29]
	v_mfma_i32_16x16x64_i8 v[14:17], v[62:65], v[222:225], v[14:17]
	v_mfma_i32_16x16x64_i8 v[10:13], v[78:81], v[222:225], v[10:13]
	v_mfma_i32_16x16x64_i8 v[54:57], v[162:165], v[194:197], v[54:57]
	v_mfma_i32_16x16x64_i8 v[50:53], v[170:173], v[194:197], v[50:53]
	v_mfma_i32_16x16x64_i8 v[38:41], v[162:165], v[202:205], v[38:41]
	v_mfma_i32_16x16x64_i8 v[34:37], v[170:173], v[202:205], v[34:37]
	v_mfma_i32_16x16x64_i8 v[22:25], v[162:165], v[210:213], v[22:25]
	v_mfma_i32_16x16x64_i8 v[18:21], v[170:173], v[210:213], v[18:21]
	v_mfma_i32_16x16x64_i8 v[6:9], v[162:165], v[218:221], v[6:9]
	v_mfma_i32_16x16x64_i8 v[2:5], v[170:173], v[218:221], v[2:5]
	v_mfma_i32_16x16x64_i8 v[54:57], v[166:169], v[198:201], v[54:57]
	v_mfma_i32_16x16x64_i8 v[50:53], v[190:193], v[198:201], v[50:53]
	v_mfma_i32_16x16x64_i8 v[38:41], v[166:169], v[206:209], v[38:41]
	v_mfma_i32_16x16x64_i8 v[34:37], v[190:193], v[206:209], v[34:37]
	v_mfma_i32_16x16x64_i8 v[22:25], v[166:169], v[214:217], v[22:25]
	v_mfma_i32_16x16x64_i8 v[18:21], v[190:193], v[214:217], v[18:21]
	v_mfma_i32_16x16x64_i8 v[6:9], v[166:169], v[222:225], v[6:9]
	v_mfma_i32_16x16x64_i8 v[2:5], v[190:193], v[222:225], v[2:5]
	s_barrier
; #define PG8_STAGE(bufoff, gbase, voff) do { _Pragma("unroll") for (int _i = 0; _i < 2; ++_i) \
;         __builtin_amdgcn_global_load_lds((const unsigned*)((const char*)(gbase) + (voff)[_i]), (PG8_LAS unsigned*)(lds + (bufoff) + ldsw + _i * 8192), 16, 0, 0); } while (0)
; #define PG8_LDA(dst, b, h) do { _Pragma("unroll") for (int m = 0; m < 4; ++m) _Pragma("unroll") for (int k = 0; k < 2; ++k) dst[m][k] = *(const PG8_LAS bf16x8*)(lds + PG8_SA(b, h) + aoff + m * 2048 + k * 1024); } while (0)
; #define PG8_WAIT_V(n) asm volatile("s_waitcnt vmcnt(" #n ")" ::: "memory")
; #define PG8_WAIT_L(n) asm volatile("s_waitcnt lgkmcnt(" #n ")" ::: "memory")
; #define PG8_BAR __builtin_amdgcn_s_barrier()
; template <class Epi, class Sched, bool ALIGN_EPI = false, bool SP2 = false, bool I8 = false>
; __device__ __forceinline__ void gemm_phase(PG8_LAS unsigned char* lds, const Gemm g, const Sched& S, const Epi& E) {
;     ...
;         for (int t = 0; t < nt; t += 2) {
;             const bool last = (t == nt - 2);
;             const char* a1 = cA + (size_t)(t + 1) * kstep;
;             const char* a2 = last ? nA : cA + (size_t)(t + 2) * kstep; const char* b2 = last ? nB : cB + (size_t)(t + 2) * kstep;
;             const char* a3 = a2 + kstep; const char* b3 = b2 + kstep;
;             if (last && has_next) S.a_ready(nxt);
;             if constexpr (SP2) {
;             PG8_LDB(B0, 0, 0); PG8_LDB(B1, 0, 1); PG8_SCHED; PG8_LDA(At, 0, 0); PG8_STAGE(PG8_SA(1, 1), a1 + hstepA, voffA);
;             PG8_WAIT_V(8); PG8_WAIT_L(0); PG8_BAR; PG8_MMA(0, 0, At, B0); PG8_MMA(0, 1, At, B1); PG8_BAR; PG8_SCHED;
;             PG8_LDA(At, 0, 1); PG8_STAGE(PG8_SB(0, 0), b2, voffB); PG8_STAGE(PG8_SB(0, 1), b2 + hstepB, voffB); PG8_STAGE(PG8_SA(0, 0), a2, voffA);
;             PG8_WAIT_V(8); PG8_WAIT_L(0); PG8_BAR; PG8_MMA(1, 0, At, B0); PG8_MMA(1, 1, At, B1); PG8_BAR; PG8_SCHED;
;             PG8_LDB(B0, 1, 0); PG8_LDB(B1, 1, 1); PG8_SCHED; PG8_LDA(At, 1, 0); PG8_STAGE(PG8_SA(0, 1), a2 + hstepA, voffA);
;             PG8_WAIT_V(8); PG8_WAIT_L(0); PG8_BAR; PG8_MMA(0, 0, At, B0); PG8_MMA(0, 1, At, B1); PG8_BAR; PG8_SCHED;
;             PG8_LDA(At, 1, 1); PG8_STAGE(PG8_SB(1, 0), b3, voffB); PG8_STAGE(PG8_SB(1, 1), b3 + hstepB, voffB); PG8_STAGE(PG8_SA(1, 0), a3, voffA);
;             PG8_WAIT_V(8); PG8_WAIT_L(0); PG8_BAR; PG8_MMA(1, 0, At, B0); PG8_MMA(1, 1, At, B1); PG8_BAR; PG8_SCHED;
	s_add_i32 s41, 0, 0x18000
	s_add_i32 s95, 0, 0x1c000
	ds_read_b128 v[58:61], v188 offset:16384
	ds_read_b128 v[62:65], v188 offset:17408
	ds_read_b128 v[74:77], v188 offset:18432
	ds_read_b128 v[78:81], v188 offset:19456
	ds_read_b128 v[162:165], v188 offset:32768
	ds_read_b128 v[166:169], v188 offset:33792
	ds_read_b128 v[170:173], v188 offset:34816
	ds_read_b128 v[190:193], v188 offset:35840
	s_add_u32 s36, s36, 0x80000
	s_addc_u32 s37, s37, 0
	s_mov_b32 m0, s70
	ds_read_b128 v[194:197], v189 offset:32768
	ds_read_b128 v[198:201], v189 offset:33792
	ds_read_b128 v[202:205], v189 offset:34816
	ds_read_b128 v[206:209], v189 offset:35840
	ds_read_b128 v[210:213], v189 offset:36864
	ds_read_b128 v[214:217], v189 offset:37888
	ds_read_b128 v[218:221], v189 offset:38912
	ds_read_b128 v[222:225], v189 offset:39936
	global_load_lds_dwordx4 v146, s[36:37]
	s_mov_b32 m0, s71
	s_nop 0
	global_load_lds_dwordx4 v150, s[36:37]
	s_waitcnt vmcnt(8)
	s_waitcnt lgkmcnt(0)
	s_barrier
	s_waitcnt lgkmcnt(0)
	v_mfma_i32_16x16x64_i8 v[142:145], v[58:61], v[194:197], v[142:145]
	v_mfma_i32_16x16x64_i8 v[138:141], v[74:77], v[194:197], v[138:141]
	v_mfma_i32_16x16x64_i8 v[126:129], v[58:61], v[202:205], v[126:129]
	v_mfma_i32_16x16x64_i8 v[122:125], v[74:77], v[202:205], v[122:125]
	v_mfma_i32_16x16x64_i8 v[110:113], v[58:61], v[210:213], v[110:113]
	v_mfma_i32_16x16x64_i8 v[106:109], v[74:77], v[210:213], v[106:109]
	v_mfma_i32_16x16x64_i8 v[94:97], v[58:61], v[218:221], v[94:97]
	v_mfma_i32_16x16x64_i8 v[90:93], v[74:77], v[218:221], v[90:93]
	v_mfma_i32_16x16x64_i8 v[142:145], v[62:65], v[198:201], v[142:145]
	v_mfma_i32_16x16x64_i8 v[138:141], v[78:81], v[198:201], v[138:141]
	v_mfma_i32_16x16x64_i8 v[126:129], v[62:65], v[206:209], v[126:129]
	v_mfma_i32_16x16x64_i8 v[122:125], v[78:81], v[206:209], v[122:125]
	v_mfma_i32_16x16x64_i8 v[110:113], v[62:65], v[214:217], v[110:113]
	v_mfma_i32_16x16x64_i8 v[106:109], v[78:81], v[214:217], v[106:109]
	v_mfma_i32_16x16x64_i8 v[94:97], v[62:65], v[222:225], v[94:97]
	v_mfma_i32_16x16x64_i8 v[90:93], v[78:81], v[222:225], v[90:93]
	v_mfma_i32_16x16x64_i8 v[134:137], v[162:165], v[194:197], v[134:137]
	v_mfma_i32_16x16x64_i8 v[130:133], v[170:173], v[194:197], v[130:133]
	v_mfma_i32_16x16x64_i8 v[118:121], v[162:165], v[202:205], v[118:121]
	v_mfma_i32_16x16x64_i8 v[114:117], v[170:173], v[202:205], v[114:117]
	v_mfma_i32_16x16x64_i8 v[102:105], v[162:165], v[210:213], v[102:105]
	v_mfma_i32_16x16x64_i8 v[98:101], v[170:173], v[210:213], v[98:101]
	v_mfma_i32_16x16x64_i8 v[86:89], v[162:165], v[218:221], v[86:89]
	v_mfma_i32_16x16x64_i8 v[82:85], v[170:173], v[218:221], v[82:85]
	v_mfma_i32_16x16x64_i8 v[134:137], v[166:169], v[198:201], v[134:137]
	v_mfma_i32_16x16x64_i8 v[130:133], v[190:193], v[198:201], v[130:133]
	v_mfma_i32_16x16x64_i8 v[118:121], v[166:169], v[206:209], v[118:121]
	v_mfma_i32_16x16x64_i8 v[114:117], v[190:193], v[206:209], v[114:117]
	v_mfma_i32_16x16x64_i8 v[102:105], v[166:169], v[214:217], v[102:105]
	v_mfma_i32_16x16x64_i8 v[98:101], v[190:193], v[214:217], v[98:101]
	v_mfma_i32_16x16x64_i8 v[86:89], v[166:169], v[222:225], v[86:89]
	v_mfma_i32_16x16x64_i8 v[82:85], v[190:193], v[222:225], v[82:85]
	s_barrier
	s_add_i32 s36, s41, s68
	s_add_i32 m0, s36, 0xffffff80
	ds_read_b128 v[194:197], v189 offset:49152
	ds_read_b128 v[198:201], v189 offset:50176
	ds_read_b128 v[202:205], v189 offset:51200
	ds_read_b128 v[206:209], v189 offset:52224
	ds_read_b128 v[210:213], v189 offset:53248
	ds_read_b128 v[214:217], v189 offset:54272
	ds_read_b128 v[218:221], v189 offset:55296
	ds_read_b128 v[222:225], v189 offset:56320
	global_load_lds_dwordx4 v148, s[98:99] offset:128
	s_add_i32 m0, s36, 0x1f80
	s_add_u32 s34, s34, 0x80080
	s_addc_u32 s35, s35, 0
	s_add_i32 s36, s95, s68
	global_load_lds_dwordx4 v152, s[98:99] offset:128
	s_mov_b32 m0, s36
	s_nop 0
	global_load_lds_dwordx4 v148, s[34:35]
	s_add_i32 m0, s36, 0x2000
	s_nop 0
	global_load_lds_dwordx4 v152, s[34:35]
	s_add_i32 m0, s89, 0xffffff80
	s_nop 0
	global_load_lds_dwordx4 v146, s[100:101] offset:128
	s_add_i32 m0, s92, 0xffffff80
	s_nop 0
	global_load_lds_dwordx4 v150, s[100:101] offset:128
	s_waitcnt vmcnt(8)
	s_waitcnt lgkmcnt(0)
	s_barrier
	s_waitcnt lgkmcnt(0)
	v_mfma_i32_16x16x64_i8 v[70:73], v[58:61], v[194:197], v[70:73]
	v_mfma_i32_16x16x64_i8 v[66:69], v[74:77], v[194:197], v[66:69]
	v_mfma_i32_16x16x64_i8 v[46:49], v[58:61], v[202:205], v[46:49]
	v_mfma_i32_16x16x64_i8 v[42:45], v[74:77], v[202:205], v[42:45]
	v_mfma_i32_16x16x64_i8 v[30:33], v[58:61], v[210:213], v[30:33]
	v_mfma_i32_16x16x64_i8 v[26:29], v[74:77], v[210:213], v[26:29]
	v_mfma_i32_16x16x64_i8 v[14:17], v[58:61], v[218:221], v[14:17]
	v_mfma_i32_16x16x64_i8 v[10:13], v[74:77], v[218:221], v[10:13]
	v_mfma_i32_16x16x64_i8 v[70:73], v[62:65], v[198:201], v[70:73]
	v_mfma_i32_16x16x64_i8 v[66:69], v[78:81], v[198:201], v[66:69]
	v_mfma_i32_16x16x64_i8 v[46:49], v[62:65], v[206:209], v[46:49]
	v_mfma_i32_16x16x64_i8 v[42:45], v[78:81], v[206:209], v[42:45]
	v_mfma_i32_16x16x64_i8 v[30:33], v[62:65], v[214:217], v[30:33]
	v_mfma_i32_16x16x64_i8 v[26:29], v[78:81], v[214:217], v[26:29]
	v_mfma_i32_16x16x64_i8 v[14:17], v[62:65], v[222:225], v[14:17]
	v_mfma_i32_16x16x64_i8 v[10:13], v[78:81], v[222:225], v[10:13]
	v_mfma_i32_16x16x64_i8 v[54:57], v[162:165], v[194:197], v[54:57]
	v_mfma_i32_16x16x64_i8 v[50:53], v[170:173], v[194:197], v[50:53]
	v_mfma_i32_16x16x64_i8 v[38:41], v[162:165], v[202:205], v[38:41]
	v_mfma_i32_16x16x64_i8 v[34:37], v[170:173], v[202:205], v[34:37]
	v_mfma_i32_16x16x64_i8 v[22:25], v[162:165], v[210:213], v[22:25]
	v_mfma_i32_16x16x64_i8 v[18:21], v[170:173], v[210:213], v[18:21]
	v_mfma_i32_16x16x64_i8 v[6:9], v[162:165], v[218:221], v[6:9]
	v_mfma_i32_16x16x64_i8 v[2:5], v[170:173], v[218:221], v[2:5]
	v_mfma_i32_16x16x64_i8 v[54:57], v[166:169], v[198:201], v[54:57]
	v_mfma_i32_16x16x64_i8 v[50:53], v[190:193], v[198:201], v[50:53]
	v_mfma_i32_16x16x64_i8 v[38:41], v[166:169], v[206:209], v[38:41]
	v_mfma_i32_16x16x64_i8 v[34:37], v[190:193], v[206:209], v[34:37]
	v_mfma_i32_16x16x64_i8 v[22:25], v[166:169], v[214:217], v[22:25]
	v_mfma_i32_16x16x64_i8 v[18:21], v[190:193], v[214:217], v[18:21]
	v_mfma_i32_16x16x64_i8 v[6:9], v[166:169], v[222:225], v[6:9]
	v_mfma_i32_16x16x64_i8 v[2:5], v[190:193], v[222:225], v[2:5]
	s_barrier
	s_add_i32 s40, s40, 2
	s_add_u32 s2, s2, 0x100
	s_addc_u32 s3, s3, 0
	s_add_u32 s38, s38, 0x100
	s_addc_u32 s39, s39, 0
	s_cmp_gt_u32 s40, 29
	s_cbranch_scc0 .LBB0_483
	s_and_b64 vcc, exec, s[20:21]
	s_cbranch_vccz .LBB0_486
	s_barrier

; #define PG8_STAGE(bufoff, gbase, voff) do { _Pragma("unroll") for (int _i = 0; _i < 2; ++_i) \
;         __builtin_amdgcn_global_load_lds((const unsigned*)((const char*)(gbase) + (voff)[_i]), (PG8_LAS unsigned*)(lds + (bufoff) + ldsw + _i * 8192), 16, 0, 0); } while (0)
; #define PG8_LDA(dst, b, h) do { _Pragma("unroll") for (int m = 0; m < 4; ++m) _Pragma("unroll") for (int k = 0; k < 2; ++k) dst[m][k] = *(const PG8_LAS bf16x8*)(lds + PG8_SA(b, h) + aoff + m * 2048 + k * 1024); } while (0)
; #define PG8_LDB(dst, b, h) do { _Pragma("unroll") for (int n = 0; n < 2; ++n) _Pragma("unroll") for (int k = 0; k < 2; ++k) dst[n][k] = *(const PG8_LAS bf16x8*)(lds + PG8_SB(b, h) + boff + n * 2048 + k * 1024); } while (0)
; #define PG8_MMA(ai, bj, At, Bt) do { __builtin_amdgcn_s_setprio(1); _Pragma("unroll") for (int m = 0; m < 4; ++m) _Pragma("unroll") for (int n = 0; n < 2; ++n) _Pragma("unroll") for (int k = 0; k < 2; ++k) \
;         acc[ai][bj][m][n] = mma_<I8>(Bt[n][k], At[m][k], acc[ai][bj][m][n]); __builtin_amdgcn_s_setprio(0); } while (0)
; #define PG8_WAIT_V(n) asm volatile("s_waitcnt vmcnt(" #n ")" ::: "memory")
; #define PG8_WAIT_L(n) asm volatile("s_waitcnt lgkmcnt(" #n ")" ::: "memory")
; #define PG8_BAR __builtin_amdgcn_s_barrier()
; template <class Epi, class Sched, bool ALIGN_EPI = false, bool SP2 = false, bool I8 = false>
; __device__ __forceinline__ void gemm_phase(PG8_LAS unsigned char* lds, const Gemm g, const Sched& S, const Epi& E) {
;     ...
;             const bool last = (t == nt - 2);
;             const char* a1 = cA + (size_t)(t + 1) * kstep;
;             const char* a2 = last ? nA : cA + (size_t)(t + 2) * kstep; const char* b2 = last ? nB : cB + (size_t)(t + 2) * kstep;
;             const char* a3 = a2 + kstep; const char* b3 = b2 + kstep;
;             if (last && has_next) S.a_ready(nxt);
;             if constexpr (SP2) {
;             PG8_LDB(B0, 0, 0); PG8_LDB(B1, 0, 1); PG8_SCHED; PG8_LDA(At, 0, 0); PG8_STAGE(PG8_SA(1, 1), a1 + hstepA, voffA);
;             PG8_WAIT_V(8); PG8_WAIT_L(0); PG8_BAR; PG8_MMA(0, 0, At, B0); PG8_MMA(0, 1, At, B1); PG8_BAR; PG8_SCHED;
;             PG8_LDA(At, 0, 1); PG8_STAGE(PG8_SB(0, 0), b2, voffB); PG8_STAGE(PG8_SB(0, 1), b2 + hstepB, voffB); PG8_STAGE(PG8_SA(0, 0), a2, voffA);
;             PG8_WAIT_V(8); PG8_WAIT_L(0); PG8_BAR; PG8_MMA(1, 0, At, B0); PG8_MMA(1, 1, At, B1); PG8_BAR; PG8_SCHED;
.LBB0_541:
	ds_read_b128 v[154:157], v149
	ds_read_b128 v[158:161], v149 offset:1024
	ds_read_b128 v[162:165], v149 offset:2048
	ds_read_b128 v[166:169], v149 offset:3072
	ds_read_b128 v[170:173], v151
	ds_read_b128 v[174:177], v151 offset:1024
	ds_read_b128 v[178:181], v151 offset:2048
	ds_read_b128 v[188:191], v151 offset:3072
	s_add_u32 s34, s30, 0xfff00080
	s_addc_u32 s35, s31, -1
	s_cmp_eq_u32 s94, 60
	s_cselect_b32 s37, s7, s35
	s_cselect_b32 s36, s25, s34
	s_cselect_b32 s35, s23, s93
	s_cselect_b32 s34, s29, s92
	s_add_i32 m0, s39, 0xc000
	ds_read_b128 v[192:195], v153
	ds_read_b128 v[196:199], v153 offset:1024
	ds_read_b128 v[200:203], v153 offset:2048
	ds_read_b128 v[204:207], v153 offset:3072
	ds_read_b128 v[208:211], v153 offset:4096
	ds_read_b128 v[212:215], v153 offset:5120
	ds_read_b128 v[216:219], v153 offset:6144
	ds_read_b128 v[220:223], v153 offset:7168
	global_load_lds_dwordx4 v138, s[30:31]
	s_add_i32 m0, s39, 0xe000
	s_nop 0
	global_load_lds_dwordx4 v140, s[30:31]
	s_waitcnt vmcnt(8)
	s_waitcnt lgkmcnt(0)
	s_barrier
	s_waitcnt lgkmcnt(0)
	v_mfma_f32_16x16x32_bf16 v[126:129], v[154:157], v[192:195], v[126:129]
	v_mfma_f32_16x16x32_bf16 v[122:125], v[162:165], v[192:195], v[122:125]
	v_mfma_f32_16x16x32_bf16 v[110:113], v[154:157], v[200:203], v[110:113]
	v_mfma_f32_16x16x32_bf16 v[106:109], v[162:165], v[200:203], v[106:109]
	v_mfma_f32_16x16x32_bf16 v[94:97], v[154:157], v[208:211], v[94:97]
	v_mfma_f32_16x16x32_bf16 v[90:93], v[162:165], v[208:211], v[90:93]
	v_mfma_f32_16x16x32_bf16 v[78:81], v[154:157], v[216:219], v[78:81]
	v_mfma_f32_16x16x32_bf16 v[74:77], v[162:165], v[216:219], v[74:77]
	v_mfma_f32_16x16x32_bf16 v[126:129], v[158:161], v[196:199], v[126:129]
	v_mfma_f32_16x16x32_bf16 v[122:125], v[166:169], v[196:199], v[122:125]
	v_mfma_f32_16x16x32_bf16 v[110:113], v[158:161], v[204:207], v[110:113]
	v_mfma_f32_16x16x32_bf16 v[106:109], v[166:169], v[204:207], v[106:109]
	v_mfma_f32_16x16x32_bf16 v[94:97], v[158:161], v[212:215], v[94:97]
	v_mfma_f32_16x16x32_bf16 v[90:93], v[166:169], v[212:215], v[90:93]
	v_mfma_f32_16x16x32_bf16 v[78:81], v[158:161], v[220:223], v[78:81]
	v_mfma_f32_16x16x32_bf16 v[74:77], v[166:169], v[220:223], v[74:77]
	v_mfma_f32_16x16x32_bf16 v[118:121], v[170:173], v[192:195], v[118:121]
	v_mfma_f32_16x16x32_bf16 v[114:117], v[178:181], v[192:195], v[114:117]
	v_mfma_f32_16x16x32_bf16 v[102:105], v[170:173], v[200:203], v[102:105]
	v_mfma_f32_16x16x32_bf16 v[98:101], v[178:181], v[200:203], v[98:101]
	v_mfma_f32_16x16x32_bf16 v[86:89], v[170:173], v[208:211], v[86:89]
	v_mfma_f32_16x16x32_bf16 v[82:85], v[178:181], v[208:211], v[82:85]
	v_mfma_f32_16x16x32_bf16 v[70:73], v[170:173], v[216:219], v[70:73]
	v_mfma_f32_16x16x32_bf16 v[66:69], v[178:181], v[216:219], v[66:69]
	v_mfma_f32_16x16x32_bf16 v[118:121], v[174:177], v[196:199], v[118:121]
	v_mfma_f32_16x16x32_bf16 v[114:117], v[188:191], v[196:199], v[114:117]
	v_mfma_f32_16x16x32_bf16 v[102:105], v[174:177], v[204:207], v[102:105]
	v_mfma_f32_16x16x32_bf16 v[98:101], v[188:191], v[204:207], v[98:101]
	v_mfma_f32_16x16x32_bf16 v[86:89], v[174:177], v[212:215], v[86:89]
	v_mfma_f32_16x16x32_bf16 v[82:85], v[188:191], v[212:215], v[82:85]
	v_mfma_f32_16x16x32_bf16 v[70:73], v[174:177], v[220:223], v[70:73]
	v_mfma_f32_16x16x32_bf16 v[66:69], v[188:191], v[220:223], v[66:69]
	s_barrier
	s_add_i32 s95, s88, s38
	s_mov_b64 s[98:99], s[34:35]
	s_mov_b32 m0, s95
	ds_read_b128 v[192:195], v153 offset:16384
	ds_read_b128 v[196:199], v153 offset:17408
	ds_read_b128 v[200:203], v153 offset:18432
	ds_read_b128 v[204:207], v153 offset:19456
	ds_read_b128 v[208:211], v153 offset:20480
	ds_read_b128 v[212:215], v153 offset:21504
	ds_read_b128 v[216:219], v153 offset:22528
	ds_read_b128 v[220:223], v153 offset:23552
	global_load_lds_dwordx4 v132, s[34:35]
	s_add_i32 m0, s95, 0x2000
	s_add_u32 vcc_lo, s34, 0x100000
	s_mov_b64 s[98:99], s[34:35]
	s_addc_u32 vcc_hi, s35, 0
	s_add_i32 s95, s89, s38
	global_load_lds_dwordx4 v136, s[34:35]
	s_mov_b32 m0, s95
	s_mov_b64 s[100:101], s[36:37]
	global_load_lds_dwordx4 v132, vcc
	s_add_i32 m0, s95, 0x2000
	s_nop 0
	global_load_lds_dwordx4 v136, vcc
	s_mov_b64 s[100:101], s[36:37]
	s_mov_b32 m0, s39
	s_nop 0
	global_load_lds_dwordx4 v130, s[36:37]
	s_mov_b32 m0, s40
	s_nop 0
	global_load_lds_dwordx4 v134, s[36:37]
	s_waitcnt vmcnt(8)
	s_waitcnt lgkmcnt(0)
	s_barrier
	s_waitcnt lgkmcnt(0)
	v_mfma_f32_16x16x32_bf16 v[62:65], v[154:157], v[192:195], v[62:65]
	v_mfma_f32_16x16x32_bf16 v[58:61], v[162:165], v[192:195], v[58:61]
	v_mfma_f32_16x16x32_bf16 v[46:49], v[154:157], v[200:203], v[46:49]
	v_mfma_f32_16x16x32_bf16 v[42:45], v[162:165], v[200:203], v[42:45]
	v_mfma_f32_16x16x32_bf16 v[30:33], v[154:157], v[208:211], v[30:33]
	v_mfma_f32_16x16x32_bf16 v[26:29], v[162:165], v[208:211], v[26:29]
	v_mfma_f32_16x16x32_bf16 v[14:17], v[154:157], v[216:219], v[14:17]
	v_mfma_f32_16x16x32_bf16 v[10:13], v[162:165], v[216:219], v[10:13]
	v_mfma_f32_16x16x32_bf16 v[62:65], v[158:161], v[196:199], v[62:65]
	v_mfma_f32_16x16x32_bf16 v[58:61], v[166:169], v[196:199], v[58:61]
	v_mfma_f32_16x16x32_bf16 v[46:49], v[158:161], v[204:207], v[46:49]
	v_mfma_f32_16x16x32_bf16 v[42:45], v[166:169], v[204:207], v[42:45]
	v_mfma_f32_16x16x32_bf16 v[30:33], v[158:161], v[212:215], v[30:33]
	v_mfma_f32_16x16x32_bf16 v[26:29], v[166:169], v[212:215], v[26:29]
	v_mfma_f32_16x16x32_bf16 v[14:17], v[158:161], v[220:223], v[14:17]
	v_mfma_f32_16x16x32_bf16 v[10:13], v[166:169], v[220:223], v[10:13]
	v_mfma_f32_16x16x32_bf16 v[54:57], v[170:173], v[192:195], v[54:57]
	v_mfma_f32_16x16x32_bf16 v[50:53], v[178:181], v[192:195], v[50:53]
	v_mfma_f32_16x16x32_bf16 v[38:41], v[170:173], v[200:203], v[38:41]
	v_mfma_f32_16x16x32_bf16 v[34:37], v[178:181], v[200:203], v[34:37]
	v_mfma_f32_16x16x32_bf16 v[22:25], v[170:173], v[208:211], v[22:25]
	v_mfma_f32_16x16x32_bf16 v[18:21], v[178:181], v[208:211], v[18:21]
	v_mfma_f32_16x16x32_bf16 v[6:9], v[170:173], v[216:219], v[6:9]
	v_mfma_f32_16x16x32_bf16 v[2:5], v[178:181], v[216:219], v[2:5]
	v_mfma_f32_16x16x32_bf16 v[54:57], v[174:177], v[196:199], v[54:57]
	v_mfma_f32_16x16x32_bf16 v[50:53], v[188:191], v[196:199], v[50:53]
	v_mfma_f32_16x16x32_bf16 v[38:41], v[174:177], v[204:207], v[38:41]
	v_mfma_f32_16x16x32_bf16 v[34:37], v[188:191], v[204:207], v[34:37]
	v_mfma_f32_16x16x32_bf16 v[22:25], v[174:177], v[212:215], v[22:25]
	v_mfma_f32_16x16x32_bf16 v[18:21], v[188:191], v[212:215], v[18:21]
	v_mfma_f32_16x16x32_bf16 v[6:9], v[174:177], v[220:223], v[6:9]
	v_mfma_f32_16x16x32_bf16 v[2:5], v[188:191], v[220:223], v[2:5]
	s_barrier
; #define PG8_STAGE(bufoff, gbase, voff) do { _Pragma("unroll") for (int _i = 0; _i < 2; ++_i) \
;         __builtin_amdgcn_global_load_lds((const unsigned*)((const char*)(gbase) + (voff)[_i]), (PG8_LAS unsigned*)(lds + (bufoff) + ldsw + _i * 8192), 16, 0, 0); } while (0)
; #define PG8_LDA(dst, b, h) do { _Pragma("unroll") for (int m = 0; m < 4; ++m) _Pragma("unroll") for (int k = 0; k < 2; ++k) dst[m][k] = *(const PG8_LAS bf16x8*)(lds + PG8_SA(b, h) + aoff + m * 2048 + k * 1024); } while (0)
; #define PG8_LDB(dst, b, h) do { _Pragma("unroll") for (int n = 0; n < 2; ++n) _Pragma("unroll") for (int k = 0; k < 2; ++k) dst[n][k] = *(const PG8_LAS bf16x8*)(lds + PG8_SB(b, h) + boff + n * 2048 + k * 1024); } while (0)
; #define PG8_MMA(ai, bj, At, Bt) do { __builtin_amdgcn_s_setprio(1); _Pragma("unroll") for (int m = 0; m < 4; ++m) _Pragma("unroll") for (int n = 0; n < 2; ++n) _Pragma("unroll") for (int k = 0; k < 2; ++k) \
;         acc[ai][bj][m][n] = mma_<I8>(Bt[n][k], At[m][k], acc[ai][bj][m][n]); __builtin_amdgcn_s_setprio(0); } while (0)
; #define PG8_WAIT_V(n) asm volatile("s_waitcnt vmcnt(" #n ")" ::: "memory")
; #define PG8_WAIT_L(n) asm volatile("s_waitcnt lgkmcnt(" #n ")" ::: "memory")
; #define PG8_BAR __builtin_amdgcn_s_barrier()
; #define PG8_SCHED __builtin_amdgcn_sched_barrier(0)
; template <class Epi, class Sched, bool ALIGN_EPI = false, bool SP2 = false, bool I8 = false>
; __device__ __forceinline__ void gemm_phase(PG8_LAS unsigned char* lds, const Gemm g, const Sched& S, const Epi& E) {
;     ...
;         for (int t = 0; t < nt; t += 2) {
;     ...
;             PG8_LDB(B0, 1, 0); PG8_LDB(B1, 1, 1); PG8_SCHED; PG8_LDA(At, 1, 0); PG8_STAGE(PG8_SA(0, 1), a2 + hstepA, voffA);
;             PG8_WAIT_V(8); PG8_WAIT_L(0); PG8_BAR; PG8_MMA(0, 0, At, B0); PG8_MMA(0, 1, At, B1); PG8_BAR; PG8_SCHED;
;             PG8_LDA(At, 1, 1); PG8_STAGE(PG8_SB(1, 0), b3, voffB); PG8_STAGE(PG8_SB(1, 1), b3 + hstepB, voffB); PG8_STAGE(PG8_SA(1, 0), a3, voffA);
;             PG8_WAIT_V(8); PG8_WAIT_L(0); PG8_BAR; PG8_MMA(1, 0, At, B0); PG8_MMA(1, 1, At, B1); PG8_BAR; PG8_SCHED;
	s_add_i32 s95, 0, 0x18000
	s_add_i32 vcc_lo, 0, 0x1c000
	ds_read_b128 v[154:157], v151 offset:16384
	ds_read_b128 v[158:161], v151 offset:17408
	ds_read_b128 v[162:165], v151 offset:18432
	ds_read_b128 v[166:169], v151 offset:19456
	ds_read_b128 v[170:173], v151 offset:32768
	ds_read_b128 v[174:177], v151 offset:33792
	ds_read_b128 v[178:181], v151 offset:34816
	ds_read_b128 v[188:191], v151 offset:35840
	s_add_u32 s36, s36, 0x100000
	s_addc_u32 s37, s37, 0
	s_mov_b32 m0, s41
	ds_read_b128 v[192:195], v153 offset:32768
	ds_read_b128 v[196:199], v153 offset:33792
	ds_read_b128 v[200:203], v153 offset:34816
	ds_read_b128 v[204:207], v153 offset:35840
	ds_read_b128 v[208:211], v153 offset:36864
	ds_read_b128 v[212:215], v153 offset:37888
	ds_read_b128 v[216:219], v153 offset:38912
	ds_read_b128 v[220:223], v153 offset:39936
	global_load_lds_dwordx4 v130, s[36:37]
	s_mov_b32 m0, s46
	s_nop 0
	global_load_lds_dwordx4 v134, s[36:37]
	s_waitcnt vmcnt(8)
	s_waitcnt lgkmcnt(0)
	s_barrier
	s_waitcnt lgkmcnt(0)
	v_mfma_f32_16x16x32_bf16 v[126:129], v[154:157], v[192:195], v[126:129]
	v_mfma_f32_16x16x32_bf16 v[122:125], v[162:165], v[192:195], v[122:125]
	v_mfma_f32_16x16x32_bf16 v[110:113], v[154:157], v[200:203], v[110:113]
	v_mfma_f32_16x16x32_bf16 v[106:109], v[162:165], v[200:203], v[106:109]
	v_mfma_f32_16x16x32_bf16 v[94:97], v[154:157], v[208:211], v[94:97]
	v_mfma_f32_16x16x32_bf16 v[90:93], v[162:165], v[208:211], v[90:93]
	v_mfma_f32_16x16x32_bf16 v[78:81], v[154:157], v[216:219], v[78:81]
	v_mfma_f32_16x16x32_bf16 v[74:77], v[162:165], v[216:219], v[74:77]
	v_mfma_f32_16x16x32_bf16 v[126:129], v[158:161], v[196:199], v[126:129]
	v_mfma_f32_16x16x32_bf16 v[122:125], v[166:169], v[196:199], v[122:125]
	v_mfma_f32_16x16x32_bf16 v[110:113], v[158:161], v[204:207], v[110:113]
	v_mfma_f32_16x16x32_bf16 v[106:109], v[166:169], v[204:207], v[106:109]
	v_mfma_f32_16x16x32_bf16 v[94:97], v[158:161], v[212:215], v[94:97]
	v_mfma_f32_16x16x32_bf16 v[90:93], v[166:169], v[212:215], v[90:93]
	v_mfma_f32_16x16x32_bf16 v[78:81], v[158:161], v[220:223], v[78:81]
	v_mfma_f32_16x16x32_bf16 v[74:77], v[166:169], v[220:223], v[74:77]
	v_mfma_f32_16x16x32_bf16 v[118:121], v[170:173], v[192:195], v[118:121]
	v_mfma_f32_16x16x32_bf16 v[114:117], v[178:181], v[192:195], v[114:117]
	v_mfma_f32_16x16x32_bf16 v[102:105], v[170:173], v[200:203], v[102:105]
	v_mfma_f32_16x16x32_bf16 v[98:101], v[178:181], v[200:203], v[98:101]
	v_mfma_f32_16x16x32_bf16 v[86:89], v[170:173], v[208:211], v[86:89]
	v_mfma_f32_16x16x32_bf16 v[82:85], v[178:181], v[208:211], v[82:85]
	v_mfma_f32_16x16x32_bf16 v[70:73], v[170:173], v[216:219], v[70:73]
	v_mfma_f32_16x16x32_bf16 v[66:69], v[178:181], v[216:219], v[66:69]
	v_mfma_f32_16x16x32_bf16 v[118:121], v[174:177], v[196:199], v[118:121]
	v_mfma_f32_16x16x32_bf16 v[114:117], v[188:191], v[196:199], v[114:117]
	v_mfma_f32_16x16x32_bf16 v[102:105], v[174:177], v[204:207], v[102:105]
	v_mfma_f32_16x16x32_bf16 v[98:101], v[188:191], v[204:207], v[98:101]
	v_mfma_f32_16x16x32_bf16 v[86:89], v[174:177], v[212:215], v[86:89]
	v_mfma_f32_16x16x32_bf16 v[82:85], v[188:191], v[212:215], v[82:85]
	v_mfma_f32_16x16x32_bf16 v[70:73], v[174:177], v[220:223], v[70:73]
	v_mfma_f32_16x16x32_bf16 v[66:69], v[188:191], v[220:223], v[66:69]
	s_barrier
	s_add_i32 s36, s95, s38
	s_add_i32 m0, s36, 0xffffff80
	ds_read_b128 v[192:195], v153 offset:49152
	ds_read_b128 v[196:199], v153 offset:50176
	ds_read_b128 v[200:203], v153 offset:51200
	ds_read_b128 v[204:207], v153 offset:52224
	ds_read_b128 v[208:211], v153 offset:53248
	ds_read_b128 v[212:215], v153 offset:54272
	ds_read_b128 v[216:219], v153 offset:55296
	ds_read_b128 v[220:223], v153 offset:56320
	global_load_lds_dwordx4 v132, s[98:99] offset:128
	s_add_i32 m0, s36, 0x1f80
	s_add_u32 s34, s34, 0x100080
	s_addc_u32 s35, s35, 0
	s_add_i32 s36, vcc_lo, s38
	global_load_lds_dwordx4 v136, s[98:99] offset:128
	s_mov_b32 m0, s36
	s_nop 0
	global_load_lds_dwordx4 v132, s[34:35]
	s_add_i32 m0, s36, 0x2000
	s_nop 0
	global_load_lds_dwordx4 v136, s[34:35]
	s_add_i32 m0, s68, 0xffffff80
	s_nop 0
	global_load_lds_dwordx4 v130, s[100:101] offset:128
	s_add_i32 m0, s69, 0xffffff80
	s_nop 0
	global_load_lds_dwordx4 v134, s[100:101] offset:128
	s_waitcnt vmcnt(8)
	s_waitcnt lgkmcnt(0)
	s_barrier
	s_waitcnt lgkmcnt(0)
	v_mfma_f32_16x16x32_bf16 v[62:65], v[154:157], v[192:195], v[62:65]
	v_mfma_f32_16x16x32_bf16 v[58:61], v[162:165], v[192:195], v[58:61]
	v_mfma_f32_16x16x32_bf16 v[46:49], v[154:157], v[200:203], v[46:49]
	v_mfma_f32_16x16x32_bf16 v[42:45], v[162:165], v[200:203], v[42:45]
	v_mfma_f32_16x16x32_bf16 v[30:33], v[154:157], v[208:211], v[30:33]
	v_mfma_f32_16x16x32_bf16 v[26:29], v[162:165], v[208:211], v[26:29]
	v_mfma_f32_16x16x32_bf16 v[14:17], v[154:157], v[216:219], v[14:17]
	v_mfma_f32_16x16x32_bf16 v[10:13], v[162:165], v[216:219], v[10:13]
	v_mfma_f32_16x16x32_bf16 v[62:65], v[158:161], v[196:199], v[62:65]
	v_mfma_f32_16x16x32_bf16 v[58:61], v[166:169], v[196:199], v[58:61]
	v_mfma_f32_16x16x32_bf16 v[46:49], v[158:161], v[204:207], v[46:49]
	v_mfma_f32_16x16x32_bf16 v[42:45], v[166:169], v[204:207], v[42:45]
	v_mfma_f32_16x16x32_bf16 v[30:33], v[158:161], v[212:215], v[30:33]
	v_mfma_f32_16x16x32_bf16 v[26:29], v[166:169], v[212:215], v[26:29]
	v_mfma_f32_16x16x32_bf16 v[14:17], v[158:161], v[220:223], v[14:17]
	v_mfma_f32_16x16x32_bf16 v[10:13], v[166:169], v[220:223], v[10:13]
	v_mfma_f32_16x16x32_bf16 v[54:57], v[170:173], v[192:195], v[54:57]
	v_mfma_f32_16x16x32_bf16 v[50:53], v[178:181], v[192:195], v[50:53]
	v_mfma_f32_16x16x32_bf16 v[38:41], v[170:173], v[200:203], v[38:41]
	v_mfma_f32_16x16x32_bf16 v[34:37], v[178:181], v[200:203], v[34:37]
	v_mfma_f32_16x16x32_bf16 v[22:25], v[170:173], v[208:211], v[22:25]
	v_mfma_f32_16x16x32_bf16 v[18:21], v[178:181], v[208:211], v[18:21]
	v_mfma_f32_16x16x32_bf16 v[6:9], v[170:173], v[216:219], v[6:9]
	v_mfma_f32_16x16x32_bf16 v[2:5], v[178:181], v[216:219], v[2:5]
	v_mfma_f32_16x16x32_bf16 v[54:57], v[174:177], v[196:199], v[54:57]
	v_mfma_f32_16x16x32_bf16 v[50:53], v[188:191], v[196:199], v[50:53]
	v_mfma_f32_16x16x32_bf16 v[38:41], v[174:177], v[204:207], v[38:41]
	v_mfma_f32_16x16x32_bf16 v[34:37], v[188:191], v[204:207], v[34:37]
	v_mfma_f32_16x16x32_bf16 v[22:25], v[174:177], v[212:215], v[22:25]
	v_mfma_f32_16x16x32_bf16 v[18:21], v[188:191], v[212:215], v[18:21]
	v_mfma_f32_16x16x32_bf16 v[6:9], v[174:177], v[220:223], v[6:9]
	v_mfma_f32_16x16x32_bf16 v[2:5], v[188:191], v[220:223], v[2:5]
	s_barrier
	s_add_i32 s94, s94, 2
	s_add_u32 s30, s30, 0x100
	s_addc_u32 s31, s31, 0
	s_add_u32 s92, s92, 0x100
	s_addc_u32 s93, s93, 0
	s_cmp_gt_u32 s94, 61
	s_cbranch_scc0 .LBB0_541
	s_and_b64 vcc, exec, s[20:21]
	s_cbranch_vccz .LBB0_544
	s_barrier

; #define PG8_STAGE(bufoff, gbase, voff) do { _Pragma("unroll") for (int _i = 0; _i < 2; ++_i) \
;         __builtin_amdgcn_global_load_lds((const unsigned*)((const char*)(gbase) + (voff)[_i]), (PG8_LAS unsigned*)(lds + (bufoff) + ldsw + _i * 8192), 16, 0, 0); } while (0)
; #define PG8_LDA(dst, b, h) do { _Pragma("unroll") for (int m = 0; m < 4; ++m) _Pragma("unroll") for (int k = 0; k < 2; ++k) dst[m][k] = *(const PG8_LAS bf16x8*)(lds + PG8_SA(b, h) + aoff + m * 2048 + k * 1024); } while (0)
; #define PG8_LDB(dst, b, h) do { _Pragma("unroll") for (int n = 0; n < 2; ++n) _Pragma("unroll") for (int k = 0; k < 2; ++k) dst[n][k] = *(const PG8_LAS bf16x8*)(lds + PG8_SB(b, h) + boff + n * 2048 + k * 1024); } while (0)
; #define PG8_MMA(ai, bj, At, Bt) do { __builtin_amdgcn_s_setprio(1); _Pragma("unroll") for (int m = 0; m < 4; ++m) _Pragma("unroll") for (int n = 0; n < 2; ++n) _Pragma("unroll") for (int k = 0; k < 2; ++k) \
;         acc[ai][bj][m][n] = mma_<I8>(Bt[n][k], At[m][k], acc[ai][bj][m][n]); __builtin_amdgcn_s_setprio(0); } while (0)
; #define PG8_WAIT_V(n) asm volatile("s_waitcnt vmcnt(" #n ")" ::: "memory")
; #define PG8_WAIT_L(n) asm volatile("s_waitcnt lgkmcnt(" #n ")" ::: "memory")
; #define PG8_BAR __builtin_amdgcn_s_barrier()
; template <class Epi, class Sched, bool ALIGN_EPI = false, bool SP2 = false, bool I8 = false>
; __device__ __forceinline__ void gemm_phase(PG8_LAS unsigned char* lds, const Gemm g, const Sched& S, const Epi& E) {
;     ...
;             const bool last = (t == nt - 2);
;             const char* a1 = cA + (size_t)(t + 1) * kstep;
;             const char* a2 = last ? nA : cA + (size_t)(t + 2) * kstep; const char* b2 = last ? nB : cB + (size_t)(t + 2) * kstep;
;             const char* a3 = a2 + kstep; const char* b3 = b2 + kstep;
;             if (last && has_next) S.a_ready(nxt);
;             if constexpr (SP2) {
;             PG8_LDB(B0, 0, 0); PG8_LDB(B1, 0, 1); PG8_SCHED; PG8_LDA(At, 0, 0); PG8_STAGE(PG8_SA(1, 1), a1 + hstepA, voffA);
;             PG8_WAIT_V(8); PG8_WAIT_L(0); PG8_BAR; PG8_MMA(0, 0, At, B0); PG8_MMA(0, 1, At, B1); PG8_BAR; PG8_SCHED;
;             PG8_LDA(At, 0, 1); PG8_STAGE(PG8_SB(0, 0), b2, voffB); PG8_STAGE(PG8_SB(0, 1), b2 + hstepB, voffB); PG8_STAGE(PG8_SA(0, 0), a2, voffA);
;             PG8_WAIT_V(8); PG8_WAIT_L(0); PG8_BAR; PG8_MMA(1, 0, At, B0); PG8_MMA(1, 1, At, B1); PG8_BAR; PG8_SCHED;
.LBB0_607:
	ds_read_b128 v[58:61], v177
	ds_read_b128 v[62:65], v177 offset:1024
	ds_read_b128 v[74:77], v177 offset:2048
	ds_read_b128 v[78:81], v177 offset:3072
	ds_read_b128 v[162:165], v178
	ds_read_b128 v[166:169], v178 offset:1024
	ds_read_b128 v[170:173], v178 offset:2048
	ds_read_b128 v[180:183], v178 offset:3072
	s_add_u32 s34, s2, 0xfff80080
	s_addc_u32 s35, s3, -1
	s_cmp_eq_u32 s39, 28
	s_cselect_b32 s37, s7, s35
	s_cselect_b32 s36, s9, s34
	s_cselect_b32 s35, s23, s38
	s_cselect_b32 s34, s25, s31
	s_add_i32 m0, s69, 0xc000
	ds_read_b128 v[184:187], v179
	ds_read_b128 v[188:191], v179 offset:1024
	ds_read_b128 v[192:195], v179 offset:2048
	ds_read_b128 v[196:199], v179 offset:3072
	ds_read_b128 v[200:203], v179 offset:4096
	ds_read_b128 v[204:207], v179 offset:5120
	ds_read_b128 v[208:211], v179 offset:6144
	ds_read_b128 v[212:215], v179 offset:7168
	global_load_lds_dwordx4 v154, s[2:3]
	s_add_i32 m0, s69, 0xe000
	s_nop 0
	global_load_lds_dwordx4 v156, s[2:3]
	s_waitcnt vmcnt(8)
	s_waitcnt lgkmcnt(0)
	s_barrier
	s_waitcnt lgkmcnt(0)
	v_mfma_i32_16x16x64_i8 v[142:145], v[58:61], v[184:187], v[142:145]
	v_mfma_i32_16x16x64_i8 v[138:141], v[74:77], v[184:187], v[138:141]
	v_mfma_i32_16x16x64_i8 v[126:129], v[58:61], v[192:195], v[126:129]
	v_mfma_i32_16x16x64_i8 v[122:125], v[74:77], v[192:195], v[122:125]
	v_mfma_i32_16x16x64_i8 v[110:113], v[58:61], v[200:203], v[110:113]
	v_mfma_i32_16x16x64_i8 v[106:109], v[74:77], v[200:203], v[106:109]
	v_mfma_i32_16x16x64_i8 v[94:97], v[58:61], v[208:211], v[94:97]
	v_mfma_i32_16x16x64_i8 v[90:93], v[74:77], v[208:211], v[90:93]
	v_mfma_i32_16x16x64_i8 v[142:145], v[62:65], v[188:191], v[142:145]
	v_mfma_i32_16x16x64_i8 v[138:141], v[78:81], v[188:191], v[138:141]
	v_mfma_i32_16x16x64_i8 v[126:129], v[62:65], v[196:199], v[126:129]
	v_mfma_i32_16x16x64_i8 v[122:125], v[78:81], v[196:199], v[122:125]
	v_mfma_i32_16x16x64_i8 v[110:113], v[62:65], v[204:207], v[110:113]
	v_mfma_i32_16x16x64_i8 v[106:109], v[78:81], v[204:207], v[106:109]
	v_mfma_i32_16x16x64_i8 v[94:97], v[62:65], v[212:215], v[94:97]
	v_mfma_i32_16x16x64_i8 v[90:93], v[78:81], v[212:215], v[90:93]
	v_mfma_i32_16x16x64_i8 v[134:137], v[162:165], v[184:187], v[134:137]
	v_mfma_i32_16x16x64_i8 v[130:133], v[170:173], v[184:187], v[130:133]
	v_mfma_i32_16x16x64_i8 v[118:121], v[162:165], v[192:195], v[118:121]
	v_mfma_i32_16x16x64_i8 v[114:117], v[170:173], v[192:195], v[114:117]
	v_mfma_i32_16x16x64_i8 v[102:105], v[162:165], v[200:203], v[102:105]
	v_mfma_i32_16x16x64_i8 v[98:101], v[170:173], v[200:203], v[98:101]
	v_mfma_i32_16x16x64_i8 v[86:89], v[162:165], v[208:211], v[86:89]
	v_mfma_i32_16x16x64_i8 v[82:85], v[170:173], v[208:211], v[82:85]
	v_mfma_i32_16x16x64_i8 v[134:137], v[166:169], v[188:191], v[134:137]
	v_mfma_i32_16x16x64_i8 v[130:133], v[180:183], v[188:191], v[130:133]
	v_mfma_i32_16x16x64_i8 v[118:121], v[166:169], v[196:199], v[118:121]
	v_mfma_i32_16x16x64_i8 v[114:117], v[180:183], v[196:199], v[114:117]
	v_mfma_i32_16x16x64_i8 v[102:105], v[166:169], v[204:207], v[102:105]
	v_mfma_i32_16x16x64_i8 v[98:101], v[180:183], v[204:207], v[98:101]
	v_mfma_i32_16x16x64_i8 v[86:89], v[166:169], v[212:215], v[86:89]
	v_mfma_i32_16x16x64_i8 v[82:85], v[180:183], v[212:215], v[82:85]
	s_barrier
	s_add_i32 s40, s33, s68
	s_mov_b64 s[98:99], s[34:35]
	s_mov_b32 m0, s40
	ds_read_b128 v[184:187], v179 offset:16384
	ds_read_b128 v[188:191], v179 offset:17408
	ds_read_b128 v[192:195], v179 offset:18432
	ds_read_b128 v[196:199], v179 offset:19456
	ds_read_b128 v[200:203], v179 offset:20480
	ds_read_b128 v[204:207], v179 offset:21504
	ds_read_b128 v[208:211], v179 offset:22528
	ds_read_b128 v[212:215], v179 offset:23552
	global_load_lds_dwordx4 v148, s[34:35]
	s_add_i32 m0, s40, 0x2000
	s_add_u32 s40, s34, 0x80000
	s_mov_b64 s[98:99], s[34:35]
	s_addc_u32 s41, s35, 0
	s_add_i32 vcc_lo, s8, s68
	global_load_lds_dwordx4 v152, s[34:35]
	s_mov_b32 m0, vcc_lo
	s_mov_b64 s[100:101], s[36:37]
	global_load_lds_dwordx4 v148, s[40:41]
	s_add_i32 m0, vcc_lo, 0x2000
	s_nop 0
	global_load_lds_dwordx4 v152, s[40:41]
	s_mov_b64 s[100:101], s[36:37]
	s_mov_b32 m0, s69
	s_nop 0
	global_load_lds_dwordx4 v146, s[36:37]
	s_mov_b32 m0, s70
	s_nop 0
	global_load_lds_dwordx4 v150, s[36:37]
	s_waitcnt vmcnt(8)
	s_waitcnt lgkmcnt(0)
	s_barrier
	s_waitcnt lgkmcnt(0)
	v_mfma_i32_16x16x64_i8 v[70:73], v[58:61], v[184:187], v[70:73]
	v_mfma_i32_16x16x64_i8 v[66:69], v[74:77], v[184:187], v[66:69]
	v_mfma_i32_16x16x64_i8 v[46:49], v[58:61], v[192:195], v[46:49]
	v_mfma_i32_16x16x64_i8 v[42:45], v[74:77], v[192:195], v[42:45]
	v_mfma_i32_16x16x64_i8 v[30:33], v[58:61], v[200:203], v[30:33]
	v_mfma_i32_16x16x64_i8 v[26:29], v[74:77], v[200:203], v[26:29]
	v_mfma_i32_16x16x64_i8 v[14:17], v[58:61], v[208:211], v[14:17]
	v_mfma_i32_16x16x64_i8 v[10:13], v[74:77], v[208:211], v[10:13]
	v_mfma_i32_16x16x64_i8 v[70:73], v[62:65], v[188:191], v[70:73]
	v_mfma_i32_16x16x64_i8 v[66:69], v[78:81], v[188:191], v[66:69]
	v_mfma_i32_16x16x64_i8 v[46:49], v[62:65], v[196:199], v[46:49]
	v_mfma_i32_16x16x64_i8 v[42:45], v[78:81], v[196:199], v[42:45]
	v_mfma_i32_16x16x64_i8 v[30:33], v[62:65], v[204:207], v[30:33]
	v_mfma_i32_16x16x64_i8 v[26:29], v[78:81], v[204:207], v[26:29]
	v_mfma_i32_16x16x64_i8 v[14:17], v[62:65], v[212:215], v[14:17]
	v_mfma_i32_16x16x64_i8 v[10:13], v[78:81], v[212:215], v[10:13]
	v_mfma_i32_16x16x64_i8 v[54:57], v[162:165], v[184:187], v[54:57]
	v_mfma_i32_16x16x64_i8 v[50:53], v[170:173], v[184:187], v[50:53]
	v_mfma_i32_16x16x64_i8 v[38:41], v[162:165], v[192:195], v[38:41]
	v_mfma_i32_16x16x64_i8 v[34:37], v[170:173], v[192:195], v[34:37]
	v_mfma_i32_16x16x64_i8 v[22:25], v[162:165], v[200:203], v[22:25]
	v_mfma_i32_16x16x64_i8 v[18:21], v[170:173], v[200:203], v[18:21]
	v_mfma_i32_16x16x64_i8 v[6:9], v[162:165], v[208:211], v[6:9]
	v_mfma_i32_16x16x64_i8 v[2:5], v[170:173], v[208:211], v[2:5]
	v_mfma_i32_16x16x64_i8 v[54:57], v[166:169], v[188:191], v[54:57]
	v_mfma_i32_16x16x64_i8 v[50:53], v[180:183], v[188:191], v[50:53]
	v_mfma_i32_16x16x64_i8 v[38:41], v[166:169], v[196:199], v[38:41]
	v_mfma_i32_16x16x64_i8 v[34:37], v[180:183], v[196:199], v[34:37]
	v_mfma_i32_16x16x64_i8 v[22:25], v[166:169], v[204:207], v[22:25]
	v_mfma_i32_16x16x64_i8 v[18:21], v[180:183], v[204:207], v[18:21]
	v_mfma_i32_16x16x64_i8 v[6:9], v[166:169], v[212:215], v[6:9]
	v_mfma_i32_16x16x64_i8 v[2:5], v[180:183], v[212:215], v[2:5]
	s_barrier
; #define PG8_STAGE(bufoff, gbase, voff) do { _Pragma("unroll") for (int _i = 0; _i < 2; ++_i) \
;         __builtin_amdgcn_global_load_lds((const unsigned*)((const char*)(gbase) + (voff)[_i]), (PG8_LAS unsigned*)(lds + (bufoff) + ldsw + _i * 8192), 16, 0, 0); } while (0)
; #define PG8_LDA(dst, b, h) do { _Pragma("unroll") for (int m = 0; m < 4; ++m) _Pragma("unroll") for (int k = 0; k < 2; ++k) dst[m][k] = *(const PG8_LAS bf16x8*)(lds + PG8_SA(b, h) + aoff + m * 2048 + k * 1024); } while (0)
; #define PG8_LDB(dst, b, h) do { _Pragma("unroll") for (int n = 0; n < 2; ++n) _Pragma("unroll") for (int k = 0; k < 2; ++k) dst[n][k] = *(const PG8_LAS bf16x8*)(lds + PG8_SB(b, h) + boff + n * 2048 + k * 1024); } while (0)
; #define PG8_MMA(ai, bj, At, Bt) do { __builtin_amdgcn_s_setprio(1); _Pragma("unroll") for (int m = 0; m < 4; ++m) _Pragma("unroll") for (int n = 0; n < 2; ++n) _Pragma("unroll") for (int k = 0; k < 2; ++k) \
;         acc[ai][bj][m][n] = mma_<I8>(Bt[n][k], At[m][k], acc[ai][bj][m][n]); __builtin_amdgcn_s_setprio(0); } while (0)
; #define PG8_WAIT_V(n) asm volatile("s_waitcnt vmcnt(" #n ")" ::: "memory")
; #define PG8_WAIT_L(n) asm volatile("s_waitcnt lgkmcnt(" #n ")" ::: "memory")
; #define PG8_BAR __builtin_amdgcn_s_barrier()
; #define PG8_SCHED __builtin_amdgcn_sched_barrier(0)
; template <class Epi, class Sched, bool ALIGN_EPI = false, bool SP2 = false, bool I8 = false>
; __device__ __forceinline__ void gemm_phase(PG8_LAS unsigned char* lds, const Gemm g, const Sched& S, const Epi& E) {
;     ...
;         for (int t = 0; t < nt; t += 2) {
;     ...
;             PG8_LDB(B0, 1, 0); PG8_LDB(B1, 1, 1); PG8_SCHED; PG8_LDA(At, 1, 0); PG8_STAGE(PG8_SA(0, 1), a2 + hstepA, voffA);
;             PG8_WAIT_V(8); PG8_WAIT_L(0); PG8_BAR; PG8_MMA(0, 0, At, B0); PG8_MMA(0, 1, At, B1); PG8_BAR; PG8_SCHED;
;             PG8_LDA(At, 1, 1); PG8_STAGE(PG8_SB(1, 0), b3, voffB); PG8_STAGE(PG8_SB(1, 1), b3 + hstepB, voffB); PG8_STAGE(PG8_SA(1, 0), a3, voffA);
;             PG8_WAIT_V(8); PG8_WAIT_L(0); PG8_BAR; PG8_MMA(1, 0, At, B0); PG8_MMA(1, 1, At, B1); PG8_BAR; PG8_SCHED;
	s_add_i32 s40, 0, 0x18000
	s_add_i32 s41, 0, 0x1c000
	ds_read_b128 v[58:61], v178 offset:16384
	ds_read_b128 v[62:65], v178 offset:17408
	ds_read_b128 v[74:77], v178 offset:18432
	ds_read_b128 v[78:81], v178 offset:19456
	ds_read_b128 v[162:165], v178 offset:32768
	ds_read_b128 v[166:169], v178 offset:33792
	ds_read_b128 v[170:173], v178 offset:34816
	ds_read_b128 v[180:183], v178 offset:35840
	s_add_u32 s36, s36, 0x80000
	s_addc_u32 s37, s37, 0
	s_mov_b32 m0, s71
	ds_read_b128 v[184:187], v179 offset:32768
	ds_read_b128 v[188:191], v179 offset:33792
	ds_read_b128 v[192:195], v179 offset:34816
	ds_read_b128 v[196:199], v179 offset:35840
	ds_read_b128 v[200:203], v179 offset:36864
	ds_read_b128 v[204:207], v179 offset:37888
	ds_read_b128 v[208:211], v179 offset:38912
	ds_read_b128 v[212:215], v179 offset:39936
	global_load_lds_dwordx4 v146, s[36:37]
	s_mov_b32 m0, s88
	s_nop 0
	global_load_lds_dwordx4 v150, s[36:37]
	s_waitcnt vmcnt(8)
	s_waitcnt lgkmcnt(0)
	s_barrier
	s_waitcnt lgkmcnt(0)
	v_mfma_i32_16x16x64_i8 v[142:145], v[58:61], v[184:187], v[142:145]
	v_mfma_i32_16x16x64_i8 v[138:141], v[74:77], v[184:187], v[138:141]
	v_mfma_i32_16x16x64_i8 v[126:129], v[58:61], v[192:195], v[126:129]
	v_mfma_i32_16x16x64_i8 v[122:125], v[74:77], v[192:195], v[122:125]
	v_mfma_i32_16x16x64_i8 v[110:113], v[58:61], v[200:203], v[110:113]
	v_mfma_i32_16x16x64_i8 v[106:109], v[74:77], v[200:203], v[106:109]
	v_mfma_i32_16x16x64_i8 v[94:97], v[58:61], v[208:211], v[94:97]
	v_mfma_i32_16x16x64_i8 v[90:93], v[74:77], v[208:211], v[90:93]
	v_mfma_i32_16x16x64_i8 v[142:145], v[62:65], v[188:191], v[142:145]
	v_mfma_i32_16x16x64_i8 v[138:141], v[78:81], v[188:191], v[138:141]
	v_mfma_i32_16x16x64_i8 v[126:129], v[62:65], v[196:199], v[126:129]
	v_mfma_i32_16x16x64_i8 v[122:125], v[78:81], v[196:199], v[122:125]
	v_mfma_i32_16x16x64_i8 v[110:113], v[62:65], v[204:207], v[110:113]
	v_mfma_i32_16x16x64_i8 v[106:109], v[78:81], v[204:207], v[106:109]
	v_mfma_i32_16x16x64_i8 v[94:97], v[62:65], v[212:215], v[94:97]
	v_mfma_i32_16x16x64_i8 v[90:93], v[78:81], v[212:215], v[90:93]
	v_mfma_i32_16x16x64_i8 v[134:137], v[162:165], v[184:187], v[134:137]
	v_mfma_i32_16x16x64_i8 v[130:133], v[170:173], v[184:187], v[130:133]
	v_mfma_i32_16x16x64_i8 v[118:121], v[162:165], v[192:195], v[118:121]
	v_mfma_i32_16x16x64_i8 v[114:117], v[170:173], v[192:195], v[114:117]
	v_mfma_i32_16x16x64_i8 v[102:105], v[162:165], v[200:203], v[102:105]
	v_mfma_i32_16x16x64_i8 v[98:101], v[170:173], v[200:203], v[98:101]
	v_mfma_i32_16x16x64_i8 v[86:89], v[162:165], v[208:211], v[86:89]
	v_mfma_i32_16x16x64_i8 v[82:85], v[170:173], v[208:211], v[82:85]
	v_mfma_i32_16x16x64_i8 v[134:137], v[166:169], v[188:191], v[134:137]
	v_mfma_i32_16x16x64_i8 v[130:133], v[180:183], v[188:191], v[130:133]
	v_mfma_i32_16x16x64_i8 v[118:121], v[166:169], v[196:199], v[118:121]
	v_mfma_i32_16x16x64_i8 v[114:117], v[180:183], v[196:199], v[114:117]
	v_mfma_i32_16x16x64_i8 v[102:105], v[166:169], v[204:207], v[102:105]
	v_mfma_i32_16x16x64_i8 v[98:101], v[180:183], v[204:207], v[98:101]
	v_mfma_i32_16x16x64_i8 v[86:89], v[166:169], v[212:215], v[86:89]
	v_mfma_i32_16x16x64_i8 v[82:85], v[180:183], v[212:215], v[82:85]
	s_barrier
	s_add_i32 s36, s40, s68
	s_add_i32 m0, s36, 0xffffff80
	ds_read_b128 v[184:187], v179 offset:49152
	ds_read_b128 v[188:191], v179 offset:50176
	ds_read_b128 v[192:195], v179 offset:51200
	ds_read_b128 v[196:199], v179 offset:52224
	ds_read_b128 v[200:203], v179 offset:53248
	ds_read_b128 v[204:207], v179 offset:54272
	ds_read_b128 v[208:211], v179 offset:55296
	ds_read_b128 v[212:215], v179 offset:56320
	global_load_lds_dwordx4 v148, s[98:99] offset:128
	s_add_i32 m0, s36, 0x1f80
	s_add_u32 s34, s34, 0x80080
	s_addc_u32 s35, s35, 0
	s_add_i32 s36, s41, s68
	global_load_lds_dwordx4 v152, s[98:99] offset:128
	s_mov_b32 m0, s36
	s_nop 0
	global_load_lds_dwordx4 v148, s[34:35]
	s_add_i32 m0, s36, 0x2000
	s_nop 0
	global_load_lds_dwordx4 v152, s[34:35]
	s_add_i32 m0, s92, 0xffffff80
	s_nop 0
	global_load_lds_dwordx4 v146, s[100:101] offset:128
	s_add_i32 m0, s93, 0xffffff80
	s_nop 0
	global_load_lds_dwordx4 v150, s[100:101] offset:128
	s_waitcnt vmcnt(8)
	s_waitcnt lgkmcnt(0)
	s_barrier
	s_waitcnt lgkmcnt(0)
	v_mfma_i32_16x16x64_i8 v[70:73], v[58:61], v[184:187], v[70:73]
	v_mfma_i32_16x16x64_i8 v[66:69], v[74:77], v[184:187], v[66:69]
	v_mfma_i32_16x16x64_i8 v[46:49], v[58:61], v[192:195], v[46:49]
	v_mfma_i32_16x16x64_i8 v[42:45], v[74:77], v[192:195], v[42:45]
	v_mfma_i32_16x16x64_i8 v[30:33], v[58:61], v[200:203], v[30:33]
	v_mfma_i32_16x16x64_i8 v[26:29], v[74:77], v[200:203], v[26:29]
	v_mfma_i32_16x16x64_i8 v[14:17], v[58:61], v[208:211], v[14:17]
	v_mfma_i32_16x16x64_i8 v[10:13], v[74:77], v[208:211], v[10:13]
	v_mfma_i32_16x16x64_i8 v[70:73], v[62:65], v[188:191], v[70:73]
	v_mfma_i32_16x16x64_i8 v[66:69], v[78:81], v[188:191], v[66:69]
	v_mfma_i32_16x16x64_i8 v[46:49], v[62:65], v[196:199], v[46:49]
	v_mfma_i32_16x16x64_i8 v[42:45], v[78:81], v[196:199], v[42:45]
	v_mfma_i32_16x16x64_i8 v[30:33], v[62:65], v[204:207], v[30:33]
	v_mfma_i32_16x16x64_i8 v[26:29], v[78:81], v[204:207], v[26:29]
	v_mfma_i32_16x16x64_i8 v[14:17], v[62:65], v[212:215], v[14:17]
	v_mfma_i32_16x16x64_i8 v[10:13], v[78:81], v[212:215], v[10:13]
	v_mfma_i32_16x16x64_i8 v[54:57], v[162:165], v[184:187], v[54:57]
	v_mfma_i32_16x16x64_i8 v[50:53], v[170:173], v[184:187], v[50:53]
	v_mfma_i32_16x16x64_i8 v[38:41], v[162:165], v[192:195], v[38:41]
	v_mfma_i32_16x16x64_i8 v[34:37], v[170:173], v[192:195], v[34:37]
	v_mfma_i32_16x16x64_i8 v[22:25], v[162:165], v[200:203], v[22:25]
	v_mfma_i32_16x16x64_i8 v[18:21], v[170:173], v[200:203], v[18:21]
	v_mfma_i32_16x16x64_i8 v[6:9], v[162:165], v[208:211], v[6:9]
	v_mfma_i32_16x16x64_i8 v[2:5], v[170:173], v[208:211], v[2:5]
	v_mfma_i32_16x16x64_i8 v[54:57], v[166:169], v[188:191], v[54:57]
	v_mfma_i32_16x16x64_i8 v[50:53], v[180:183], v[188:191], v[50:53]
	v_mfma_i32_16x16x64_i8 v[38:41], v[166:169], v[196:199], v[38:41]
	v_mfma_i32_16x16x64_i8 v[34:37], v[180:183], v[196:199], v[34:37]
	v_mfma_i32_16x16x64_i8 v[22:25], v[166:169], v[204:207], v[22:25]
	v_mfma_i32_16x16x64_i8 v[18:21], v[180:183], v[204:207], v[18:21]
	v_mfma_i32_16x16x64_i8 v[6:9], v[166:169], v[212:215], v[6:9]
	v_mfma_i32_16x16x64_i8 v[2:5], v[180:183], v[212:215], v[2:5]
	s_barrier
	s_add_i32 s39, s39, 2
	s_add_u32 s2, s2, 0x100
	s_addc_u32 s3, s3, 0
	s_add_u32 s31, s31, 0x100
	s_addc_u32 s38, s38, 0
	s_cmp_gt_u32 s39, 29
	s_cbranch_scc0 .LBB0_607
	s_and_b64 vcc, exec, s[20:21]
	s_cbranch_vccz .LBB0_610
	s_barrier

; #define PG8_STAGE(bufoff, gbase, voff) do { _Pragma("unroll") for (int _i = 0; _i < 2; ++_i) \
;         __builtin_amdgcn_global_load_lds((const unsigned*)((const char*)(gbase) + (voff)[_i]), (PG8_LAS unsigned*)(lds + (bufoff) + ldsw + _i * 8192), 16, 0, 0); } while (0)
; #define PG8_LDA(dst, b, h) do { _Pragma("unroll") for (int m = 0; m < 4; ++m) _Pragma("unroll") for (int k = 0; k < 2; ++k) dst[m][k] = *(const PG8_LAS bf16x8*)(lds + PG8_SA(b, h) + aoff + m * 2048 + k * 1024); } while (0)
; #define PG8_LDB(dst, b, h) do { _Pragma("unroll") for (int n = 0; n < 2; ++n) _Pragma("unroll") for (int k = 0; k < 2; ++k) dst[n][k] = *(const PG8_LAS bf16x8*)(lds + PG8_SB(b, h) + boff + n * 2048 + k * 1024); } while (0)
; #define PG8_MMA(ai, bj, At, Bt) do { __builtin_amdgcn_s_setprio(1); _Pragma("unroll") for (int m = 0; m < 4; ++m) _Pragma("unroll") for (int n = 0; n < 2; ++n) _Pragma("unroll") for (int k = 0; k < 2; ++k) \
;         acc[ai][bj][m][n] = mma_<I8>(Bt[n][k], At[m][k], acc[ai][bj][m][n]); __builtin_amdgcn_s_setprio(0); } while (0)
; #define PG8_WAIT_V(n) asm volatile("s_waitcnt vmcnt(" #n ")" ::: "memory")
; #define PG8_WAIT_L(n) asm volatile("s_waitcnt lgkmcnt(" #n ")" ::: "memory")
; #define PG8_BAR __builtin_amdgcn_s_barrier()
; template <class Epi, class Sched, bool ALIGN_EPI = false, bool SP2 = false, bool I8 = false>
; __device__ __forceinline__ void gemm_phase(PG8_LAS unsigned char* lds, const Gemm g, const Sched& S, const Epi& E) {
;     ...
;             const bool last = (t == nt - 2);
;             const char* a1 = cA + (size_t)(t + 1) * kstep;
;             const char* a2 = last ? nA : cA + (size_t)(t + 2) * kstep; const char* b2 = last ? nB : cB + (size_t)(t + 2) * kstep;
;             const char* a3 = a2 + kstep; const char* b3 = b2 + kstep;
;             if (last && has_next) S.a_ready(nxt);
;             if constexpr (SP2) {
;             PG8_LDB(B0, 0, 0); PG8_LDB(B1, 0, 1); PG8_SCHED; PG8_LDA(At, 0, 0); PG8_STAGE(PG8_SA(1, 1), a1 + hstepA, voffA);
;             PG8_WAIT_V(8); PG8_WAIT_L(0); PG8_BAR; PG8_MMA(0, 0, At, B0); PG8_MMA(0, 1, At, B1); PG8_BAR; PG8_SCHED;
;             PG8_LDA(At, 0, 1); PG8_STAGE(PG8_SB(0, 0), b2, voffB); PG8_STAGE(PG8_SB(0, 1), b2 + hstepB, voffB); PG8_STAGE(PG8_SA(0, 0), a2, voffA);
;             PG8_WAIT_V(8); PG8_WAIT_L(0); PG8_BAR; PG8_MMA(1, 0, At, B0); PG8_MMA(1, 1, At, B1); PG8_BAR; PG8_SCHED;
.LBB0_1092:
	ds_read_b128 v[58:61], v172
	ds_read_b128 v[62:65], v172 offset:1024
	ds_read_b128 v[74:77], v172 offset:2048
	ds_read_b128 v[78:81], v172 offset:3072
	ds_read_b128 v[164:167], v173
	ds_read_b128 v[168:171], v173 offset:1024
	ds_read_b128 v[176:179], v173 offset:2048
	ds_read_b128 v[180:183], v173 offset:3072
	s_add_i32 s47, s22, 2
	s_add_u32 s23, s8, 0xfffe0080
	s_addc_u32 s24, s9, -1
	s_cmp_eq_u32 s3, s22
	s_cselect_b32 s22, s20, s17
	s_cselect_b32 s25, s1, s24
	s_cselect_b32 s24, s0, s23
	s_cselect_b32 s23, s21, s19
	s_add_i32 m0, s33, 0xc000
	ds_read_b128 v[184:187], v174
	ds_read_b128 v[188:191], v174 offset:1024
	ds_read_b128 v[192:195], v174 offset:2048
	ds_read_b128 v[196:199], v174 offset:3072
	ds_read_b128 v[200:203], v174 offset:4096
	ds_read_b128 v[204:207], v174 offset:5120
	ds_read_b128 v[208:211], v174 offset:6144
	ds_read_b128 v[212:215], v174 offset:7168
	global_load_lds_dwordx4 v156, s[8:9]
	s_add_i32 m0, s33, 0xe000
	s_nop 0
	global_load_lds_dwordx4 v158, s[8:9]
	s_waitcnt vmcnt(8)
	s_waitcnt lgkmcnt(0)
	s_barrier
	s_waitcnt lgkmcnt(0)
	v_mfma_f32_16x16x32_bf16 v[142:145], v[58:61], v[184:187], v[142:145]
	v_mfma_f32_16x16x32_bf16 v[138:141], v[74:77], v[184:187], v[138:141]
	v_mfma_f32_16x16x32_bf16 v[126:129], v[58:61], v[192:195], v[126:129]
	v_mfma_f32_16x16x32_bf16 v[122:125], v[74:77], v[192:195], v[122:125]
	v_mfma_f32_16x16x32_bf16 v[110:113], v[58:61], v[200:203], v[110:113]
	v_mfma_f32_16x16x32_bf16 v[106:109], v[74:77], v[200:203], v[106:109]
	v_mfma_f32_16x16x32_bf16 v[94:97], v[58:61], v[208:211], v[94:97]
	v_mfma_f32_16x16x32_bf16 v[90:93], v[74:77], v[208:211], v[90:93]
	v_mfma_f32_16x16x32_bf16 v[142:145], v[62:65], v[188:191], v[142:145]
	v_mfma_f32_16x16x32_bf16 v[138:141], v[78:81], v[188:191], v[138:141]
	v_mfma_f32_16x16x32_bf16 v[126:129], v[62:65], v[196:199], v[126:129]
	v_mfma_f32_16x16x32_bf16 v[122:125], v[78:81], v[196:199], v[122:125]
	v_mfma_f32_16x16x32_bf16 v[110:113], v[62:65], v[204:207], v[110:113]
	v_mfma_f32_16x16x32_bf16 v[106:109], v[78:81], v[204:207], v[106:109]
	v_mfma_f32_16x16x32_bf16 v[94:97], v[62:65], v[212:215], v[94:97]
	v_mfma_f32_16x16x32_bf16 v[90:93], v[78:81], v[212:215], v[90:93]
	v_mfma_f32_16x16x32_bf16 v[134:137], v[164:167], v[184:187], v[134:137]
	v_mfma_f32_16x16x32_bf16 v[130:133], v[176:179], v[184:187], v[130:133]
	v_mfma_f32_16x16x32_bf16 v[118:121], v[164:167], v[192:195], v[118:121]
	v_mfma_f32_16x16x32_bf16 v[114:117], v[176:179], v[192:195], v[114:117]
	v_mfma_f32_16x16x32_bf16 v[102:105], v[164:167], v[200:203], v[102:105]
	v_mfma_f32_16x16x32_bf16 v[98:101], v[176:179], v[200:203], v[98:101]
	v_mfma_f32_16x16x32_bf16 v[86:89], v[164:167], v[208:211], v[86:89]
	v_mfma_f32_16x16x32_bf16 v[82:85], v[176:179], v[208:211], v[82:85]
	v_mfma_f32_16x16x32_bf16 v[134:137], v[168:171], v[188:191], v[134:137]
	v_mfma_f32_16x16x32_bf16 v[130:133], v[180:183], v[188:191], v[130:133]
	v_mfma_f32_16x16x32_bf16 v[118:121], v[168:171], v[196:199], v[118:121]
	v_mfma_f32_16x16x32_bf16 v[114:117], v[180:183], v[196:199], v[114:117]
	v_mfma_f32_16x16x32_bf16 v[102:105], v[168:171], v[204:207], v[102:105]
	v_mfma_f32_16x16x32_bf16 v[98:101], v[180:183], v[204:207], v[98:101]
	v_mfma_f32_16x16x32_bf16 v[86:89], v[168:171], v[212:215], v[86:89]
	v_mfma_f32_16x16x32_bf16 v[82:85], v[180:183], v[212:215], v[82:85]
	s_barrier
	s_add_i32 s56, s44, s30
	s_mov_b64 s[98:99], s[22:23]
	s_mov_b32 m0, s56
	ds_read_b128 v[184:187], v174 offset:16384
	ds_read_b128 v[188:191], v174 offset:17408
	ds_read_b128 v[192:195], v174 offset:18432
	ds_read_b128 v[196:199], v174 offset:19456
	ds_read_b128 v[200:203], v174 offset:20480
	ds_read_b128 v[204:207], v174 offset:21504
	ds_read_b128 v[208:211], v174 offset:22528
	ds_read_b128 v[212:215], v174 offset:23552
	global_load_lds_dwordx4 v148, s[22:23]
	s_add_i32 m0, s56, 0x2000
	s_add_u32 s56, s22, 0x20000
	s_mov_b64 s[98:99], s[22:23]
	s_addc_u32 s57, s23, 0
	s_add_i32 s58, s45, s30
	global_load_lds_dwordx4 v152, s[22:23]
	s_mov_b32 m0, s58
	s_mov_b64 s[100:101], s[24:25]
	global_load_lds_dwordx4 v148, s[56:57]
	s_add_i32 m0, s58, 0x2000
	s_nop 0
	global_load_lds_dwordx4 v152, s[56:57]
	s_mov_b64 s[100:101], s[24:25]
	s_mov_b32 m0, s33
	s_nop 0
	global_load_lds_dwordx4 v146, s[24:25]
	s_mov_b32 m0, s34
	s_nop 0
	global_load_lds_dwordx4 v150, s[24:25]
	s_waitcnt vmcnt(8)
	s_waitcnt lgkmcnt(0)
	s_barrier
	s_waitcnt lgkmcnt(0)
	v_mfma_f32_16x16x32_bf16 v[70:73], v[58:61], v[184:187], v[70:73]
	v_mfma_f32_16x16x32_bf16 v[66:69], v[74:77], v[184:187], v[66:69]
	v_mfma_f32_16x16x32_bf16 v[46:49], v[58:61], v[192:195], v[46:49]
	v_mfma_f32_16x16x32_bf16 v[42:45], v[74:77], v[192:195], v[42:45]
	v_mfma_f32_16x16x32_bf16 v[30:33], v[58:61], v[200:203], v[30:33]
	v_mfma_f32_16x16x32_bf16 v[26:29], v[74:77], v[200:203], v[26:29]
	v_mfma_f32_16x16x32_bf16 v[14:17], v[58:61], v[208:211], v[14:17]
	v_mfma_f32_16x16x32_bf16 v[10:13], v[74:77], v[208:211], v[10:13]
	v_mfma_f32_16x16x32_bf16 v[70:73], v[62:65], v[188:191], v[70:73]
	v_mfma_f32_16x16x32_bf16 v[66:69], v[78:81], v[188:191], v[66:69]
	v_mfma_f32_16x16x32_bf16 v[46:49], v[62:65], v[196:199], v[46:49]
	v_mfma_f32_16x16x32_bf16 v[42:45], v[78:81], v[196:199], v[42:45]
	v_mfma_f32_16x16x32_bf16 v[30:33], v[62:65], v[204:207], v[30:33]
	v_mfma_f32_16x16x32_bf16 v[26:29], v[78:81], v[204:207], v[26:29]
	v_mfma_f32_16x16x32_bf16 v[14:17], v[62:65], v[212:215], v[14:17]
	v_mfma_f32_16x16x32_bf16 v[10:13], v[78:81], v[212:215], v[10:13]
	v_mfma_f32_16x16x32_bf16 v[54:57], v[164:167], v[184:187], v[54:57]
	v_mfma_f32_16x16x32_bf16 v[50:53], v[176:179], v[184:187], v[50:53]
	v_mfma_f32_16x16x32_bf16 v[38:41], v[164:167], v[192:195], v[38:41]
	v_mfma_f32_16x16x32_bf16 v[34:37], v[176:179], v[192:195], v[34:37]
	v_mfma_f32_16x16x32_bf16 v[22:25], v[164:167], v[200:203], v[22:25]
	v_mfma_f32_16x16x32_bf16 v[18:21], v[176:179], v[200:203], v[18:21]
	v_mfma_f32_16x16x32_bf16 v[6:9], v[164:167], v[208:211], v[6:9]
	v_mfma_f32_16x16x32_bf16 v[2:5], v[176:179], v[208:211], v[2:5]
	v_mfma_f32_16x16x32_bf16 v[54:57], v[168:171], v[188:191], v[54:57]
	v_mfma_f32_16x16x32_bf16 v[50:53], v[180:183], v[188:191], v[50:53]
	v_mfma_f32_16x16x32_bf16 v[38:41], v[168:171], v[196:199], v[38:41]
	v_mfma_f32_16x16x32_bf16 v[34:37], v[180:183], v[196:199], v[34:37]
	v_mfma_f32_16x16x32_bf16 v[22:25], v[168:171], v[204:207], v[22:25]
	v_mfma_f32_16x16x32_bf16 v[18:21], v[180:183], v[204:207], v[18:21]
	v_mfma_f32_16x16x32_bf16 v[6:9], v[168:171], v[212:215], v[6:9]
	v_mfma_f32_16x16x32_bf16 v[2:5], v[180:183], v[212:215], v[2:5]
	s_barrier
; #define PG8_STAGE(bufoff, gbase, voff) do { _Pragma("unroll") for (int _i = 0; _i < 2; ++_i) \
;         __builtin_amdgcn_global_load_lds((const unsigned*)((const char*)(gbase) + (voff)[_i]), (PG8_LAS unsigned*)(lds + (bufoff) + ldsw + _i * 8192), 16, 0, 0); } while (0)
; #define PG8_LDA(dst, b, h) do { _Pragma("unroll") for (int m = 0; m < 4; ++m) _Pragma("unroll") for (int k = 0; k < 2; ++k) dst[m][k] = *(const PG8_LAS bf16x8*)(lds + PG8_SA(b, h) + aoff + m * 2048 + k * 1024); } while (0)
; #define PG8_LDB(dst, b, h) do { _Pragma("unroll") for (int n = 0; n < 2; ++n) _Pragma("unroll") for (int k = 0; k < 2; ++k) dst[n][k] = *(const PG8_LAS bf16x8*)(lds + PG8_SB(b, h) + boff + n * 2048 + k * 1024); } while (0)
; #define PG8_MMA(ai, bj, At, Bt) do { __builtin_amdgcn_s_setprio(1); _Pragma("unroll") for (int m = 0; m < 4; ++m) _Pragma("unroll") for (int n = 0; n < 2; ++n) _Pragma("unroll") for (int k = 0; k < 2; ++k) \
;         acc[ai][bj][m][n] = mma_<I8>(Bt[n][k], At[m][k], acc[ai][bj][m][n]); __builtin_amdgcn_s_setprio(0); } while (0)
; #define PG8_WAIT_V(n) asm volatile("s_waitcnt vmcnt(" #n ")" ::: "memory")
; #define PG8_WAIT_L(n) asm volatile("s_waitcnt lgkmcnt(" #n ")" ::: "memory")
; #define PG8_BAR __builtin_amdgcn_s_barrier()
; #define PG8_SCHED __builtin_amdgcn_sched_barrier(0)
; template <class Epi, class Sched, bool ALIGN_EPI = false, bool SP2 = false, bool I8 = false>
; __device__ __forceinline__ void gemm_phase(PG8_LAS unsigned char* lds, const Gemm g, const Sched& S, const Epi& E) {
;     ...
;         for (int t = 0; t < nt; t += 2) {
;     ...
;             PG8_LDB(B0, 1, 0); PG8_LDB(B1, 1, 1); PG8_SCHED; PG8_LDA(At, 1, 0); PG8_STAGE(PG8_SA(0, 1), a2 + hstepA, voffA);
;             PG8_WAIT_V(8); PG8_WAIT_L(0); PG8_BAR; PG8_MMA(0, 0, At, B0); PG8_MMA(0, 1, At, B1); PG8_BAR; PG8_SCHED;
;             PG8_LDA(At, 1, 1); PG8_STAGE(PG8_SB(1, 0), b3, voffB); PG8_STAGE(PG8_SB(1, 1), b3 + hstepB, voffB); PG8_STAGE(PG8_SA(1, 0), a3, voffA);
;             PG8_WAIT_V(8); PG8_WAIT_L(0); PG8_BAR; PG8_MMA(1, 0, At, B0); PG8_MMA(1, 1, At, B1); PG8_BAR; PG8_SCHED;
	s_add_i32 s56, 0, 0x18000
	s_add_i32 s57, 0, 0x1c000
	ds_read_b128 v[58:61], v173 offset:16384
	ds_read_b128 v[62:65], v173 offset:17408
	ds_read_b128 v[74:77], v173 offset:18432
	ds_read_b128 v[78:81], v173 offset:19456
	ds_read_b128 v[164:167], v173 offset:32768
	ds_read_b128 v[168:171], v173 offset:33792
	ds_read_b128 v[176:179], v173 offset:34816
	ds_read_b128 v[180:183], v173 offset:35840
	s_add_u32 s24, s24, 0x20000
	s_addc_u32 s25, s25, 0
	s_mov_b32 m0, s35
	ds_read_b128 v[184:187], v174 offset:32768
	ds_read_b128 v[188:191], v174 offset:33792
	ds_read_b128 v[192:195], v174 offset:34816
	ds_read_b128 v[196:199], v174 offset:35840
	ds_read_b128 v[200:203], v174 offset:36864
	ds_read_b128 v[204:207], v174 offset:37888
	ds_read_b128 v[208:211], v174 offset:38912
	ds_read_b128 v[212:215], v174 offset:39936
	global_load_lds_dwordx4 v146, s[24:25]
	s_mov_b32 m0, s36
	s_nop 0
	global_load_lds_dwordx4 v150, s[24:25]
	s_waitcnt vmcnt(8)
	s_waitcnt lgkmcnt(0)
	s_barrier
	s_waitcnt lgkmcnt(0)
	v_mfma_f32_16x16x32_bf16 v[142:145], v[58:61], v[184:187], v[142:145]
	v_mfma_f32_16x16x32_bf16 v[138:141], v[74:77], v[184:187], v[138:141]
	v_mfma_f32_16x16x32_bf16 v[126:129], v[58:61], v[192:195], v[126:129]
	v_mfma_f32_16x16x32_bf16 v[122:125], v[74:77], v[192:195], v[122:125]
	v_mfma_f32_16x16x32_bf16 v[110:113], v[58:61], v[200:203], v[110:113]
	v_mfma_f32_16x16x32_bf16 v[106:109], v[74:77], v[200:203], v[106:109]
	v_mfma_f32_16x16x32_bf16 v[94:97], v[58:61], v[208:211], v[94:97]
	v_mfma_f32_16x16x32_bf16 v[90:93], v[74:77], v[208:211], v[90:93]
	v_mfma_f32_16x16x32_bf16 v[142:145], v[62:65], v[188:191], v[142:145]
	v_mfma_f32_16x16x32_bf16 v[138:141], v[78:81], v[188:191], v[138:141]
	v_mfma_f32_16x16x32_bf16 v[126:129], v[62:65], v[196:199], v[126:129]
	v_mfma_f32_16x16x32_bf16 v[122:125], v[78:81], v[196:199], v[122:125]
	v_mfma_f32_16x16x32_bf16 v[110:113], v[62:65], v[204:207], v[110:113]
	v_mfma_f32_16x16x32_bf16 v[106:109], v[78:81], v[204:207], v[106:109]
	v_mfma_f32_16x16x32_bf16 v[94:97], v[62:65], v[212:215], v[94:97]
	v_mfma_f32_16x16x32_bf16 v[90:93], v[78:81], v[212:215], v[90:93]
	v_mfma_f32_16x16x32_bf16 v[134:137], v[164:167], v[184:187], v[134:137]
	v_mfma_f32_16x16x32_bf16 v[130:133], v[176:179], v[184:187], v[130:133]
	v_mfma_f32_16x16x32_bf16 v[118:121], v[164:167], v[192:195], v[118:121]
	v_mfma_f32_16x16x32_bf16 v[114:117], v[176:179], v[192:195], v[114:117]
	v_mfma_f32_16x16x32_bf16 v[102:105], v[164:167], v[200:203], v[102:105]
	v_mfma_f32_16x16x32_bf16 v[98:101], v[176:179], v[200:203], v[98:101]
	v_mfma_f32_16x16x32_bf16 v[86:89], v[164:167], v[208:211], v[86:89]
	v_mfma_f32_16x16x32_bf16 v[82:85], v[176:179], v[208:211], v[82:85]
	v_mfma_f32_16x16x32_bf16 v[134:137], v[168:171], v[188:191], v[134:137]
	v_mfma_f32_16x16x32_bf16 v[130:133], v[180:183], v[188:191], v[130:133]
	v_mfma_f32_16x16x32_bf16 v[118:121], v[168:171], v[196:199], v[118:121]
	v_mfma_f32_16x16x32_bf16 v[114:117], v[180:183], v[196:199], v[114:117]
	v_mfma_f32_16x16x32_bf16 v[102:105], v[168:171], v[204:207], v[102:105]
	v_mfma_f32_16x16x32_bf16 v[98:101], v[180:183], v[204:207], v[98:101]
	v_mfma_f32_16x16x32_bf16 v[86:89], v[168:171], v[212:215], v[86:89]
	v_mfma_f32_16x16x32_bf16 v[82:85], v[180:183], v[212:215], v[82:85]
	s_barrier
	s_add_i32 s24, s56, s30
	s_add_i32 m0, s24, 0xffffff80
	ds_read_b128 v[184:187], v174 offset:49152
	ds_read_b128 v[188:191], v174 offset:50176
	ds_read_b128 v[192:195], v174 offset:51200
	ds_read_b128 v[196:199], v174 offset:52224
	ds_read_b128 v[200:203], v174 offset:53248
	ds_read_b128 v[204:207], v174 offset:54272
	ds_read_b128 v[208:211], v174 offset:55296
	ds_read_b128 v[212:215], v174 offset:56320
	global_load_lds_dwordx4 v148, s[98:99] offset:128
	s_add_i32 m0, s24, 0x1f80
	s_add_u32 s22, s22, 0x20080
	s_addc_u32 s23, s23, 0
	s_add_i32 s24, s57, s30
	global_load_lds_dwordx4 v152, s[98:99] offset:128
	s_mov_b32 m0, s24
	s_nop 0
	global_load_lds_dwordx4 v148, s[22:23]
	s_add_i32 m0, s24, 0x2000
	s_nop 0
	global_load_lds_dwordx4 v152, s[22:23]
	s_add_i32 m0, s40, 0xffffff80
	s_nop 0
	global_load_lds_dwordx4 v146, s[100:101] offset:128
	s_add_i32 m0, s41, 0xffffff80
	s_nop 0
	global_load_lds_dwordx4 v150, s[100:101] offset:128
	s_waitcnt vmcnt(8)
	s_waitcnt lgkmcnt(0)
	s_barrier
	s_waitcnt lgkmcnt(0)
	v_mfma_f32_16x16x32_bf16 v[70:73], v[58:61], v[184:187], v[70:73]
	v_mfma_f32_16x16x32_bf16 v[66:69], v[74:77], v[184:187], v[66:69]
	v_mfma_f32_16x16x32_bf16 v[46:49], v[58:61], v[192:195], v[46:49]
	v_mfma_f32_16x16x32_bf16 v[42:45], v[74:77], v[192:195], v[42:45]
	v_mfma_f32_16x16x32_bf16 v[30:33], v[58:61], v[200:203], v[30:33]
	v_mfma_f32_16x16x32_bf16 v[26:29], v[74:77], v[200:203], v[26:29]
	v_mfma_f32_16x16x32_bf16 v[14:17], v[58:61], v[208:211], v[14:17]
	v_mfma_f32_16x16x32_bf16 v[10:13], v[74:77], v[208:211], v[10:13]
	v_mfma_f32_16x16x32_bf16 v[70:73], v[62:65], v[188:191], v[70:73]
	v_mfma_f32_16x16x32_bf16 v[66:69], v[78:81], v[188:191], v[66:69]
	v_mfma_f32_16x16x32_bf16 v[46:49], v[62:65], v[196:199], v[46:49]
	v_mfma_f32_16x16x32_bf16 v[42:45], v[78:81], v[196:199], v[42:45]
	v_mfma_f32_16x16x32_bf16 v[30:33], v[62:65], v[204:207], v[30:33]
	v_mfma_f32_16x16x32_bf16 v[26:29], v[78:81], v[204:207], v[26:29]
	v_mfma_f32_16x16x32_bf16 v[14:17], v[62:65], v[212:215], v[14:17]
	v_mfma_f32_16x16x32_bf16 v[10:13], v[78:81], v[212:215], v[10:13]
	v_mfma_f32_16x16x32_bf16 v[54:57], v[164:167], v[184:187], v[54:57]
	v_mfma_f32_16x16x32_bf16 v[50:53], v[176:179], v[184:187], v[50:53]
	v_mfma_f32_16x16x32_bf16 v[38:41], v[164:167], v[192:195], v[38:41]
	v_mfma_f32_16x16x32_bf16 v[34:37], v[176:179], v[192:195], v[34:37]
	v_mfma_f32_16x16x32_bf16 v[22:25], v[164:167], v[200:203], v[22:25]
	v_mfma_f32_16x16x32_bf16 v[18:21], v[176:179], v[200:203], v[18:21]
	v_mfma_f32_16x16x32_bf16 v[6:9], v[164:167], v[208:211], v[6:9]
	v_mfma_f32_16x16x32_bf16 v[2:5], v[176:179], v[208:211], v[2:5]
	v_mfma_f32_16x16x32_bf16 v[54:57], v[168:171], v[188:191], v[54:57]
	v_mfma_f32_16x16x32_bf16 v[50:53], v[180:183], v[188:191], v[50:53]
	v_mfma_f32_16x16x32_bf16 v[38:41], v[168:171], v[196:199], v[38:41]
	v_mfma_f32_16x16x32_bf16 v[34:37], v[180:183], v[196:199], v[34:37]
	v_mfma_f32_16x16x32_bf16 v[22:25], v[168:171], v[204:207], v[22:25]
	v_mfma_f32_16x16x32_bf16 v[18:21], v[180:183], v[204:207], v[18:21]
	v_mfma_f32_16x16x32_bf16 v[6:9], v[168:171], v[212:215], v[6:9]
	v_mfma_f32_16x16x32_bf16 v[2:5], v[180:183], v[212:215], v[2:5]
	s_barrier
	s_add_u32 s8, s8, 0x100
	s_addc_u32 s9, s9, 0
	s_add_u32 s17, s17, 0x100
	s_addc_u32 s19, s19, 0
	s_cmp_ge_u32 s47, s7
	s_mov_b32 s22, s47
	s_cbranch_scc0 .LBB0_1092
	s_and_b64 vcc, exec, s[14:15]
	s_cbranch_vccz .LBB0_1095
	s_barrier

; #define PG8_STAGE(bufoff, gbase, voff) do { _Pragma("unroll") for (int _i = 0; _i < 2; ++_i) \
;         __builtin_amdgcn_global_load_lds((const unsigned*)((const char*)(gbase) + (voff)[_i]), (PG8_LAS unsigned*)(lds + (bufoff) + ldsw + _i * 8192), 16, 0, 0); } while (0)
; #define PG8_LDA(dst, b, h) do { _Pragma("unroll") for (int m = 0; m < 4; ++m) _Pragma("unroll") for (int k = 0; k < 2; ++k) dst[m][k] = *(const PG8_LAS bf16x8*)(lds + PG8_SA(b, h) + aoff + m * 2048 + k * 1024); } while (0)
; #define PG8_LDB(dst, b, h) do { _Pragma("unroll") for (int n = 0; n < 2; ++n) _Pragma("unroll") for (int k = 0; k < 2; ++k) dst[n][k] = *(const PG8_LAS bf16x8*)(lds + PG8_SB(b, h) + boff + n * 2048 + k * 1024); } while (0)
; #define PG8_MMA(ai, bj, At, Bt) do { __builtin_amdgcn_s_setprio(1); _Pragma("unroll") for (int m = 0; m < 4; ++m) _Pragma("unroll") for (int n = 0; n < 2; ++n) _Pragma("unroll") for (int k = 0; k < 2; ++k) \
;         acc[ai][bj][m][n] = mma_<I8>(Bt[n][k], At[m][k], acc[ai][bj][m][n]); __builtin_amdgcn_s_setprio(0); } while (0)
; #define PG8_WAIT_V(n) asm volatile("s_waitcnt vmcnt(" #n ")" ::: "memory")
; #define PG8_WAIT_L(n) asm volatile("s_waitcnt lgkmcnt(" #n ")" ::: "memory")
; #define PG8_BAR __builtin_amdgcn_s_barrier()
; template <class Epi, class Sched, bool ALIGN_EPI = false, bool SP2 = false, bool I8 = false>
; __device__ __forceinline__ void gemm_phase(PG8_LAS unsigned char* lds, const Gemm g, const Sched& S, const Epi& E) {
;     ...
;             const bool last = (t == nt - 2);
;             const char* a1 = cA + (size_t)(t + 1) * kstep;
;             const char* a2 = last ? nA : cA + (size_t)(t + 2) * kstep; const char* b2 = last ? nB : cB + (size_t)(t + 2) * kstep;
;             const char* a3 = a2 + kstep; const char* b3 = b2 + kstep;
;             if (last && has_next) S.a_ready(nxt);
;             if constexpr (SP2) {
;             PG8_LDB(B0, 0, 0); PG8_LDB(B1, 0, 1); PG8_SCHED; PG8_LDA(At, 0, 0); PG8_STAGE(PG8_SA(1, 1), a1 + hstepA, voffA);
;             PG8_WAIT_V(8); PG8_WAIT_L(0); PG8_BAR; PG8_MMA(0, 0, At, B0); PG8_MMA(0, 1, At, B1); PG8_BAR; PG8_SCHED;
;             PG8_LDA(At, 0, 1); PG8_STAGE(PG8_SB(0, 0), b2, voffB); PG8_STAGE(PG8_SB(0, 1), b2 + hstepB, voffB); PG8_STAGE(PG8_SA(0, 0), a2, voffA);
;             PG8_WAIT_V(8); PG8_WAIT_L(0); PG8_BAR; PG8_MMA(1, 0, At, B0); PG8_MMA(1, 1, At, B1); PG8_BAR; PG8_SCHED;
.LBB0_1538:
	ds_read_b128 v[146:149], v154
	ds_read_b128 v[150:153], v154 offset:1024
	ds_read_b128 v[158:161], v154 offset:2048
	ds_read_b128 v[162:165], v154 offset:3072
	ds_read_b128 v[166:169], v155
	ds_read_b128 v[170:173], v155 offset:1024
	ds_read_b128 v[174:177], v155 offset:2048
	ds_read_b128 v[178:181], v155 offset:3072
	s_add_u32 s24, s22, 0xfffe0080
	s_addc_u32 s25, s23, -1
	s_cmp_eq_u32 s49, 4
	s_cselect_b32 s27, s15, s25
	s_cselect_b32 s26, s45, s24
	s_cselect_b32 s25, s13, s48
	s_cselect_b32 s24, s46, s47
	s_add_i32 m0, s21, 0xc000
	ds_read_b128 v[182:185], v156
	ds_read_b128 v[186:189], v156 offset:1024
	ds_read_b128 v[190:193], v156 offset:2048
	ds_read_b128 v[194:197], v156 offset:3072
	ds_read_b128 v[198:201], v156 offset:4096
	ds_read_b128 v[202:205], v156 offset:5120
	ds_read_b128 v[206:209], v156 offset:6144
	ds_read_b128 v[210:213], v156 offset:7168
	global_load_lds_dwordx4 v138, s[22:23]
	s_add_i32 m0, s21, 0xe000
	s_nop 0
	global_load_lds_dwordx4 v140, s[22:23]
	s_waitcnt vmcnt(8)
	s_waitcnt lgkmcnt(0)
	s_barrier
	s_waitcnt lgkmcnt(0)
	v_mfma_f32_16x16x32_bf16 v[126:129], v[146:149], v[182:185], v[126:129]
	v_mfma_f32_16x16x32_bf16 v[122:125], v[158:161], v[182:185], v[122:125]
	v_mfma_f32_16x16x32_bf16 v[114:117], v[146:149], v[190:193], v[114:117]
	v_mfma_f32_16x16x32_bf16 v[106:109], v[158:161], v[190:193], v[106:109]
	v_mfma_f32_16x16x32_bf16 v[94:97], v[146:149], v[198:201], v[94:97]
	v_mfma_f32_16x16x32_bf16 v[90:93], v[158:161], v[198:201], v[90:93]
	v_mfma_f32_16x16x32_bf16 v[86:89], v[146:149], v[206:209], v[86:89]
	v_mfma_f32_16x16x32_bf16 v[82:85], v[158:161], v[206:209], v[82:85]
	v_mfma_f32_16x16x32_bf16 v[126:129], v[150:153], v[186:189], v[126:129]
	v_mfma_f32_16x16x32_bf16 v[122:125], v[162:165], v[186:189], v[122:125]
	v_mfma_f32_16x16x32_bf16 v[114:117], v[150:153], v[194:197], v[114:117]
	v_mfma_f32_16x16x32_bf16 v[106:109], v[162:165], v[194:197], v[106:109]
	v_mfma_f32_16x16x32_bf16 v[94:97], v[150:153], v[202:205], v[94:97]
	v_mfma_f32_16x16x32_bf16 v[90:93], v[162:165], v[202:205], v[90:93]
	v_mfma_f32_16x16x32_bf16 v[86:89], v[150:153], v[210:213], v[86:89]
	v_mfma_f32_16x16x32_bf16 v[82:85], v[162:165], v[210:213], v[82:85]
	v_mfma_f32_16x16x32_bf16 v[118:121], v[166:169], v[182:185], v[118:121]
	v_mfma_f32_16x16x32_bf16 v[110:113], v[174:177], v[182:185], v[110:113]
	v_mfma_f32_16x16x32_bf16 v[102:105], v[166:169], v[190:193], v[102:105]
	v_mfma_f32_16x16x32_bf16 v[98:101], v[174:177], v[190:193], v[98:101]
	v_mfma_f32_16x16x32_bf16 v[78:81], v[166:169], v[198:201], v[78:81]
	v_mfma_f32_16x16x32_bf16 v[74:77], v[174:177], v[198:201], v[74:77]
	v_mfma_f32_16x16x32_bf16 v[70:73], v[166:169], v[206:209], v[70:73]
	v_mfma_f32_16x16x32_bf16 v[66:69], v[174:177], v[206:209], v[66:69]
	v_mfma_f32_16x16x32_bf16 v[118:121], v[170:173], v[186:189], v[118:121]
	v_mfma_f32_16x16x32_bf16 v[110:113], v[178:181], v[186:189], v[110:113]
	v_mfma_f32_16x16x32_bf16 v[102:105], v[170:173], v[194:197], v[102:105]
	v_mfma_f32_16x16x32_bf16 v[98:101], v[178:181], v[194:197], v[98:101]
	v_mfma_f32_16x16x32_bf16 v[78:81], v[170:173], v[202:205], v[78:81]
	v_mfma_f32_16x16x32_bf16 v[74:77], v[178:181], v[202:205], v[74:77]
	v_mfma_f32_16x16x32_bf16 v[70:73], v[170:173], v[210:213], v[70:73]
	v_mfma_f32_16x16x32_bf16 v[66:69], v[178:181], v[210:213], v[66:69]
	s_barrier
	s_add_i32 s50, s42, s34
	s_mov_b64 s[98:99], s[24:25]
	s_mov_b32 m0, s50
	ds_read_b128 v[182:185], v156 offset:16384
	ds_read_b128 v[186:189], v156 offset:17408
	ds_read_b128 v[190:193], v156 offset:18432
	ds_read_b128 v[194:197], v156 offset:19456
	ds_read_b128 v[198:201], v156 offset:20480
	ds_read_b128 v[202:205], v156 offset:21504
	ds_read_b128 v[206:209], v156 offset:22528
	ds_read_b128 v[210:213], v156 offset:23552
	global_load_lds_dwordx4 v132, s[24:25]
	s_add_i32 m0, s50, 0x2000
	s_add_u32 s50, s24, 0x20000
	s_mov_b64 s[98:99], s[24:25]
	s_addc_u32 s51, s25, 0
	s_add_i32 s52, s43, s34
	global_load_lds_dwordx4 v136, s[24:25]
	s_mov_b32 m0, s52
	s_mov_b64 s[100:101], s[26:27]
	global_load_lds_dwordx4 v132, s[50:51]
	s_add_i32 m0, s52, 0x2000
	s_nop 0
	global_load_lds_dwordx4 v136, s[50:51]
	s_mov_b64 s[100:101], s[26:27]
	s_mov_b32 m0, s21
	s_nop 0
	global_load_lds_dwordx4 v130, s[26:27]
	s_mov_b32 m0, s35
	s_nop 0
	global_load_lds_dwordx4 v134, s[26:27]
	s_waitcnt vmcnt(8)
	s_waitcnt lgkmcnt(0)
	s_barrier
	s_waitcnt lgkmcnt(0)
	v_mfma_f32_16x16x32_bf16 v[62:65], v[146:149], v[182:185], v[62:65]
	v_mfma_f32_16x16x32_bf16 v[58:61], v[158:161], v[182:185], v[58:61]
	v_mfma_f32_16x16x32_bf16 v[54:57], v[146:149], v[190:193], v[54:57]
	v_mfma_f32_16x16x32_bf16 v[50:53], v[158:161], v[190:193], v[50:53]
	v_mfma_f32_16x16x32_bf16 v[30:33], v[146:149], v[198:201], v[30:33]
	v_mfma_f32_16x16x32_bf16 v[26:29], v[158:161], v[198:201], v[26:29]
	v_mfma_f32_16x16x32_bf16 v[22:25], v[146:149], v[206:209], v[22:25]
	v_mfma_f32_16x16x32_bf16 v[10:13], v[158:161], v[206:209], v[10:13]
	v_mfma_f32_16x16x32_bf16 v[62:65], v[150:153], v[186:189], v[62:65]
	v_mfma_f32_16x16x32_bf16 v[58:61], v[162:165], v[186:189], v[58:61]
	v_mfma_f32_16x16x32_bf16 v[54:57], v[150:153], v[194:197], v[54:57]
	v_mfma_f32_16x16x32_bf16 v[50:53], v[162:165], v[194:197], v[50:53]
	v_mfma_f32_16x16x32_bf16 v[30:33], v[150:153], v[202:205], v[30:33]
	v_mfma_f32_16x16x32_bf16 v[26:29], v[162:165], v[202:205], v[26:29]
	v_mfma_f32_16x16x32_bf16 v[22:25], v[150:153], v[210:213], v[22:25]
	v_mfma_f32_16x16x32_bf16 v[10:13], v[162:165], v[210:213], v[10:13]
	v_mfma_f32_16x16x32_bf16 v[46:49], v[166:169], v[182:185], v[46:49]
	v_mfma_f32_16x16x32_bf16 v[42:45], v[174:177], v[182:185], v[42:45]
	v_mfma_f32_16x16x32_bf16 v[38:41], v[166:169], v[190:193], v[38:41]
	v_mfma_f32_16x16x32_bf16 v[34:37], v[174:177], v[190:193], v[34:37]
	v_mfma_f32_16x16x32_bf16 v[18:21], v[166:169], v[198:201], v[18:21]
	v_mfma_f32_16x16x32_bf16 v[14:17], v[174:177], v[198:201], v[14:17]
	v_mfma_f32_16x16x32_bf16 v[6:9], v[166:169], v[206:209], v[6:9]
	v_mfma_f32_16x16x32_bf16 v[2:5], v[174:177], v[206:209], v[2:5]
	v_mfma_f32_16x16x32_bf16 v[46:49], v[170:173], v[186:189], v[46:49]
	v_mfma_f32_16x16x32_bf16 v[42:45], v[178:181], v[186:189], v[42:45]
	v_mfma_f32_16x16x32_bf16 v[38:41], v[170:173], v[194:197], v[38:41]
	v_mfma_f32_16x16x32_bf16 v[34:37], v[178:181], v[194:197], v[34:37]
	v_mfma_f32_16x16x32_bf16 v[18:21], v[170:173], v[202:205], v[18:21]
	v_mfma_f32_16x16x32_bf16 v[14:17], v[178:181], v[202:205], v[14:17]
	v_mfma_f32_16x16x32_bf16 v[6:9], v[170:173], v[210:213], v[6:9]
	v_mfma_f32_16x16x32_bf16 v[2:5], v[178:181], v[210:213], v[2:5]
	s_barrier
; #define PG8_STAGE(bufoff, gbase, voff) do { _Pragma("unroll") for (int _i = 0; _i < 2; ++_i) \
;         __builtin_amdgcn_global_load_lds((const unsigned*)((const char*)(gbase) + (voff)[_i]), (PG8_LAS unsigned*)(lds + (bufoff) + ldsw + _i * 8192), 16, 0, 0); } while (0)
; #define PG8_LDA(dst, b, h) do { _Pragma("unroll") for (int m = 0; m < 4; ++m) _Pragma("unroll") for (int k = 0; k < 2; ++k) dst[m][k] = *(const PG8_LAS bf16x8*)(lds + PG8_SA(b, h) + aoff + m * 2048 + k * 1024); } while (0)
; #define PG8_LDB(dst, b, h) do { _Pragma("unroll") for (int n = 0; n < 2; ++n) _Pragma("unroll") for (int k = 0; k < 2; ++k) dst[n][k] = *(const PG8_LAS bf16x8*)(lds + PG8_SB(b, h) + boff + n * 2048 + k * 1024); } while (0)
; #define PG8_MMA(ai, bj, At, Bt) do { __builtin_amdgcn_s_setprio(1); _Pragma("unroll") for (int m = 0; m < 4; ++m) _Pragma("unroll") for (int n = 0; n < 2; ++n) _Pragma("unroll") for (int k = 0; k < 2; ++k) \
;         acc[ai][bj][m][n] = mma_<I8>(Bt[n][k], At[m][k], acc[ai][bj][m][n]); __builtin_amdgcn_s_setprio(0); } while (0)
; #define PG8_WAIT_V(n) asm volatile("s_waitcnt vmcnt(" #n ")" ::: "memory")
; #define PG8_WAIT_L(n) asm volatile("s_waitcnt lgkmcnt(" #n ")" ::: "memory")
; #define PG8_BAR __builtin_amdgcn_s_barrier()
; #define PG8_SCHED __builtin_amdgcn_sched_barrier(0)
; template <class Epi, class Sched, bool ALIGN_EPI = false, bool SP2 = false, bool I8 = false>
; __device__ __forceinline__ void gemm_phase(PG8_LAS unsigned char* lds, const Gemm g, const Sched& S, const Epi& E) {
;     ...
;         for (int t = 0; t < nt; t += 2) {
;     ...
;             PG8_LDB(B0, 1, 0); PG8_LDB(B1, 1, 1); PG8_SCHED; PG8_LDA(At, 1, 0); PG8_STAGE(PG8_SA(0, 1), a2 + hstepA, voffA);
;             PG8_WAIT_V(8); PG8_WAIT_L(0); PG8_BAR; PG8_MMA(0, 0, At, B0); PG8_MMA(0, 1, At, B1); PG8_BAR; PG8_SCHED;
;             PG8_LDA(At, 1, 1); PG8_STAGE(PG8_SB(1, 0), b3, voffB); PG8_STAGE(PG8_SB(1, 1), b3 + hstepB, voffB); PG8_STAGE(PG8_SA(1, 0), a3, voffA);
;             PG8_WAIT_V(8); PG8_WAIT_L(0); PG8_BAR; PG8_MMA(1, 0, At, B0); PG8_MMA(1, 1, At, B1); PG8_BAR; PG8_SCHED;
	s_add_i32 s50, 0, 0x18000
	s_add_i32 s51, 0, 0x1c000
	ds_read_b128 v[146:149], v155 offset:16384
	ds_read_b128 v[150:153], v155 offset:17408
	ds_read_b128 v[158:161], v155 offset:18432
	ds_read_b128 v[162:165], v155 offset:19456
	ds_read_b128 v[166:169], v155 offset:32768
	ds_read_b128 v[170:173], v155 offset:33792
	ds_read_b128 v[174:177], v155 offset:34816
	ds_read_b128 v[178:181], v155 offset:35840
	s_add_u32 s26, s26, 0x20000
	s_addc_u32 s27, s27, 0
	s_mov_b32 m0, s36
	ds_read_b128 v[182:185], v156 offset:32768
	ds_read_b128 v[186:189], v156 offset:33792
	ds_read_b128 v[190:193], v156 offset:34816
	ds_read_b128 v[194:197], v156 offset:35840
	ds_read_b128 v[198:201], v156 offset:36864
	ds_read_b128 v[202:205], v156 offset:37888
	ds_read_b128 v[206:209], v156 offset:38912
	ds_read_b128 v[210:213], v156 offset:39936
	global_load_lds_dwordx4 v130, s[26:27]
	s_mov_b32 m0, s37
	s_nop 0
	global_load_lds_dwordx4 v134, s[26:27]
	s_waitcnt vmcnt(8)
	s_waitcnt lgkmcnt(0)
	s_barrier
	s_waitcnt lgkmcnt(0)
	v_mfma_f32_16x16x32_bf16 v[126:129], v[146:149], v[182:185], v[126:129]
	v_mfma_f32_16x16x32_bf16 v[122:125], v[158:161], v[182:185], v[122:125]
	v_mfma_f32_16x16x32_bf16 v[114:117], v[146:149], v[190:193], v[114:117]
	v_mfma_f32_16x16x32_bf16 v[106:109], v[158:161], v[190:193], v[106:109]
	v_mfma_f32_16x16x32_bf16 v[94:97], v[146:149], v[198:201], v[94:97]
	v_mfma_f32_16x16x32_bf16 v[90:93], v[158:161], v[198:201], v[90:93]
	v_mfma_f32_16x16x32_bf16 v[86:89], v[146:149], v[206:209], v[86:89]
	v_mfma_f32_16x16x32_bf16 v[82:85], v[158:161], v[206:209], v[82:85]
	v_mfma_f32_16x16x32_bf16 v[126:129], v[150:153], v[186:189], v[126:129]
	v_mfma_f32_16x16x32_bf16 v[122:125], v[162:165], v[186:189], v[122:125]
	v_mfma_f32_16x16x32_bf16 v[114:117], v[150:153], v[194:197], v[114:117]
	v_mfma_f32_16x16x32_bf16 v[106:109], v[162:165], v[194:197], v[106:109]
	v_mfma_f32_16x16x32_bf16 v[94:97], v[150:153], v[202:205], v[94:97]
	v_mfma_f32_16x16x32_bf16 v[90:93], v[162:165], v[202:205], v[90:93]
	v_mfma_f32_16x16x32_bf16 v[86:89], v[150:153], v[210:213], v[86:89]
	v_mfma_f32_16x16x32_bf16 v[82:85], v[162:165], v[210:213], v[82:85]
	v_mfma_f32_16x16x32_bf16 v[118:121], v[166:169], v[182:185], v[118:121]
	v_mfma_f32_16x16x32_bf16 v[110:113], v[174:177], v[182:185], v[110:113]
	v_mfma_f32_16x16x32_bf16 v[102:105], v[166:169], v[190:193], v[102:105]
	v_mfma_f32_16x16x32_bf16 v[98:101], v[174:177], v[190:193], v[98:101]
	v_mfma_f32_16x16x32_bf16 v[78:81], v[166:169], v[198:201], v[78:81]
	v_mfma_f32_16x16x32_bf16 v[74:77], v[174:177], v[198:201], v[74:77]
	v_mfma_f32_16x16x32_bf16 v[70:73], v[166:169], v[206:209], v[70:73]
	v_mfma_f32_16x16x32_bf16 v[66:69], v[174:177], v[206:209], v[66:69]
	v_mfma_f32_16x16x32_bf16 v[118:121], v[170:173], v[186:189], v[118:121]
	v_mfma_f32_16x16x32_bf16 v[110:113], v[178:181], v[186:189], v[110:113]
	v_mfma_f32_16x16x32_bf16 v[102:105], v[170:173], v[194:197], v[102:105]
	v_mfma_f32_16x16x32_bf16 v[98:101], v[178:181], v[194:197], v[98:101]
	v_mfma_f32_16x16x32_bf16 v[78:81], v[170:173], v[202:205], v[78:81]
	v_mfma_f32_16x16x32_bf16 v[74:77], v[178:181], v[202:205], v[74:77]
	v_mfma_f32_16x16x32_bf16 v[70:73], v[170:173], v[210:213], v[70:73]
	v_mfma_f32_16x16x32_bf16 v[66:69], v[178:181], v[210:213], v[66:69]
	s_barrier
	s_add_i32 s26, s50, s34
	s_add_i32 m0, s26, 0xffffff80
	ds_read_b128 v[182:185], v156 offset:49152
	ds_read_b128 v[186:189], v156 offset:50176
	ds_read_b128 v[190:193], v156 offset:51200
	ds_read_b128 v[194:197], v156 offset:52224
	ds_read_b128 v[198:201], v156 offset:53248
	ds_read_b128 v[202:205], v156 offset:54272
	ds_read_b128 v[206:209], v156 offset:55296
	ds_read_b128 v[210:213], v156 offset:56320
	global_load_lds_dwordx4 v132, s[98:99] offset:128
	s_add_i32 m0, s26, 0x1f80
	s_add_u32 s24, s24, 0x20080
	s_addc_u32 s25, s25, 0
	s_add_i32 s26, s51, s34
	global_load_lds_dwordx4 v136, s[98:99] offset:128
	s_mov_b32 m0, s26
	s_nop 0
	global_load_lds_dwordx4 v132, s[24:25]
	s_add_i32 m0, s26, 0x2000
	s_nop 0
	global_load_lds_dwordx4 v136, s[24:25]
	s_add_i32 m0, s39, 0xffffff80
	s_nop 0
	global_load_lds_dwordx4 v130, s[100:101] offset:128
	s_add_i32 m0, s40, 0xffffff80
	s_nop 0
	global_load_lds_dwordx4 v134, s[100:101] offset:128
	s_waitcnt vmcnt(8)
	s_waitcnt lgkmcnt(0)
	s_barrier
	s_waitcnt lgkmcnt(0)
	v_mfma_f32_16x16x32_bf16 v[62:65], v[146:149], v[182:185], v[62:65]
	v_mfma_f32_16x16x32_bf16 v[58:61], v[158:161], v[182:185], v[58:61]
	v_mfma_f32_16x16x32_bf16 v[54:57], v[146:149], v[190:193], v[54:57]
	v_mfma_f32_16x16x32_bf16 v[50:53], v[158:161], v[190:193], v[50:53]
	v_mfma_f32_16x16x32_bf16 v[30:33], v[146:149], v[198:201], v[30:33]
	v_mfma_f32_16x16x32_bf16 v[26:29], v[158:161], v[198:201], v[26:29]
	v_mfma_f32_16x16x32_bf16 v[22:25], v[146:149], v[206:209], v[22:25]
	v_mfma_f32_16x16x32_bf16 v[10:13], v[158:161], v[206:209], v[10:13]
	v_mfma_f32_16x16x32_bf16 v[62:65], v[150:153], v[186:189], v[62:65]
	v_mfma_f32_16x16x32_bf16 v[58:61], v[162:165], v[186:189], v[58:61]
	v_mfma_f32_16x16x32_bf16 v[54:57], v[150:153], v[194:197], v[54:57]
	v_mfma_f32_16x16x32_bf16 v[50:53], v[162:165], v[194:197], v[50:53]
	v_mfma_f32_16x16x32_bf16 v[30:33], v[150:153], v[202:205], v[30:33]
	v_mfma_f32_16x16x32_bf16 v[26:29], v[162:165], v[202:205], v[26:29]
	v_mfma_f32_16x16x32_bf16 v[22:25], v[150:153], v[210:213], v[22:25]
	v_mfma_f32_16x16x32_bf16 v[10:13], v[162:165], v[210:213], v[10:13]
	v_mfma_f32_16x16x32_bf16 v[46:49], v[166:169], v[182:185], v[46:49]
	v_mfma_f32_16x16x32_bf16 v[42:45], v[174:177], v[182:185], v[42:45]
	v_mfma_f32_16x16x32_bf16 v[38:41], v[166:169], v[190:193], v[38:41]
	v_mfma_f32_16x16x32_bf16 v[34:37], v[174:177], v[190:193], v[34:37]
	v_mfma_f32_16x16x32_bf16 v[18:21], v[166:169], v[198:201], v[18:21]
	v_mfma_f32_16x16x32_bf16 v[14:17], v[174:177], v[198:201], v[14:17]
	v_mfma_f32_16x16x32_bf16 v[6:9], v[166:169], v[206:209], v[6:9]
	v_mfma_f32_16x16x32_bf16 v[2:5], v[174:177], v[206:209], v[2:5]
	v_mfma_f32_16x16x32_bf16 v[46:49], v[170:173], v[186:189], v[46:49]
	v_mfma_f32_16x16x32_bf16 v[42:45], v[178:181], v[186:189], v[42:45]
	v_mfma_f32_16x16x32_bf16 v[38:41], v[170:173], v[194:197], v[38:41]
	v_mfma_f32_16x16x32_bf16 v[34:37], v[178:181], v[194:197], v[34:37]
	v_mfma_f32_16x16x32_bf16 v[18:21], v[170:173], v[202:205], v[18:21]
	v_mfma_f32_16x16x32_bf16 v[14:17], v[178:181], v[202:205], v[14:17]
	v_mfma_f32_16x16x32_bf16 v[6:9], v[170:173], v[210:213], v[6:9]
	v_mfma_f32_16x16x32_bf16 v[2:5], v[178:181], v[210:213], v[2:5]
	s_barrier
	s_add_i32 s49, s49, 2
	s_add_u32 s22, s22, 0x100
	s_addc_u32 s23, s23, 0
	s_add_u32 s47, s47, 0x100
	s_addc_u32 s48, s48, 0
	s_cmp_gt_u32 s49, 5
	s_cbranch_scc0 .LBB0_1538
	s_and_b64 vcc, exec, s[10:11]
	s_cbranch_vccz .LBB0_1541
	s_barrier

; #define PG8_STAGE(bufoff, gbase, voff) do { _Pragma("unroll") for (int _i = 0; _i < 2; ++_i) \
;         __builtin_amdgcn_global_load_lds((const unsigned*)((const char*)(gbase) + (voff)[_i]), (PG8_LAS unsigned*)(lds + (bufoff) + ldsw + _i * 8192), 16, 0, 0); } while (0)
; #define PG8_LDA(dst, b, h) do { _Pragma("unroll") for (int m = 0; m < 4; ++m) _Pragma("unroll") for (int k = 0; k < 2; ++k) dst[m][k] = *(const PG8_LAS bf16x8*)(lds + PG8_SA(b, h) + aoff + m * 2048 + k * 1024); } while (0)
; #define PG8_LDB(dst, b, h) do { _Pragma("unroll") for (int n = 0; n < 2; ++n) _Pragma("unroll") for (int k = 0; k < 2; ++k) dst[n][k] = *(const PG8_LAS bf16x8*)(lds + PG8_SB(b, h) + boff + n * 2048 + k * 1024); } while (0)
; #define PG8_MMA(ai, bj, At, Bt) do { __builtin_amdgcn_s_setprio(1); _Pragma("unroll") for (int m = 0; m < 4; ++m) _Pragma("unroll") for (int n = 0; n < 2; ++n) _Pragma("unroll") for (int k = 0; k < 2; ++k) \
;         acc[ai][bj][m][n] = mma_<I8>(Bt[n][k], At[m][k], acc[ai][bj][m][n]); __builtin_amdgcn_s_setprio(0); } while (0)
; #define PG8_WAIT_V(n) asm volatile("s_waitcnt vmcnt(" #n ")" ::: "memory")
; #define PG8_WAIT_L(n) asm volatile("s_waitcnt lgkmcnt(" #n ")" ::: "memory")
; #define PG8_BAR __builtin_amdgcn_s_barrier()
; template <class Epi, class Sched, bool ALIGN_EPI = false, bool SP2 = false, bool I8 = false>
; __device__ __forceinline__ void gemm_phase(PG8_LAS unsigned char* lds, const Gemm g, const Sched& S, const Epi& E) {
;     ...
;             const bool last = (t == nt - 2);
;             const char* a1 = cA + (size_t)(t + 1) * kstep;
;             const char* a2 = last ? nA : cA + (size_t)(t + 2) * kstep; const char* b2 = last ? nB : cB + (size_t)(t + 2) * kstep;
;             const char* a3 = a2 + kstep; const char* b3 = b2 + kstep;
;             if (last && has_next) S.a_ready(nxt);
;             if constexpr (SP2) {
;             PG8_LDB(B0, 0, 0); PG8_LDB(B1, 0, 1); PG8_SCHED; PG8_LDA(At, 0, 0); PG8_STAGE(PG8_SA(1, 1), a1 + hstepA, voffA);
;             PG8_WAIT_V(8); PG8_WAIT_L(0); PG8_BAR; PG8_MMA(0, 0, At, B0); PG8_MMA(0, 1, At, B1); PG8_BAR; PG8_SCHED;
;             PG8_LDA(At, 0, 1); PG8_STAGE(PG8_SB(0, 0), b2, voffB); PG8_STAGE(PG8_SB(0, 1), b2 + hstepB, voffB); PG8_STAGE(PG8_SA(0, 0), a2, voffA);
;             PG8_WAIT_V(8); PG8_WAIT_L(0); PG8_BAR; PG8_MMA(1, 0, At, B0); PG8_MMA(1, 1, At, B1); PG8_BAR; PG8_SCHED;
.LBB0_1565:
	ds_read_b128 v[130:133], v176
	ds_read_b128 v[134:137], v176 offset:1024
	ds_read_b128 v[138:141], v176 offset:2048
	ds_read_b128 v[142:145], v176 offset:3072
	ds_read_b128 v[162:165], v177
	ds_read_b128 v[166:169], v177 offset:1024
	ds_read_b128 v[170:173], v177 offset:2048
	ds_read_b128 v[180:183], v177 offset:3072
	s_add_u32 s30, s28, 0xfff80080
	s_addc_u32 s31, s29, -1
	s_cmp_eq_u32 s54, 28
	s_cselect_b32 s35, s7, s31
	s_cselect_b32 s34, s21, s30
	s_cselect_b32 s31, s19, s53
	s_cselect_b32 s30, s27, s52
	s_add_i32 m0, s40, 0xc000
	ds_read_b128 v[184:187], v178
	ds_read_b128 v[188:191], v178 offset:1024
	ds_read_b128 v[192:195], v178 offset:2048
	ds_read_b128 v[196:199], v178 offset:3072
	ds_read_b128 v[200:203], v178 offset:4096
	ds_read_b128 v[204:207], v178 offset:5120
	ds_read_b128 v[208:211], v178 offset:6144
	ds_read_b128 v[212:215], v178 offset:7168
	global_load_lds_dwordx4 v154, s[28:29]
	s_add_i32 m0, s40, 0xe000
	s_nop 0
	global_load_lds_dwordx4 v156, s[28:29]
	s_waitcnt vmcnt(8)
	s_waitcnt lgkmcnt(0)
	s_barrier
	s_waitcnt lgkmcnt(0)
	v_mfma_f32_16x16x32_bf16 v[126:129], v[130:133], v[184:187], v[126:129]
	v_mfma_f32_16x16x32_bf16 v[122:125], v[138:141], v[184:187], v[122:125]
	v_mfma_f32_16x16x32_bf16 v[110:113], v[130:133], v[192:195], v[110:113]
	v_mfma_f32_16x16x32_bf16 v[106:109], v[138:141], v[192:195], v[106:109]
	v_mfma_f32_16x16x32_bf16 v[94:97], v[130:133], v[200:203], v[94:97]
	v_mfma_f32_16x16x32_bf16 v[90:93], v[138:141], v[200:203], v[90:93]
	v_mfma_f32_16x16x32_bf16 v[78:81], v[130:133], v[208:211], v[78:81]
	v_mfma_f32_16x16x32_bf16 v[74:77], v[138:141], v[208:211], v[74:77]
	v_mfma_f32_16x16x32_bf16 v[126:129], v[134:137], v[188:191], v[126:129]
	v_mfma_f32_16x16x32_bf16 v[122:125], v[142:145], v[188:191], v[122:125]
	v_mfma_f32_16x16x32_bf16 v[110:113], v[134:137], v[196:199], v[110:113]
	v_mfma_f32_16x16x32_bf16 v[106:109], v[142:145], v[196:199], v[106:109]
	v_mfma_f32_16x16x32_bf16 v[94:97], v[134:137], v[204:207], v[94:97]
	v_mfma_f32_16x16x32_bf16 v[90:93], v[142:145], v[204:207], v[90:93]
	v_mfma_f32_16x16x32_bf16 v[78:81], v[134:137], v[212:215], v[78:81]
	v_mfma_f32_16x16x32_bf16 v[74:77], v[142:145], v[212:215], v[74:77]
	v_mfma_f32_16x16x32_bf16 v[118:121], v[162:165], v[184:187], v[118:121]
	v_mfma_f32_16x16x32_bf16 v[114:117], v[170:173], v[184:187], v[114:117]
	v_mfma_f32_16x16x32_bf16 v[102:105], v[162:165], v[192:195], v[102:105]
	v_mfma_f32_16x16x32_bf16 v[98:101], v[170:173], v[192:195], v[98:101]
	v_mfma_f32_16x16x32_bf16 v[86:89], v[162:165], v[200:203], v[86:89]
	v_mfma_f32_16x16x32_bf16 v[82:85], v[170:173], v[200:203], v[82:85]
	v_mfma_f32_16x16x32_bf16 v[70:73], v[162:165], v[208:211], v[70:73]
	v_mfma_f32_16x16x32_bf16 v[66:69], v[170:173], v[208:211], v[66:69]
	v_mfma_f32_16x16x32_bf16 v[118:121], v[166:169], v[188:191], v[118:121]
	v_mfma_f32_16x16x32_bf16 v[114:117], v[180:183], v[188:191], v[114:117]
	v_mfma_f32_16x16x32_bf16 v[102:105], v[166:169], v[196:199], v[102:105]
	v_mfma_f32_16x16x32_bf16 v[98:101], v[180:183], v[196:199], v[98:101]
	v_mfma_f32_16x16x32_bf16 v[86:89], v[166:169], v[204:207], v[86:89]
	v_mfma_f32_16x16x32_bf16 v[82:85], v[180:183], v[204:207], v[82:85]
	v_mfma_f32_16x16x32_bf16 v[70:73], v[166:169], v[212:215], v[70:73]
	v_mfma_f32_16x16x32_bf16 v[66:69], v[180:183], v[212:215], v[66:69]
	s_barrier
	s_add_i32 s55, s50, s39
	s_mov_b64 s[98:99], s[30:31]
	s_mov_b32 m0, s55
	ds_read_b128 v[184:187], v178 offset:16384
	ds_read_b128 v[188:191], v178 offset:17408
	ds_read_b128 v[192:195], v178 offset:18432
	ds_read_b128 v[196:199], v178 offset:19456
	ds_read_b128 v[200:203], v178 offset:20480
	ds_read_b128 v[204:207], v178 offset:21504
	ds_read_b128 v[208:211], v178 offset:22528
	ds_read_b128 v[212:215], v178 offset:23552
	global_load_lds_dwordx4 v148, s[30:31]
	s_add_i32 m0, s55, 0x2000
	s_add_u32 s56, s30, 0x80000
	s_mov_b64 s[98:99], s[30:31]
	s_addc_u32 s57, s31, 0
	s_add_i32 s55, s51, s39
	global_load_lds_dwordx4 v152, s[30:31]
	s_mov_b32 m0, s55
	s_mov_b64 s[100:101], s[34:35]
	global_load_lds_dwordx4 v148, s[56:57]
	s_add_i32 m0, s55, 0x2000
	s_nop 0
	global_load_lds_dwordx4 v152, s[56:57]
	s_mov_b64 s[100:101], s[34:35]
	s_mov_b32 m0, s40
	s_nop 0
	global_load_lds_dwordx4 v146, s[34:35]
	s_mov_b32 m0, s41
	s_nop 0
	global_load_lds_dwordx4 v150, s[34:35]
	s_waitcnt vmcnt(8)
	s_waitcnt lgkmcnt(0)
	s_barrier
	s_waitcnt lgkmcnt(0)
	v_mfma_f32_16x16x32_bf16 v[62:65], v[130:133], v[184:187], v[62:65]
	v_mfma_f32_16x16x32_bf16 v[58:61], v[138:141], v[184:187], v[58:61]
	v_mfma_f32_16x16x32_bf16 v[46:49], v[130:133], v[192:195], v[46:49]
	v_mfma_f32_16x16x32_bf16 v[42:45], v[138:141], v[192:195], v[42:45]
	v_mfma_f32_16x16x32_bf16 v[30:33], v[130:133], v[200:203], v[30:33]
	v_mfma_f32_16x16x32_bf16 v[26:29], v[138:141], v[200:203], v[26:29]
	v_mfma_f32_16x16x32_bf16 v[14:17], v[130:133], v[208:211], v[14:17]
	v_mfma_f32_16x16x32_bf16 v[10:13], v[138:141], v[208:211], v[10:13]
	v_mfma_f32_16x16x32_bf16 v[62:65], v[134:137], v[188:191], v[62:65]
	v_mfma_f32_16x16x32_bf16 v[58:61], v[142:145], v[188:191], v[58:61]
	v_mfma_f32_16x16x32_bf16 v[46:49], v[134:137], v[196:199], v[46:49]
	v_mfma_f32_16x16x32_bf16 v[42:45], v[142:145], v[196:199], v[42:45]
	v_mfma_f32_16x16x32_bf16 v[30:33], v[134:137], v[204:207], v[30:33]
	v_mfma_f32_16x16x32_bf16 v[26:29], v[142:145], v[204:207], v[26:29]
	v_mfma_f32_16x16x32_bf16 v[14:17], v[134:137], v[212:215], v[14:17]
	v_mfma_f32_16x16x32_bf16 v[10:13], v[142:145], v[212:215], v[10:13]
	v_mfma_f32_16x16x32_bf16 v[54:57], v[162:165], v[184:187], v[54:57]
	v_mfma_f32_16x16x32_bf16 v[50:53], v[170:173], v[184:187], v[50:53]
	v_mfma_f32_16x16x32_bf16 v[38:41], v[162:165], v[192:195], v[38:41]
	v_mfma_f32_16x16x32_bf16 v[34:37], v[170:173], v[192:195], v[34:37]
	v_mfma_f32_16x16x32_bf16 v[22:25], v[162:165], v[200:203], v[22:25]
	v_mfma_f32_16x16x32_bf16 v[18:21], v[170:173], v[200:203], v[18:21]
	v_mfma_f32_16x16x32_bf16 v[6:9], v[162:165], v[208:211], v[6:9]
	v_mfma_f32_16x16x32_bf16 v[2:5], v[170:173], v[208:211], v[2:5]
	v_mfma_f32_16x16x32_bf16 v[54:57], v[166:169], v[188:191], v[54:57]
	v_mfma_f32_16x16x32_bf16 v[50:53], v[180:183], v[188:191], v[50:53]
	v_mfma_f32_16x16x32_bf16 v[38:41], v[166:169], v[196:199], v[38:41]
	v_mfma_f32_16x16x32_bf16 v[34:37], v[180:183], v[196:199], v[34:37]
	v_mfma_f32_16x16x32_bf16 v[22:25], v[166:169], v[204:207], v[22:25]
	v_mfma_f32_16x16x32_bf16 v[18:21], v[180:183], v[204:207], v[18:21]
	v_mfma_f32_16x16x32_bf16 v[6:9], v[166:169], v[212:215], v[6:9]
	v_mfma_f32_16x16x32_bf16 v[2:5], v[180:183], v[212:215], v[2:5]
	s_barrier
; #define PG8_STAGE(bufoff, gbase, voff) do { _Pragma("unroll") for (int _i = 0; _i < 2; ++_i) \
;         __builtin_amdgcn_global_load_lds((const unsigned*)((const char*)(gbase) + (voff)[_i]), (PG8_LAS unsigned*)(lds + (bufoff) + ldsw + _i * 8192), 16, 0, 0); } while (0)
; #define PG8_LDA(dst, b, h) do { _Pragma("unroll") for (int m = 0; m < 4; ++m) _Pragma("unroll") for (int k = 0; k < 2; ++k) dst[m][k] = *(const PG8_LAS bf16x8*)(lds + PG8_SA(b, h) + aoff + m * 2048 + k * 1024); } while (0)
; #define PG8_LDB(dst, b, h) do { _Pragma("unroll") for (int n = 0; n < 2; ++n) _Pragma("unroll") for (int k = 0; k < 2; ++k) dst[n][k] = *(const PG8_LAS bf16x8*)(lds + PG8_SB(b, h) + boff + n * 2048 + k * 1024); } while (0)
; #define PG8_MMA(ai, bj, At, Bt) do { __builtin_amdgcn_s_setprio(1); _Pragma("unroll") for (int m = 0; m < 4; ++m) _Pragma("unroll") for (int n = 0; n < 2; ++n) _Pragma("unroll") for (int k = 0; k < 2; ++k) \
;         acc[ai][bj][m][n] = mma_<I8>(Bt[n][k], At[m][k], acc[ai][bj][m][n]); __builtin_amdgcn_s_setprio(0); } while (0)
; #define PG8_WAIT_V(n) asm volatile("s_waitcnt vmcnt(" #n ")" ::: "memory")
; #define PG8_WAIT_L(n) asm volatile("s_waitcnt lgkmcnt(" #n ")" ::: "memory")
; #define PG8_BAR __builtin_amdgcn_s_barrier()
; #define PG8_SCHED __builtin_amdgcn_sched_barrier(0)
; template <class Epi, class Sched, bool ALIGN_EPI = false, bool SP2 = false, bool I8 = false>
; __device__ __forceinline__ void gemm_phase(PG8_LAS unsigned char* lds, const Gemm g, const Sched& S, const Epi& E) {
;     ...
;         for (int t = 0; t < nt; t += 2) {
;     ...
;             PG8_LDB(B0, 1, 0); PG8_LDB(B1, 1, 1); PG8_SCHED; PG8_LDA(At, 1, 0); PG8_STAGE(PG8_SA(0, 1), a2 + hstepA, voffA);
;             PG8_WAIT_V(8); PG8_WAIT_L(0); PG8_BAR; PG8_MMA(0, 0, At, B0); PG8_MMA(0, 1, At, B1); PG8_BAR; PG8_SCHED;
;             PG8_LDA(At, 1, 1); PG8_STAGE(PG8_SB(1, 0), b3, voffB); PG8_STAGE(PG8_SB(1, 1), b3 + hstepB, voffB); PG8_STAGE(PG8_SA(1, 0), a3, voffA);
;             PG8_WAIT_V(8); PG8_WAIT_L(0); PG8_BAR; PG8_MMA(1, 0, At, B0); PG8_MMA(1, 1, At, B1); PG8_BAR; PG8_SCHED;
	s_add_i32 s55, 0, 0x18000
	s_add_i32 s56, 0, 0x1c000
	ds_read_b128 v[130:133], v177 offset:16384
	ds_read_b128 v[134:137], v177 offset:17408
	ds_read_b128 v[138:141], v177 offset:18432
	ds_read_b128 v[142:145], v177 offset:19456
	ds_read_b128 v[162:165], v177 offset:32768
	ds_read_b128 v[166:169], v177 offset:33792
	ds_read_b128 v[170:173], v177 offset:34816
	ds_read_b128 v[180:183], v177 offset:35840
	s_add_u32 s34, s34, 0x80000
	s_addc_u32 s35, s35, 0
	s_mov_b32 m0, s42
	ds_read_b128 v[184:187], v178 offset:32768
	ds_read_b128 v[188:191], v178 offset:33792
	ds_read_b128 v[192:195], v178 offset:34816
	ds_read_b128 v[196:199], v178 offset:35840
	ds_read_b128 v[200:203], v178 offset:36864
	ds_read_b128 v[204:207], v178 offset:37888
	ds_read_b128 v[208:211], v178 offset:38912
	ds_read_b128 v[212:215], v178 offset:39936
	global_load_lds_dwordx4 v146, s[34:35]
	s_mov_b32 m0, s43
	s_nop 0
	global_load_lds_dwordx4 v150, s[34:35]
	s_waitcnt vmcnt(8)
	s_waitcnt lgkmcnt(0)
	s_barrier
	s_waitcnt lgkmcnt(0)
	v_mfma_f32_16x16x32_bf16 v[126:129], v[130:133], v[184:187], v[126:129]
	v_mfma_f32_16x16x32_bf16 v[122:125], v[138:141], v[184:187], v[122:125]
	v_mfma_f32_16x16x32_bf16 v[110:113], v[130:133], v[192:195], v[110:113]
	v_mfma_f32_16x16x32_bf16 v[106:109], v[138:141], v[192:195], v[106:109]
	v_mfma_f32_16x16x32_bf16 v[94:97], v[130:133], v[200:203], v[94:97]
	v_mfma_f32_16x16x32_bf16 v[90:93], v[138:141], v[200:203], v[90:93]
	v_mfma_f32_16x16x32_bf16 v[78:81], v[130:133], v[208:211], v[78:81]
	v_mfma_f32_16x16x32_bf16 v[74:77], v[138:141], v[208:211], v[74:77]
	v_mfma_f32_16x16x32_bf16 v[126:129], v[134:137], v[188:191], v[126:129]
	v_mfma_f32_16x16x32_bf16 v[122:125], v[142:145], v[188:191], v[122:125]
	v_mfma_f32_16x16x32_bf16 v[110:113], v[134:137], v[196:199], v[110:113]
	v_mfma_f32_16x16x32_bf16 v[106:109], v[142:145], v[196:199], v[106:109]
	v_mfma_f32_16x16x32_bf16 v[94:97], v[134:137], v[204:207], v[94:97]
	v_mfma_f32_16x16x32_bf16 v[90:93], v[142:145], v[204:207], v[90:93]
	v_mfma_f32_16x16x32_bf16 v[78:81], v[134:137], v[212:215], v[78:81]
	v_mfma_f32_16x16x32_bf16 v[74:77], v[142:145], v[212:215], v[74:77]
	v_mfma_f32_16x16x32_bf16 v[118:121], v[162:165], v[184:187], v[118:121]
	v_mfma_f32_16x16x32_bf16 v[114:117], v[170:173], v[184:187], v[114:117]
	v_mfma_f32_16x16x32_bf16 v[102:105], v[162:165], v[192:195], v[102:105]
	v_mfma_f32_16x16x32_bf16 v[98:101], v[170:173], v[192:195], v[98:101]
	v_mfma_f32_16x16x32_bf16 v[86:89], v[162:165], v[200:203], v[86:89]
	v_mfma_f32_16x16x32_bf16 v[82:85], v[170:173], v[200:203], v[82:85]
	v_mfma_f32_16x16x32_bf16 v[70:73], v[162:165], v[208:211], v[70:73]
	v_mfma_f32_16x16x32_bf16 v[66:69], v[170:173], v[208:211], v[66:69]
	v_mfma_f32_16x16x32_bf16 v[118:121], v[166:169], v[188:191], v[118:121]
	v_mfma_f32_16x16x32_bf16 v[114:117], v[180:183], v[188:191], v[114:117]
	v_mfma_f32_16x16x32_bf16 v[102:105], v[166:169], v[196:199], v[102:105]
	v_mfma_f32_16x16x32_bf16 v[98:101], v[180:183], v[196:199], v[98:101]
	v_mfma_f32_16x16x32_bf16 v[86:89], v[166:169], v[204:207], v[86:89]
	v_mfma_f32_16x16x32_bf16 v[82:85], v[180:183], v[204:207], v[82:85]
	v_mfma_f32_16x16x32_bf16 v[70:73], v[166:169], v[212:215], v[70:73]
	v_mfma_f32_16x16x32_bf16 v[66:69], v[180:183], v[212:215], v[66:69]
	s_barrier
	s_add_i32 s34, s55, s39
	s_add_i32 m0, s34, 0xffffff80
	ds_read_b128 v[184:187], v178 offset:49152
	ds_read_b128 v[188:191], v178 offset:50176
	ds_read_b128 v[192:195], v178 offset:51200
	ds_read_b128 v[196:199], v178 offset:52224
	ds_read_b128 v[200:203], v178 offset:53248
	ds_read_b128 v[204:207], v178 offset:54272
	ds_read_b128 v[208:211], v178 offset:55296
	ds_read_b128 v[212:215], v178 offset:56320
	global_load_lds_dwordx4 v148, s[98:99] offset:128
	s_add_i32 m0, s34, 0x1f80
	s_add_u32 s30, s30, 0x80080
	s_addc_u32 s31, s31, 0
	s_add_i32 s34, s56, s39
	global_load_lds_dwordx4 v152, s[98:99] offset:128
	s_mov_b32 m0, s34
	s_nop 0
	global_load_lds_dwordx4 v148, s[30:31]
	s_add_i32 m0, s34, 0x2000
	s_nop 0
	global_load_lds_dwordx4 v152, s[30:31]
	s_add_i32 m0, s46, 0xffffff80
	s_nop 0
	global_load_lds_dwordx4 v146, s[100:101] offset:128
	s_add_i32 m0, s47, 0xffffff80
	s_nop 0
	global_load_lds_dwordx4 v150, s[100:101] offset:128
	s_waitcnt vmcnt(8)
	s_waitcnt lgkmcnt(0)
	s_barrier
	s_waitcnt lgkmcnt(0)
	v_mfma_f32_16x16x32_bf16 v[62:65], v[130:133], v[184:187], v[62:65]
	v_mfma_f32_16x16x32_bf16 v[58:61], v[138:141], v[184:187], v[58:61]
	v_mfma_f32_16x16x32_bf16 v[46:49], v[130:133], v[192:195], v[46:49]
	v_mfma_f32_16x16x32_bf16 v[42:45], v[138:141], v[192:195], v[42:45]
	v_mfma_f32_16x16x32_bf16 v[30:33], v[130:133], v[200:203], v[30:33]
	v_mfma_f32_16x16x32_bf16 v[26:29], v[138:141], v[200:203], v[26:29]
	v_mfma_f32_16x16x32_bf16 v[14:17], v[130:133], v[208:211], v[14:17]
	v_mfma_f32_16x16x32_bf16 v[10:13], v[138:141], v[208:211], v[10:13]
	v_mfma_f32_16x16x32_bf16 v[62:65], v[134:137], v[188:191], v[62:65]
	v_mfma_f32_16x16x32_bf16 v[58:61], v[142:145], v[188:191], v[58:61]
	v_mfma_f32_16x16x32_bf16 v[46:49], v[134:137], v[196:199], v[46:49]
	v_mfma_f32_16x16x32_bf16 v[42:45], v[142:145], v[196:199], v[42:45]
	v_mfma_f32_16x16x32_bf16 v[30:33], v[134:137], v[204:207], v[30:33]
	v_mfma_f32_16x16x32_bf16 v[26:29], v[142:145], v[204:207], v[26:29]
	v_mfma_f32_16x16x32_bf16 v[14:17], v[134:137], v[212:215], v[14:17]
	v_mfma_f32_16x16x32_bf16 v[10:13], v[142:145], v[212:215], v[10:13]
	v_mfma_f32_16x16x32_bf16 v[54:57], v[162:165], v[184:187], v[54:57]
	v_mfma_f32_16x16x32_bf16 v[50:53], v[170:173], v[184:187], v[50:53]
	v_mfma_f32_16x16x32_bf16 v[38:41], v[162:165], v[192:195], v[38:41]
	v_mfma_f32_16x16x32_bf16 v[34:37], v[170:173], v[192:195], v[34:37]
	v_mfma_f32_16x16x32_bf16 v[22:25], v[162:165], v[200:203], v[22:25]
	v_mfma_f32_16x16x32_bf16 v[18:21], v[170:173], v[200:203], v[18:21]
	v_mfma_f32_16x16x32_bf16 v[6:9], v[162:165], v[208:211], v[6:9]
	v_mfma_f32_16x16x32_bf16 v[2:5], v[170:173], v[208:211], v[2:5]
	v_mfma_f32_16x16x32_bf16 v[54:57], v[166:169], v[188:191], v[54:57]
	v_mfma_f32_16x16x32_bf16 v[50:53], v[180:183], v[188:191], v[50:53]
	v_mfma_f32_16x16x32_bf16 v[38:41], v[166:169], v[196:199], v[38:41]
	v_mfma_f32_16x16x32_bf16 v[34:37], v[180:183], v[196:199], v[34:37]
	v_mfma_f32_16x16x32_bf16 v[22:25], v[166:169], v[204:207], v[22:25]
	v_mfma_f32_16x16x32_bf16 v[18:21], v[180:183], v[204:207], v[18:21]
	v_mfma_f32_16x16x32_bf16 v[6:9], v[166:169], v[212:215], v[6:9]
	v_mfma_f32_16x16x32_bf16 v[2:5], v[180:183], v[212:215], v[2:5]
	s_barrier
	s_add_i32 s54, s54, 2
	s_add_u32 s28, s28, 0x100
	s_addc_u32 s29, s29, 0
	s_add_u32 s52, s52, 0x100
	s_addc_u32 s53, s53, 0
	s_cmp_gt_u32 s54, 29
	s_cbranch_scc0 .LBB0_1565
	s_and_b64 vcc, exec, s[16:17]
	s_cbranch_vccz .LBB0_1568
	s_barrier

; #define PG8_STAGE(bufoff, gbase, voff) do { _Pragma("unroll") for (int _i = 0; _i < 2; ++_i) \
;         __builtin_amdgcn_global_load_lds((const unsigned*)((const char*)(gbase) + (voff)[_i]), (PG8_LAS unsigned*)(lds + (bufoff) + ldsw + _i * 8192), 16, 0, 0); } while (0)
; #define PG8_LDA(dst, b, h) do { _Pragma("unroll") for (int m = 0; m < 4; ++m) _Pragma("unroll") for (int k = 0; k < 2; ++k) dst[m][k] = *(const PG8_LAS bf16x8*)(lds + PG8_SA(b, h) + aoff + m * 2048 + k * 1024); } while (0)
; #define PG8_LDB(dst, b, h) do { _Pragma("unroll") for (int n = 0; n < 2; ++n) _Pragma("unroll") for (int k = 0; k < 2; ++k) dst[n][k] = *(const PG8_LAS bf16x8*)(lds + PG8_SB(b, h) + boff + n * 2048 + k * 1024); } while (0)
; #define PG8_MMA(ai, bj, At, Bt) do { __builtin_amdgcn_s_setprio(1); _Pragma("unroll") for (int m = 0; m < 4; ++m) _Pragma("unroll") for (int n = 0; n < 2; ++n) _Pragma("unroll") for (int k = 0; k < 2; ++k) \
;         acc[ai][bj][m][n] = mma_<I8>(Bt[n][k], At[m][k], acc[ai][bj][m][n]); __builtin_amdgcn_s_setprio(0); } while (0)
; #define PG8_WAIT_V(n) asm volatile("s_waitcnt vmcnt(" #n ")" ::: "memory")
; #define PG8_WAIT_L(n) asm volatile("s_waitcnt lgkmcnt(" #n ")" ::: "memory")
; #define PG8_BAR __builtin_amdgcn_s_barrier()
; template <class Epi, class Sched, bool ALIGN_EPI = false, bool SP2 = false, bool I8 = false>
; __device__ __forceinline__ void gemm_phase(PG8_LAS unsigned char* lds, const Gemm g, const Sched& S, const Epi& E) {
;     ...
;             const bool last = (t == nt - 2);
;             const char* a1 = cA + (size_t)(t + 1) * kstep;
;             const char* a2 = last ? nA : cA + (size_t)(t + 2) * kstep; const char* b2 = last ? nB : cB + (size_t)(t + 2) * kstep;
;             const char* a3 = a2 + kstep; const char* b3 = b2 + kstep;
;             if (last && has_next) S.a_ready(nxt);
;             if constexpr (SP2) {
;             PG8_LDB(B0, 0, 0); PG8_LDB(B1, 0, 1); PG8_SCHED; PG8_LDA(At, 0, 0); PG8_STAGE(PG8_SA(1, 1), a1 + hstepA, voffA);
;             PG8_WAIT_V(8); PG8_WAIT_L(0); PG8_BAR; PG8_MMA(0, 0, At, B0); PG8_MMA(0, 1, At, B1); PG8_BAR; PG8_SCHED;
;             PG8_LDA(At, 0, 1); PG8_STAGE(PG8_SB(0, 0), b2, voffB); PG8_STAGE(PG8_SB(0, 1), b2 + hstepB, voffB); PG8_STAGE(PG8_SA(0, 0), a2, voffA);
;             PG8_WAIT_V(8); PG8_WAIT_L(0); PG8_BAR; PG8_MMA(1, 0, At, B0); PG8_MMA(1, 1, At, B1); PG8_BAR; PG8_SCHED;
.LBB0_1721:
	ds_read_b128 v[34:37], v233
	ds_read_b128 v[38:41], v233 offset:1024
	ds_read_b128 v[42:45], v233 offset:2048
	ds_read_b128 v[62:65], v233 offset:3072
	ds_read_b128 v[146:149], v234
	ds_read_b128 v[150:153], v234 offset:1024
	ds_read_b128 v[154:157], v234 offset:2048
	ds_read_b128 v[158:161], v234 offset:3072
	s_add_u32 s34, s8, 0xfff80080
	s_addc_u32 s35, s9, -1
	s_cmp_eq_u32 s55, 28
	s_cselect_b32 s37, s3, s35
	s_cselect_b32 s36, s7, s34
	s_cselect_b32 s35, s25, s54
	s_cselect_b32 s34, s27, s33
	s_add_i32 m0, s43, 0xc000
	ds_read_b128 v[162:165], v235
	ds_read_b128 v[166:169], v235 offset:1024
	ds_read_b128 v[170:173], v235 offset:2048
	ds_read_b128 v[186:189], v235 offset:3072
	ds_read_b128 v[190:193], v235 offset:4096
	ds_read_b128 v[194:197], v235 offset:5120
	ds_read_b128 v[198:201], v235 offset:6144
	ds_read_b128 v[202:205], v235 offset:7168
	global_load_lds_dwordx4 v178, s[8:9]
	s_add_i32 m0, s43, 0xe000
	s_nop 0
	global_load_lds_dwordx4 v180, s[8:9]
	s_waitcnt vmcnt(8)
	s_waitcnt lgkmcnt(0)
	s_barrier
	s_waitcnt lgkmcnt(0)
	v_mfma_i32_16x16x64_i8 v[142:145], v[34:37], v[162:165], v[142:145]
	v_mfma_i32_16x16x64_i8 v[138:141], v[42:45], v[162:165], v[138:141]
	v_mfma_i32_16x16x64_i8 v[126:129], v[34:37], v[170:173], v[126:129]
	v_mfma_i32_16x16x64_i8 v[122:125], v[42:45], v[170:173], v[122:125]
	v_mfma_i32_16x16x64_i8 v[110:113], v[34:37], v[190:193], v[110:113]
	v_mfma_i32_16x16x64_i8 v[106:109], v[42:45], v[190:193], v[106:109]
	v_mfma_i32_16x16x64_i8 v[94:97], v[34:37], v[198:201], v[94:97]
	v_mfma_i32_16x16x64_i8 v[90:93], v[42:45], v[198:201], v[90:93]
	v_mfma_i32_16x16x64_i8 v[142:145], v[38:41], v[166:169], v[142:145]
	v_mfma_i32_16x16x64_i8 v[138:141], v[62:65], v[166:169], v[138:141]
	v_mfma_i32_16x16x64_i8 v[126:129], v[38:41], v[186:189], v[126:129]
	v_mfma_i32_16x16x64_i8 v[122:125], v[62:65], v[186:189], v[122:125]
	v_mfma_i32_16x16x64_i8 v[110:113], v[38:41], v[194:197], v[110:113]
	v_mfma_i32_16x16x64_i8 v[106:109], v[62:65], v[194:197], v[106:109]
	v_mfma_i32_16x16x64_i8 v[94:97], v[38:41], v[202:205], v[94:97]
	v_mfma_i32_16x16x64_i8 v[90:93], v[62:65], v[202:205], v[90:93]
	v_mfma_i32_16x16x64_i8 v[134:137], v[146:149], v[162:165], v[134:137]
	v_mfma_i32_16x16x64_i8 v[130:133], v[154:157], v[162:165], v[130:133]
	v_mfma_i32_16x16x64_i8 v[118:121], v[146:149], v[170:173], v[118:121]
	v_mfma_i32_16x16x64_i8 v[114:117], v[154:157], v[170:173], v[114:117]
	v_mfma_i32_16x16x64_i8 v[102:105], v[146:149], v[190:193], v[102:105]
	v_mfma_i32_16x16x64_i8 v[98:101], v[154:157], v[190:193], v[98:101]
	v_mfma_i32_16x16x64_i8 v[86:89], v[146:149], v[198:201], v[86:89]
	v_mfma_i32_16x16x64_i8 v[82:85], v[154:157], v[198:201], v[82:85]
	v_mfma_i32_16x16x64_i8 v[134:137], v[150:153], v[166:169], v[134:137]
	v_mfma_i32_16x16x64_i8 v[130:133], v[158:161], v[166:169], v[130:133]
	v_mfma_i32_16x16x64_i8 v[118:121], v[150:153], v[186:189], v[118:121]
	v_mfma_i32_16x16x64_i8 v[114:117], v[158:161], v[186:189], v[114:117]
	v_mfma_i32_16x16x64_i8 v[102:105], v[150:153], v[194:197], v[102:105]
	v_mfma_i32_16x16x64_i8 v[98:101], v[158:161], v[194:197], v[98:101]
	v_mfma_i32_16x16x64_i8 v[86:89], v[150:153], v[202:205], v[86:89]
	v_mfma_i32_16x16x64_i8 v[82:85], v[158:161], v[202:205], v[82:85]
	s_barrier
	s_add_i32 s56, s52, s40
	s_mov_b64 s[98:99], s[34:35]
	s_mov_b32 m0, s56
	ds_read_b128 v[162:165], v235 offset:16384
	ds_read_b128 v[166:169], v235 offset:17408
	ds_read_b128 v[170:173], v235 offset:18432
	ds_read_b128 v[186:189], v235 offset:19456
	ds_read_b128 v[190:193], v235 offset:20480
	ds_read_b128 v[194:197], v235 offset:21504
	ds_read_b128 v[198:201], v235 offset:22528
	ds_read_b128 v[202:205], v235 offset:23552
	global_load_lds_dwordx4 v174, s[34:35]
	s_add_i32 m0, s56, 0x2000
	s_add_u32 s56, s34, 0x80000
	s_mov_b64 s[98:99], s[34:35]
	s_addc_u32 s57, s35, 0
	s_add_i32 s58, s53, s40
	global_load_lds_dwordx4 v176, s[34:35]
	s_mov_b32 m0, s58
	s_mov_b64 s[100:101], s[36:37]
	global_load_lds_dwordx4 v174, s[56:57]
	s_add_i32 m0, s58, 0x2000
	s_nop 0
	global_load_lds_dwordx4 v176, s[56:57]
	s_mov_b64 s[100:101], s[36:37]
	s_mov_b32 m0, s43
	s_nop 0
	global_load_lds_dwordx4 v174, s[36:37]
	s_mov_b32 m0, s44
	s_nop 0
	global_load_lds_dwordx4 v176, s[36:37]
	s_waitcnt vmcnt(8)
	s_waitcnt lgkmcnt(0)
	s_barrier
	s_waitcnt lgkmcnt(0)
	v_mfma_i32_16x16x64_i8 v[78:81], v[34:37], v[162:165], v[78:81]
	v_mfma_i32_16x16x64_i8 v[74:77], v[42:45], v[162:165], v[74:77]
	v_mfma_i32_16x16x64_i8 v[58:61], v[34:37], v[170:173], v[58:61]
	v_mfma_i32_16x16x64_i8 v[54:57], v[42:45], v[170:173], v[54:57]
	v_mfma_i32_16x16x64_i8 v[30:33], v[34:37], v[190:193], v[30:33]
	v_mfma_i32_16x16x64_i8 v[26:29], v[42:45], v[190:193], v[26:29]
	v_mfma_i32_16x16x64_i8 v[14:17], v[34:37], v[198:201], v[14:17]
	v_mfma_i32_16x16x64_i8 v[10:13], v[42:45], v[198:201], v[10:13]
	v_mfma_i32_16x16x64_i8 v[78:81], v[38:41], v[166:169], v[78:81]
	v_mfma_i32_16x16x64_i8 v[74:77], v[62:65], v[166:169], v[74:77]
	v_mfma_i32_16x16x64_i8 v[58:61], v[38:41], v[186:189], v[58:61]
	v_mfma_i32_16x16x64_i8 v[54:57], v[62:65], v[186:189], v[54:57]
	v_mfma_i32_16x16x64_i8 v[30:33], v[38:41], v[194:197], v[30:33]
	v_mfma_i32_16x16x64_i8 v[26:29], v[62:65], v[194:197], v[26:29]
	v_mfma_i32_16x16x64_i8 v[14:17], v[38:41], v[202:205], v[14:17]
	v_mfma_i32_16x16x64_i8 v[10:13], v[62:65], v[202:205], v[10:13]
	v_mfma_i32_16x16x64_i8 v[46:49], v[154:157], v[170:173], v[46:49]
	v_mfma_i32_16x16x64_i8 v[22:25], v[146:149], v[190:193], v[22:25]
	v_mfma_i32_16x16x64_i8 v[18:21], v[154:157], v[190:193], v[18:21]
	v_mfma_i32_16x16x64_i8 v[6:9], v[146:149], v[198:201], v[6:9]
	v_mfma_i32_16x16x64_i8 v[2:5], v[154:157], v[198:201], v[2:5]
	v_mfma_i32_16x16x64_i8 v[34:37], v[146:149], v[162:165], v[70:73]
	v_mfma_i32_16x16x64_i8 v[38:41], v[154:157], v[162:165], v[66:69]
	v_mfma_i32_16x16x64_i8 v[42:45], v[146:149], v[170:173], v[50:53]
	v_mfma_i32_16x16x64_i8 v[46:49], v[158:161], v[186:189], v[46:49]
	v_mfma_i32_16x16x64_i8 v[22:25], v[150:153], v[194:197], v[22:25]
	v_mfma_i32_16x16x64_i8 v[18:21], v[158:161], v[194:197], v[18:21]
	v_mfma_i32_16x16x64_i8 v[6:9], v[150:153], v[202:205], v[6:9]
	v_mfma_i32_16x16x64_i8 v[2:5], v[158:161], v[202:205], v[2:5]
	v_mfma_i32_16x16x64_i8 v[34:37], v[150:153], v[166:169], v[34:37]
	v_mfma_i32_16x16x64_i8 v[38:41], v[158:161], v[166:169], v[38:41]
	v_mfma_i32_16x16x64_i8 v[42:45], v[150:153], v[186:189], v[42:45]
	s_barrier
; #define PG8_STAGE(bufoff, gbase, voff) do { _Pragma("unroll") for (int _i = 0; _i < 2; ++_i) \
;         __builtin_amdgcn_global_load_lds((const unsigned*)((const char*)(gbase) + (voff)[_i]), (PG8_LAS unsigned*)(lds + (bufoff) + ldsw + _i * 8192), 16, 0, 0); } while (0)
; #define PG8_LDA(dst, b, h) do { _Pragma("unroll") for (int m = 0; m < 4; ++m) _Pragma("unroll") for (int k = 0; k < 2; ++k) dst[m][k] = *(const PG8_LAS bf16x8*)(lds + PG8_SA(b, h) + aoff + m * 2048 + k * 1024); } while (0)
; #define PG8_LDB(dst, b, h) do { _Pragma("unroll") for (int n = 0; n < 2; ++n) _Pragma("unroll") for (int k = 0; k < 2; ++k) dst[n][k] = *(const PG8_LAS bf16x8*)(lds + PG8_SB(b, h) + boff + n * 2048 + k * 1024); } while (0)
; #define PG8_MMA(ai, bj, At, Bt) do { __builtin_amdgcn_s_setprio(1); _Pragma("unroll") for (int m = 0; m < 4; ++m) _Pragma("unroll") for (int n = 0; n < 2; ++n) _Pragma("unroll") for (int k = 0; k < 2; ++k) \
;         acc[ai][bj][m][n] = mma_<I8>(Bt[n][k], At[m][k], acc[ai][bj][m][n]); __builtin_amdgcn_s_setprio(0); } while (0)
; #define PG8_WAIT_V(n) asm volatile("s_waitcnt vmcnt(" #n ")" ::: "memory")
; #define PG8_WAIT_L(n) asm volatile("s_waitcnt lgkmcnt(" #n ")" ::: "memory")
; #define PG8_BAR __builtin_amdgcn_s_barrier()
; #define PG8_SCHED __builtin_amdgcn_sched_barrier(0)
; template <class Epi, class Sched, bool ALIGN_EPI = false, bool SP2 = false, bool I8 = false>
; __device__ __forceinline__ void gemm_phase(PG8_LAS unsigned char* lds, const Gemm g, const Sched& S, const Epi& E) {
;     ...
;         for (int t = 0; t < nt; t += 2) {
;     ...
;             PG8_LDB(B0, 1, 0); PG8_LDB(B1, 1, 1); PG8_SCHED; PG8_LDA(At, 1, 0); PG8_STAGE(PG8_SA(0, 1), a2 + hstepA, voffA);
;             PG8_WAIT_V(8); PG8_WAIT_L(0); PG8_BAR; PG8_MMA(0, 0, At, B0); PG8_MMA(0, 1, At, B1); PG8_BAR; PG8_SCHED;
;             PG8_LDA(At, 1, 1); PG8_STAGE(PG8_SB(1, 0), b3, voffB); PG8_STAGE(PG8_SB(1, 1), b3 + hstepB, voffB); PG8_STAGE(PG8_SA(1, 0), a3, voffA);
;             PG8_WAIT_V(8); PG8_WAIT_L(0); PG8_BAR; PG8_MMA(1, 0, At, B0); PG8_MMA(1, 1, At, B1); PG8_BAR; PG8_SCHED;
	s_add_i32 s56, 0, 0x18000
	s_add_i32 s57, 0, 0x1c000
	ds_read_b128 v[50:53], v234 offset:16384
	ds_read_b128 v[62:65], v234 offset:17408
	ds_read_b128 v[66:69], v234 offset:18432
	ds_read_b128 v[70:73], v234 offset:19456
	ds_read_b128 v[146:149], v234 offset:32768
	ds_read_b128 v[150:153], v234 offset:33792
	ds_read_b128 v[154:157], v234 offset:34816
	ds_read_b128 v[158:161], v234 offset:35840
	s_add_u32 s36, s36, 0x80000
	s_addc_u32 s37, s37, 0
	s_mov_b32 m0, s45
	ds_read_b128 v[162:165], v235 offset:32768
	ds_read_b128 v[166:169], v235 offset:33792
	ds_read_b128 v[170:173], v235 offset:34816
	ds_read_b128 v[186:189], v235 offset:35840
	ds_read_b128 v[190:193], v235 offset:36864
	ds_read_b128 v[194:197], v235 offset:37888
	ds_read_b128 v[198:201], v235 offset:38912
	ds_read_b128 v[202:205], v235 offset:39936
	global_load_lds_dwordx4 v174, s[36:37]
	s_mov_b32 m0, s46
	s_nop 0
	global_load_lds_dwordx4 v176, s[36:37]
	s_waitcnt vmcnt(8)
	s_waitcnt lgkmcnt(0)
	s_barrier
	s_waitcnt lgkmcnt(0)
	v_mfma_i32_16x16x64_i8 v[142:145], v[50:53], v[162:165], v[142:145]
	v_mfma_i32_16x16x64_i8 v[138:141], v[66:69], v[162:165], v[138:141]
	v_mfma_i32_16x16x64_i8 v[126:129], v[50:53], v[170:173], v[126:129]
	v_mfma_i32_16x16x64_i8 v[122:125], v[66:69], v[170:173], v[122:125]
	v_mfma_i32_16x16x64_i8 v[110:113], v[50:53], v[190:193], v[110:113]
	v_mfma_i32_16x16x64_i8 v[106:109], v[66:69], v[190:193], v[106:109]
	v_mfma_i32_16x16x64_i8 v[94:97], v[50:53], v[198:201], v[94:97]
	v_mfma_i32_16x16x64_i8 v[90:93], v[66:69], v[198:201], v[90:93]
	v_mfma_i32_16x16x64_i8 v[142:145], v[62:65], v[166:169], v[142:145]
	v_mfma_i32_16x16x64_i8 v[138:141], v[70:73], v[166:169], v[138:141]
	v_mfma_i32_16x16x64_i8 v[126:129], v[62:65], v[186:189], v[126:129]
	v_mfma_i32_16x16x64_i8 v[122:125], v[70:73], v[186:189], v[122:125]
	v_mfma_i32_16x16x64_i8 v[110:113], v[62:65], v[194:197], v[110:113]
	v_mfma_i32_16x16x64_i8 v[106:109], v[70:73], v[194:197], v[106:109]
	v_mfma_i32_16x16x64_i8 v[94:97], v[62:65], v[202:205], v[94:97]
	v_mfma_i32_16x16x64_i8 v[90:93], v[70:73], v[202:205], v[90:93]
	v_mfma_i32_16x16x64_i8 v[134:137], v[146:149], v[162:165], v[134:137]
	v_mfma_i32_16x16x64_i8 v[130:133], v[154:157], v[162:165], v[130:133]
	v_mfma_i32_16x16x64_i8 v[118:121], v[146:149], v[170:173], v[118:121]
	v_mfma_i32_16x16x64_i8 v[114:117], v[154:157], v[170:173], v[114:117]
	v_mfma_i32_16x16x64_i8 v[102:105], v[146:149], v[190:193], v[102:105]
	v_mfma_i32_16x16x64_i8 v[98:101], v[154:157], v[190:193], v[98:101]
	v_mfma_i32_16x16x64_i8 v[86:89], v[146:149], v[198:201], v[86:89]
	v_mfma_i32_16x16x64_i8 v[82:85], v[154:157], v[198:201], v[82:85]
	v_mfma_i32_16x16x64_i8 v[134:137], v[150:153], v[166:169], v[134:137]
	v_mfma_i32_16x16x64_i8 v[130:133], v[158:161], v[166:169], v[130:133]
	v_mfma_i32_16x16x64_i8 v[118:121], v[150:153], v[186:189], v[118:121]
	v_mfma_i32_16x16x64_i8 v[114:117], v[158:161], v[186:189], v[114:117]
	v_mfma_i32_16x16x64_i8 v[102:105], v[150:153], v[194:197], v[102:105]
	v_mfma_i32_16x16x64_i8 v[98:101], v[158:161], v[194:197], v[98:101]
	v_mfma_i32_16x16x64_i8 v[86:89], v[150:153], v[202:205], v[86:89]
	v_mfma_i32_16x16x64_i8 v[82:85], v[158:161], v[202:205], v[82:85]
	s_barrier
	s_add_i32 s36, s56, s40
	s_add_i32 m0, s36, 0xffffff80
	ds_read_b128 v[162:165], v235 offset:49152
	ds_read_b128 v[166:169], v235 offset:50176
	ds_read_b128 v[170:173], v235 offset:51200
	ds_read_b128 v[186:189], v235 offset:52224
	ds_read_b128 v[190:193], v235 offset:53248
	ds_read_b128 v[194:197], v235 offset:54272
	ds_read_b128 v[198:201], v235 offset:55296
	ds_read_b128 v[202:205], v235 offset:56320
	global_load_lds_dwordx4 v174, s[98:99] offset:128
	s_add_i32 m0, s36, 0x1f80
	s_add_u32 s34, s34, 0x80080
	s_addc_u32 s35, s35, 0
	s_add_i32 s36, s57, s40
	global_load_lds_dwordx4 v176, s[98:99] offset:128
	s_mov_b32 m0, s36
	s_nop 0
	global_load_lds_dwordx4 v174, s[34:35]
	s_add_i32 m0, s36, 0x2000
	s_nop 0
	global_load_lds_dwordx4 v176, s[34:35]
	s_add_i32 m0, s48, 0xffffff80
	s_nop 0
	global_load_lds_dwordx4 v174, s[100:101] offset:128
	s_add_i32 m0, s49, 0xffffff80
	s_nop 0
	global_load_lds_dwordx4 v176, s[100:101] offset:128
	s_waitcnt vmcnt(8)
	s_waitcnt lgkmcnt(0)
	s_barrier
	s_waitcnt lgkmcnt(0)
	v_mfma_i32_16x16x64_i8 v[78:81], v[50:53], v[162:165], v[78:81]
	v_mfma_i32_16x16x64_i8 v[74:77], v[66:69], v[162:165], v[74:77]
	v_mfma_i32_16x16x64_i8 v[58:61], v[50:53], v[170:173], v[58:61]
	v_mfma_i32_16x16x64_i8 v[54:57], v[66:69], v[170:173], v[54:57]
	v_mfma_i32_16x16x64_i8 v[30:33], v[50:53], v[190:193], v[30:33]
	v_mfma_i32_16x16x64_i8 v[26:29], v[66:69], v[190:193], v[26:29]
	v_mfma_i32_16x16x64_i8 v[14:17], v[50:53], v[198:201], v[14:17]
	v_mfma_i32_16x16x64_i8 v[10:13], v[66:69], v[198:201], v[10:13]
	v_mfma_i32_16x16x64_i8 v[78:81], v[62:65], v[166:169], v[78:81]
	v_mfma_i32_16x16x64_i8 v[74:77], v[70:73], v[166:169], v[74:77]
	v_mfma_i32_16x16x64_i8 v[58:61], v[62:65], v[186:189], v[58:61]
	v_mfma_i32_16x16x64_i8 v[54:57], v[70:73], v[186:189], v[54:57]
	v_mfma_i32_16x16x64_i8 v[30:33], v[62:65], v[194:197], v[30:33]
	v_mfma_i32_16x16x64_i8 v[26:29], v[70:73], v[194:197], v[26:29]
	v_mfma_i32_16x16x64_i8 v[14:17], v[62:65], v[202:205], v[14:17]
	v_mfma_i32_16x16x64_i8 v[10:13], v[70:73], v[202:205], v[10:13]
	v_mfma_i32_16x16x64_i8 v[34:37], v[146:149], v[162:165], v[34:37]
	v_mfma_i32_16x16x64_i8 v[70:73], v[150:153], v[166:169], v[34:37]
	v_mfma_i32_16x16x64_i8 v[34:37], v[154:157], v[162:165], v[38:41]
	v_mfma_i32_16x16x64_i8 v[66:69], v[158:161], v[166:169], v[34:37]
	v_mfma_i32_16x16x64_i8 v[34:37], v[146:149], v[170:173], v[42:45]
	v_mfma_i32_16x16x64_i8 v[50:53], v[150:153], v[186:189], v[34:37]
	v_mfma_i32_16x16x64_i8 v[34:37], v[154:157], v[170:173], v[46:49]
	v_mfma_i32_16x16x64_i8 v[22:25], v[146:149], v[190:193], v[22:25]
	v_mfma_i32_16x16x64_i8 v[18:21], v[154:157], v[190:193], v[18:21]
	v_mfma_i32_16x16x64_i8 v[6:9], v[146:149], v[198:201], v[6:9]
	v_mfma_i32_16x16x64_i8 v[2:5], v[154:157], v[198:201], v[2:5]
	v_mfma_i32_16x16x64_i8 v[46:49], v[158:161], v[186:189], v[34:37]
	v_mfma_i32_16x16x64_i8 v[22:25], v[150:153], v[194:197], v[22:25]
	v_mfma_i32_16x16x64_i8 v[18:21], v[158:161], v[194:197], v[18:21]
	v_mfma_i32_16x16x64_i8 v[6:9], v[150:153], v[202:205], v[6:9]
	v_mfma_i32_16x16x64_i8 v[2:5], v[158:161], v[202:205], v[2:5]
	s_barrier
	s_add_i32 s55, s55, 2
	s_add_u32 s8, s8, 0x100
	s_addc_u32 s9, s9, 0
	s_add_u32 s33, s33, 0x100
	s_addc_u32 s54, s54, 0
	s_cmp_gt_u32 s55, 29
	s_cbranch_scc0 .LBB0_1721
	s_and_b64 vcc, exec, s[20:21]
	s_cbranch_vccz .LBB0_1724
	s_barrier

; #define PG8_STAGE(bufoff, gbase, voff) do { _Pragma("unroll") for (int _i = 0; _i < 2; ++_i) \
;         __builtin_amdgcn_global_load_lds((const unsigned*)((const char*)(gbase) + (voff)[_i]), (PG8_LAS unsigned*)(lds + (bufoff) + ldsw + _i * 8192), 16, 0, 0); } while (0)
; #define PG8_LDA(dst, b, h) do { _Pragma("unroll") for (int m = 0; m < 4; ++m) _Pragma("unroll") for (int k = 0; k < 2; ++k) dst[m][k] = *(const PG8_LAS bf16x8*)(lds + PG8_SA(b, h) + aoff + m * 2048 + k * 1024); } while (0)
; #define PG8_LDB(dst, b, h) do { _Pragma("unroll") for (int n = 0; n < 2; ++n) _Pragma("unroll") for (int k = 0; k < 2; ++k) dst[n][k] = *(const PG8_LAS bf16x8*)(lds + PG8_SB(b, h) + boff + n * 2048 + k * 1024); } while (0)
; #define PG8_MMA(ai, bj, At, Bt) do { __builtin_amdgcn_s_setprio(1); _Pragma("unroll") for (int m = 0; m < 4; ++m) _Pragma("unroll") for (int n = 0; n < 2; ++n) _Pragma("unroll") for (int k = 0; k < 2; ++k) \
;         acc[ai][bj][m][n] = mma_<I8>(Bt[n][k], At[m][k], acc[ai][bj][m][n]); __builtin_amdgcn_s_setprio(0); } while (0)
; #define PG8_WAIT_V(n) asm volatile("s_waitcnt vmcnt(" #n ")" ::: "memory")
; #define PG8_WAIT_L(n) asm volatile("s_waitcnt lgkmcnt(" #n ")" ::: "memory")
; #define PG8_BAR __builtin_amdgcn_s_barrier()
; template <class Epi, class Sched, bool ALIGN_EPI = false, bool SP2 = false, bool I8 = false>
; __device__ __forceinline__ void gemm_phase(PG8_LAS unsigned char* lds, const Gemm g, const Sched& S, const Epi& E) {
;     ...
;             const bool last = (t == nt - 2);
;             const char* a1 = cA + (size_t)(t + 1) * kstep;
;             const char* a2 = last ? nA : cA + (size_t)(t + 2) * kstep; const char* b2 = last ? nB : cB + (size_t)(t + 2) * kstep;
;             const char* a3 = a2 + kstep; const char* b3 = b2 + kstep;
;             if (last && has_next) S.a_ready(nxt);
;             if constexpr (SP2) {
;             PG8_LDB(B0, 0, 0); PG8_LDB(B1, 0, 1); PG8_SCHED; PG8_LDA(At, 0, 0); PG8_STAGE(PG8_SA(1, 1), a1 + hstepA, voffA);
;             PG8_WAIT_V(8); PG8_WAIT_L(0); PG8_BAR; PG8_MMA(0, 0, At, B0); PG8_MMA(0, 1, At, B1); PG8_BAR; PG8_SCHED;
;             PG8_LDA(At, 0, 1); PG8_STAGE(PG8_SB(0, 0), b2, voffB); PG8_STAGE(PG8_SB(0, 1), b2 + hstepB, voffB); PG8_STAGE(PG8_SA(0, 0), a2, voffA);
;             PG8_WAIT_V(8); PG8_WAIT_L(0); PG8_BAR; PG8_MMA(1, 0, At, B0); PG8_MMA(1, 1, At, B1); PG8_BAR; PG8_SCHED;
.LBB0_2014:
	ds_read_b128 v[118:121], v163
	ds_read_b128 v[126:129], v163 offset:1024
	ds_read_b128 v[130:133], v163 offset:2048
	ds_read_b128 v[134:137], v163 offset:3072
	ds_read_b128 v[168:171], v167
	ds_read_b128 v[176:179], v167 offset:1024
	ds_read_b128 v[180:183], v167 offset:2048
	ds_read_b128 v[184:187], v167 offset:3072
	s_add_u32 s38, s36, 0xfff80080
	s_addc_u32 s39, s37, -1
	s_cmp_eq_u32 s65, 28
	s_cselect_b32 s41, s27, s39
	s_cselect_b32 s40, s61, s38
	s_cselect_b32 s39, s25, s64
	s_cselect_b32 s38, s62, s63
	s_add_i32 m0, s35, 0xc000
	ds_read_b128 v[188:191], v173
	ds_read_b128 v[192:195], v173 offset:1024
	ds_read_b128 v[196:199], v173 offset:2048
	ds_read_b128 v[200:203], v173 offset:3072
	ds_read_b128 v[204:207], v173 offset:4096
	ds_read_b128 v[208:211], v173 offset:5120
	ds_read_b128 v[212:215], v173 offset:6144
	ds_read_b128 v[216:219], v173 offset:7168
	global_load_lds_dwordx4 v154, s[36:37]
	s_add_i32 m0, s35, 0xe000
	s_nop 0
	global_load_lds_dwordx4 v156, s[36:37]
	s_waitcnt vmcnt(8)
	s_waitcnt lgkmcnt(0)
	s_barrier
	s_waitcnt lgkmcnt(0)
	v_mfma_i32_16x16x64_i8 v[142:145], v[118:121], v[188:191], v[142:145]
	v_mfma_i32_16x16x64_i8 v[138:141], v[130:133], v[188:191], v[138:141]
	v_mfma_i32_16x16x64_i8 v[110:113], v[118:121], v[196:199], v[110:113]
	v_mfma_i32_16x16x64_i8 v[106:109], v[130:133], v[196:199], v[106:109]
	v_mfma_i32_16x16x64_i8 v[94:97], v[118:121], v[204:207], v[94:97]
	v_mfma_i32_16x16x64_i8 v[90:93], v[130:133], v[204:207], v[90:93]
	v_mfma_i32_16x16x64_i8 v[78:81], v[118:121], v[212:215], v[78:81]
	v_mfma_i32_16x16x64_i8 v[74:77], v[130:133], v[212:215], v[74:77]
	v_mfma_i32_16x16x64_i8 v[142:145], v[126:129], v[192:195], v[142:145]
	v_mfma_i32_16x16x64_i8 v[138:141], v[134:137], v[192:195], v[138:141]
	v_mfma_i32_16x16x64_i8 v[110:113], v[126:129], v[200:203], v[110:113]
	v_mfma_i32_16x16x64_i8 v[106:109], v[134:137], v[200:203], v[106:109]
	v_mfma_i32_16x16x64_i8 v[94:97], v[126:129], v[208:211], v[94:97]
	v_mfma_i32_16x16x64_i8 v[90:93], v[134:137], v[208:211], v[90:93]
	v_mfma_i32_16x16x64_i8 v[78:81], v[126:129], v[216:219], v[78:81]
	v_mfma_i32_16x16x64_i8 v[74:77], v[134:137], v[216:219], v[74:77]
	v_mfma_i32_16x16x64_i8 v[122:125], v[168:171], v[188:191], v[122:125]
	v_mfma_i32_16x16x64_i8 v[114:117], v[180:183], v[188:191], v[114:117]
	v_mfma_i32_16x16x64_i8 v[102:105], v[168:171], v[196:199], v[102:105]
	v_mfma_i32_16x16x64_i8 v[98:101], v[180:183], v[196:199], v[98:101]
	v_mfma_i32_16x16x64_i8 v[86:89], v[168:171], v[204:207], v[86:89]
	v_mfma_i32_16x16x64_i8 v[82:85], v[180:183], v[204:207], v[82:85]
	v_mfma_i32_16x16x64_i8 v[70:73], v[168:171], v[212:215], v[70:73]
	v_mfma_i32_16x16x64_i8 v[66:69], v[180:183], v[212:215], v[66:69]
	v_mfma_i32_16x16x64_i8 v[122:125], v[176:179], v[192:195], v[122:125]
	v_mfma_i32_16x16x64_i8 v[114:117], v[184:187], v[192:195], v[114:117]
	v_mfma_i32_16x16x64_i8 v[102:105], v[176:179], v[200:203], v[102:105]
	v_mfma_i32_16x16x64_i8 v[98:101], v[184:187], v[200:203], v[98:101]
	v_mfma_i32_16x16x64_i8 v[86:89], v[176:179], v[208:211], v[86:89]
	v_mfma_i32_16x16x64_i8 v[82:85], v[184:187], v[208:211], v[82:85]
	v_mfma_i32_16x16x64_i8 v[70:73], v[176:179], v[216:219], v[70:73]
	v_mfma_i32_16x16x64_i8 v[66:69], v[184:187], v[216:219], v[66:69]
	s_barrier
	s_add_i32 s66, s54, s46
	s_mov_b64 s[98:99], s[38:39]
	s_mov_b32 m0, s66
	ds_read_b128 v[188:191], v173 offset:16384
	ds_read_b128 v[192:195], v173 offset:17408
	ds_read_b128 v[196:199], v173 offset:18432
	ds_read_b128 v[200:203], v173 offset:19456
	ds_read_b128 v[204:207], v173 offset:20480
	ds_read_b128 v[208:211], v173 offset:21504
	ds_read_b128 v[212:215], v173 offset:22528
	ds_read_b128 v[216:219], v173 offset:23552
	global_load_lds_dwordx4 v148, s[38:39]
	s_add_i32 m0, s66, 0x2000
	s_add_u32 s66, s38, 0x80000
	s_mov_b64 s[98:99], s[38:39]
	s_addc_u32 s67, s39, 0
	s_add_i32 s68, s55, s46
	global_load_lds_dwordx4 v152, s[38:39]
	s_mov_b32 m0, s68
	s_mov_b64 s[100:101], s[40:41]
	global_load_lds_dwordx4 v148, s[66:67]
	s_add_i32 m0, s68, 0x2000
	s_nop 0
	global_load_lds_dwordx4 v152, s[66:67]
	s_mov_b64 s[100:101], s[40:41]
	s_mov_b32 m0, s35
	s_nop 0
	global_load_lds_dwordx4 v146, s[40:41]
	s_mov_b32 m0, s47
	s_nop 0
	global_load_lds_dwordx4 v150, s[40:41]
	s_waitcnt vmcnt(8)
	s_waitcnt lgkmcnt(0)
	s_barrier
	s_waitcnt lgkmcnt(0)
	v_mfma_i32_16x16x64_i8 v[62:65], v[118:121], v[188:191], v[62:65]
	v_mfma_i32_16x16x64_i8 v[58:61], v[130:133], v[188:191], v[58:61]
	v_mfma_i32_16x16x64_i8 v[46:49], v[118:121], v[196:199], v[46:49]
	v_mfma_i32_16x16x64_i8 v[42:45], v[130:133], v[196:199], v[42:45]
	v_mfma_i32_16x16x64_i8 v[30:33], v[118:121], v[204:207], v[30:33]
	v_mfma_i32_16x16x64_i8 v[26:29], v[130:133], v[204:207], v[26:29]
	v_mfma_i32_16x16x64_i8 v[14:17], v[118:121], v[212:215], v[14:17]
	v_mfma_i32_16x16x64_i8 v[10:13], v[130:133], v[212:215], v[10:13]
	v_mfma_i32_16x16x64_i8 v[62:65], v[126:129], v[192:195], v[62:65]
	v_mfma_i32_16x16x64_i8 v[58:61], v[134:137], v[192:195], v[58:61]
	v_mfma_i32_16x16x64_i8 v[46:49], v[126:129], v[200:203], v[46:49]
	v_mfma_i32_16x16x64_i8 v[42:45], v[134:137], v[200:203], v[42:45]
	v_mfma_i32_16x16x64_i8 v[30:33], v[126:129], v[208:211], v[30:33]
	v_mfma_i32_16x16x64_i8 v[26:29], v[134:137], v[208:211], v[26:29]
	v_mfma_i32_16x16x64_i8 v[14:17], v[126:129], v[216:219], v[14:17]
	v_mfma_i32_16x16x64_i8 v[10:13], v[134:137], v[216:219], v[10:13]
	v_mfma_i32_16x16x64_i8 v[54:57], v[168:171], v[188:191], v[54:57]
	v_mfma_i32_16x16x64_i8 v[50:53], v[180:183], v[188:191], v[50:53]
	v_mfma_i32_16x16x64_i8 v[38:41], v[168:171], v[196:199], v[38:41]
	v_mfma_i32_16x16x64_i8 v[34:37], v[180:183], v[196:199], v[34:37]
	v_mfma_i32_16x16x64_i8 v[22:25], v[168:171], v[204:207], v[22:25]
	v_mfma_i32_16x16x64_i8 v[18:21], v[180:183], v[204:207], v[18:21]
	v_mfma_i32_16x16x64_i8 v[6:9], v[168:171], v[212:215], v[6:9]
	v_mfma_i32_16x16x64_i8 v[2:5], v[180:183], v[212:215], v[2:5]
	v_mfma_i32_16x16x64_i8 v[54:57], v[176:179], v[192:195], v[54:57]
	v_mfma_i32_16x16x64_i8 v[50:53], v[184:187], v[192:195], v[50:53]
	v_mfma_i32_16x16x64_i8 v[38:41], v[176:179], v[200:203], v[38:41]
	v_mfma_i32_16x16x64_i8 v[34:37], v[184:187], v[200:203], v[34:37]
	v_mfma_i32_16x16x64_i8 v[22:25], v[176:179], v[208:211], v[22:25]
	v_mfma_i32_16x16x64_i8 v[18:21], v[184:187], v[208:211], v[18:21]
	v_mfma_i32_16x16x64_i8 v[6:9], v[176:179], v[216:219], v[6:9]
	v_mfma_i32_16x16x64_i8 v[2:5], v[184:187], v[216:219], v[2:5]
	s_barrier
; #define PG8_STAGE(bufoff, gbase, voff) do { _Pragma("unroll") for (int _i = 0; _i < 2; ++_i) \
;         __builtin_amdgcn_global_load_lds((const unsigned*)((const char*)(gbase) + (voff)[_i]), (PG8_LAS unsigned*)(lds + (bufoff) + ldsw + _i * 8192), 16, 0, 0); } while (0)
; #define PG8_LDA(dst, b, h) do { _Pragma("unroll") for (int m = 0; m < 4; ++m) _Pragma("unroll") for (int k = 0; k < 2; ++k) dst[m][k] = *(const PG8_LAS bf16x8*)(lds + PG8_SA(b, h) + aoff + m * 2048 + k * 1024); } while (0)
; #define PG8_LDB(dst, b, h) do { _Pragma("unroll") for (int n = 0; n < 2; ++n) _Pragma("unroll") for (int k = 0; k < 2; ++k) dst[n][k] = *(const PG8_LAS bf16x8*)(lds + PG8_SB(b, h) + boff + n * 2048 + k * 1024); } while (0)
; #define PG8_MMA(ai, bj, At, Bt) do { __builtin_amdgcn_s_setprio(1); _Pragma("unroll") for (int m = 0; m < 4; ++m) _Pragma("unroll") for (int n = 0; n < 2; ++n) _Pragma("unroll") for (int k = 0; k < 2; ++k) \
;         acc[ai][bj][m][n] = mma_<I8>(Bt[n][k], At[m][k], acc[ai][bj][m][n]); __builtin_amdgcn_s_setprio(0); } while (0)
; #define PG8_WAIT_V(n) asm volatile("s_waitcnt vmcnt(" #n ")" ::: "memory")
; #define PG8_WAIT_L(n) asm volatile("s_waitcnt lgkmcnt(" #n ")" ::: "memory")
; #define PG8_BAR __builtin_amdgcn_s_barrier()
; #define PG8_SCHED __builtin_amdgcn_sched_barrier(0)
; template <class Epi, class Sched, bool ALIGN_EPI = false, bool SP2 = false, bool I8 = false>
; __device__ __forceinline__ void gemm_phase(PG8_LAS unsigned char* lds, const Gemm g, const Sched& S, const Epi& E) {
;     ...
;         for (int t = 0; t < nt; t += 2) {
;     ...
;             PG8_LDB(B0, 1, 0); PG8_LDB(B1, 1, 1); PG8_SCHED; PG8_LDA(At, 1, 0); PG8_STAGE(PG8_SA(0, 1), a2 + hstepA, voffA);
;             PG8_WAIT_V(8); PG8_WAIT_L(0); PG8_BAR; PG8_MMA(0, 0, At, B0); PG8_MMA(0, 1, At, B1); PG8_BAR; PG8_SCHED;
;             PG8_LDA(At, 1, 1); PG8_STAGE(PG8_SB(1, 0), b3, voffB); PG8_STAGE(PG8_SB(1, 1), b3 + hstepB, voffB); PG8_STAGE(PG8_SA(1, 0), a3, voffA);
;             PG8_WAIT_V(8); PG8_WAIT_L(0); PG8_BAR; PG8_MMA(1, 0, At, B0); PG8_MMA(1, 1, At, B1); PG8_BAR; PG8_SCHED;
	s_add_i32 s66, 0, 0x18000
	s_add_i32 s67, 0, 0x1c000
	ds_read_b128 v[118:121], v167 offset:16384
	ds_read_b128 v[126:129], v167 offset:17408
	ds_read_b128 v[130:133], v167 offset:18432
	ds_read_b128 v[134:137], v167 offset:19456
	ds_read_b128 v[168:171], v167 offset:32768
	ds_read_b128 v[176:179], v167 offset:33792
	ds_read_b128 v[180:183], v167 offset:34816
	ds_read_b128 v[184:187], v167 offset:35840
	s_add_u32 s40, s40, 0x80000
	s_addc_u32 s41, s41, 0
	s_mov_b32 m0, s48
	ds_read_b128 v[188:191], v173 offset:32768
	ds_read_b128 v[192:195], v173 offset:33792
	ds_read_b128 v[196:199], v173 offset:34816
	ds_read_b128 v[200:203], v173 offset:35840
	ds_read_b128 v[204:207], v173 offset:36864
	ds_read_b128 v[208:211], v173 offset:37888
	ds_read_b128 v[212:215], v173 offset:38912
	ds_read_b128 v[216:219], v173 offset:39936
	global_load_lds_dwordx4 v146, s[40:41]
	s_mov_b32 m0, s49
	s_nop 0
	global_load_lds_dwordx4 v150, s[40:41]
	s_waitcnt vmcnt(8)
	s_waitcnt lgkmcnt(0)
	s_barrier
	s_waitcnt lgkmcnt(0)
	v_mfma_i32_16x16x64_i8 v[142:145], v[118:121], v[188:191], v[142:145]
	v_mfma_i32_16x16x64_i8 v[138:141], v[130:133], v[188:191], v[138:141]
	v_mfma_i32_16x16x64_i8 v[110:113], v[118:121], v[196:199], v[110:113]
	v_mfma_i32_16x16x64_i8 v[106:109], v[130:133], v[196:199], v[106:109]
	v_mfma_i32_16x16x64_i8 v[94:97], v[118:121], v[204:207], v[94:97]
	v_mfma_i32_16x16x64_i8 v[90:93], v[130:133], v[204:207], v[90:93]
	v_mfma_i32_16x16x64_i8 v[78:81], v[118:121], v[212:215], v[78:81]
	v_mfma_i32_16x16x64_i8 v[74:77], v[130:133], v[212:215], v[74:77]
	v_mfma_i32_16x16x64_i8 v[142:145], v[126:129], v[192:195], v[142:145]
	v_mfma_i32_16x16x64_i8 v[138:141], v[134:137], v[192:195], v[138:141]
	v_mfma_i32_16x16x64_i8 v[110:113], v[126:129], v[200:203], v[110:113]
	v_mfma_i32_16x16x64_i8 v[106:109], v[134:137], v[200:203], v[106:109]
	v_mfma_i32_16x16x64_i8 v[94:97], v[126:129], v[208:211], v[94:97]
	v_mfma_i32_16x16x64_i8 v[90:93], v[134:137], v[208:211], v[90:93]
	v_mfma_i32_16x16x64_i8 v[78:81], v[126:129], v[216:219], v[78:81]
	v_mfma_i32_16x16x64_i8 v[74:77], v[134:137], v[216:219], v[74:77]
	v_mfma_i32_16x16x64_i8 v[122:125], v[168:171], v[188:191], v[122:125]
	v_mfma_i32_16x16x64_i8 v[114:117], v[180:183], v[188:191], v[114:117]
	v_mfma_i32_16x16x64_i8 v[102:105], v[168:171], v[196:199], v[102:105]
	v_mfma_i32_16x16x64_i8 v[98:101], v[180:183], v[196:199], v[98:101]
	v_mfma_i32_16x16x64_i8 v[86:89], v[168:171], v[204:207], v[86:89]
	v_mfma_i32_16x16x64_i8 v[82:85], v[180:183], v[204:207], v[82:85]
	v_mfma_i32_16x16x64_i8 v[70:73], v[168:171], v[212:215], v[70:73]
	v_mfma_i32_16x16x64_i8 v[66:69], v[180:183], v[212:215], v[66:69]
	v_mfma_i32_16x16x64_i8 v[122:125], v[176:179], v[192:195], v[122:125]
	v_mfma_i32_16x16x64_i8 v[114:117], v[184:187], v[192:195], v[114:117]
	v_mfma_i32_16x16x64_i8 v[102:105], v[176:179], v[200:203], v[102:105]
	v_mfma_i32_16x16x64_i8 v[98:101], v[184:187], v[200:203], v[98:101]
	v_mfma_i32_16x16x64_i8 v[86:89], v[176:179], v[208:211], v[86:89]
	v_mfma_i32_16x16x64_i8 v[82:85], v[184:187], v[208:211], v[82:85]
	v_mfma_i32_16x16x64_i8 v[70:73], v[176:179], v[216:219], v[70:73]
	v_mfma_i32_16x16x64_i8 v[66:69], v[184:187], v[216:219], v[66:69]
	s_barrier
	s_add_i32 s40, s66, s46
	s_add_i32 m0, s40, 0xffffff80
	ds_read_b128 v[188:191], v173 offset:49152
	ds_read_b128 v[192:195], v173 offset:50176
	ds_read_b128 v[196:199], v173 offset:51200
	ds_read_b128 v[200:203], v173 offset:52224
	ds_read_b128 v[204:207], v173 offset:53248
	ds_read_b128 v[208:211], v173 offset:54272
	ds_read_b128 v[212:215], v173 offset:55296
	ds_read_b128 v[216:219], v173 offset:56320
	global_load_lds_dwordx4 v148, s[98:99] offset:128
	s_add_i32 m0, s40, 0x1f80
	s_add_u32 s38, s38, 0x80080
	s_addc_u32 s39, s39, 0
	s_add_i32 s40, s67, s46
	global_load_lds_dwordx4 v152, s[98:99] offset:128
	s_mov_b32 m0, s40
	s_nop 0
	global_load_lds_dwordx4 v148, s[38:39]
	s_add_i32 m0, s40, 0x2000
	s_nop 0
	global_load_lds_dwordx4 v152, s[38:39]
	s_add_i32 m0, s51, 0xffffff80
	s_nop 0
	global_load_lds_dwordx4 v146, s[100:101] offset:128
	s_add_i32 m0, s52, 0xffffff80
	s_nop 0
	global_load_lds_dwordx4 v150, s[100:101] offset:128
	s_waitcnt vmcnt(8)
	s_waitcnt lgkmcnt(0)
	s_barrier
	s_waitcnt lgkmcnt(0)
	v_mfma_i32_16x16x64_i8 v[62:65], v[118:121], v[188:191], v[62:65]
	v_mfma_i32_16x16x64_i8 v[58:61], v[130:133], v[188:191], v[58:61]
	v_mfma_i32_16x16x64_i8 v[46:49], v[118:121], v[196:199], v[46:49]
	v_mfma_i32_16x16x64_i8 v[42:45], v[130:133], v[196:199], v[42:45]
	v_mfma_i32_16x16x64_i8 v[30:33], v[118:121], v[204:207], v[30:33]
	v_mfma_i32_16x16x64_i8 v[26:29], v[130:133], v[204:207], v[26:29]
	v_mfma_i32_16x16x64_i8 v[14:17], v[118:121], v[212:215], v[14:17]
	v_mfma_i32_16x16x64_i8 v[10:13], v[130:133], v[212:215], v[10:13]
	v_mfma_i32_16x16x64_i8 v[62:65], v[126:129], v[192:195], v[62:65]
	v_mfma_i32_16x16x64_i8 v[58:61], v[134:137], v[192:195], v[58:61]
	v_mfma_i32_16x16x64_i8 v[46:49], v[126:129], v[200:203], v[46:49]
	v_mfma_i32_16x16x64_i8 v[42:45], v[134:137], v[200:203], v[42:45]
	v_mfma_i32_16x16x64_i8 v[30:33], v[126:129], v[208:211], v[30:33]
	v_mfma_i32_16x16x64_i8 v[26:29], v[134:137], v[208:211], v[26:29]
	v_mfma_i32_16x16x64_i8 v[14:17], v[126:129], v[216:219], v[14:17]
	v_mfma_i32_16x16x64_i8 v[10:13], v[134:137], v[216:219], v[10:13]
	v_mfma_i32_16x16x64_i8 v[54:57], v[168:171], v[188:191], v[54:57]
	v_mfma_i32_16x16x64_i8 v[50:53], v[180:183], v[188:191], v[50:53]
	v_mfma_i32_16x16x64_i8 v[38:41], v[168:171], v[196:199], v[38:41]
	v_mfma_i32_16x16x64_i8 v[34:37], v[180:183], v[196:199], v[34:37]
	v_mfma_i32_16x16x64_i8 v[22:25], v[168:171], v[204:207], v[22:25]
	v_mfma_i32_16x16x64_i8 v[18:21], v[180:183], v[204:207], v[18:21]
	v_mfma_i32_16x16x64_i8 v[6:9], v[168:171], v[212:215], v[6:9]
	v_mfma_i32_16x16x64_i8 v[2:5], v[180:183], v[212:215], v[2:5]
	v_mfma_i32_16x16x64_i8 v[54:57], v[176:179], v[192:195], v[54:57]
	v_mfma_i32_16x16x64_i8 v[50:53], v[184:187], v[192:195], v[50:53]
	v_mfma_i32_16x16x64_i8 v[38:41], v[176:179], v[200:203], v[38:41]
	v_mfma_i32_16x16x64_i8 v[34:37], v[184:187], v[200:203], v[34:37]
	v_mfma_i32_16x16x64_i8 v[22:25], v[176:179], v[208:211], v[22:25]
	v_mfma_i32_16x16x64_i8 v[18:21], v[184:187], v[208:211], v[18:21]
	v_mfma_i32_16x16x64_i8 v[6:9], v[176:179], v[216:219], v[6:9]
	v_mfma_i32_16x16x64_i8 v[2:5], v[184:187], v[216:219], v[2:5]
	s_barrier
	s_add_i32 s65, s65, 2
	s_add_u32 s36, s36, 0x100
	s_addc_u32 s37, s37, 0
	s_add_u32 s63, s63, 0x100
	s_addc_u32 s64, s64, 0
	s_cmp_gt_u32 s65, 29
	s_cbranch_scc0 .LBB0_2014
	s_and_b64 vcc, exec, s[14:15]
	s_cbranch_vccz .LBB0_2017
	s_barrier

; #define PG8_STAGE(bufoff, gbase, voff) do { _Pragma("unroll") for (int _i = 0; _i < 2; ++_i) \
;         __builtin_amdgcn_global_load_lds((const unsigned*)((const char*)(gbase) + (voff)[_i]), (PG8_LAS unsigned*)(lds + (bufoff) + ldsw + _i * 8192), 16, 0, 0); } while (0)
; #define PG8_LDA(dst, b, h) do { _Pragma("unroll") for (int m = 0; m < 4; ++m) _Pragma("unroll") for (int k = 0; k < 2; ++k) dst[m][k] = *(const PG8_LAS bf16x8*)(lds + PG8_SA(b, h) + aoff + m * 2048 + k * 1024); } while (0)
; #define PG8_LDB(dst, b, h) do { _Pragma("unroll") for (int n = 0; n < 2; ++n) _Pragma("unroll") for (int k = 0; k < 2; ++k) dst[n][k] = *(const PG8_LAS bf16x8*)(lds + PG8_SB(b, h) + boff + n * 2048 + k * 1024); } while (0)
; #define PG8_MMA(ai, bj, At, Bt) do { __builtin_amdgcn_s_setprio(1); _Pragma("unroll") for (int m = 0; m < 4; ++m) _Pragma("unroll") for (int n = 0; n < 2; ++n) _Pragma("unroll") for (int k = 0; k < 2; ++k) \
;         acc[ai][bj][m][n] = mma_<I8>(Bt[n][k], At[m][k], acc[ai][bj][m][n]); __builtin_amdgcn_s_setprio(0); } while (0)
; #define PG8_WAIT_V(n) asm volatile("s_waitcnt vmcnt(" #n ")" ::: "memory")
; #define PG8_WAIT_L(n) asm volatile("s_waitcnt lgkmcnt(" #n ")" ::: "memory")
; #define PG8_BAR __builtin_amdgcn_s_barrier()
; template <class Epi, class Sched, bool ALIGN_EPI = false, bool SP2 = false, bool I8 = false>
; __device__ __forceinline__ void gemm_phase(PG8_LAS unsigned char* lds, const Gemm g, const Sched& S, const Epi& E) {
;     ...
;             const bool last = (t == nt - 2);
;             const char* a1 = cA + (size_t)(t + 1) * kstep;
;             const char* a2 = last ? nA : cA + (size_t)(t + 2) * kstep; const char* b2 = last ? nB : cB + (size_t)(t + 2) * kstep;
;             const char* a3 = a2 + kstep; const char* b3 = b2 + kstep;
;             if (last && has_next) S.a_ready(nxt);
;             if constexpr (SP2) {
;             PG8_LDB(B0, 0, 0); PG8_LDB(B1, 0, 1); PG8_SCHED; PG8_LDA(At, 0, 0); PG8_STAGE(PG8_SA(1, 1), a1 + hstepA, voffA);
;             PG8_WAIT_V(8); PG8_WAIT_L(0); PG8_BAR; PG8_MMA(0, 0, At, B0); PG8_MMA(0, 1, At, B1); PG8_BAR; PG8_SCHED;
;             PG8_LDA(At, 0, 1); PG8_STAGE(PG8_SB(0, 0), b2, voffB); PG8_STAGE(PG8_SB(0, 1), b2 + hstepB, voffB); PG8_STAGE(PG8_SA(0, 0), a2, voffA);
;             PG8_WAIT_V(8); PG8_WAIT_L(0); PG8_BAR; PG8_MMA(1, 0, At, B0); PG8_MMA(1, 1, At, B1); PG8_BAR; PG8_SCHED;
.LBB0_2092:
	ds_read_b128 v[130:133], v192
	ds_read_b128 v[134:137], v192 offset:1024
	ds_read_b128 v[138:141], v192 offset:2048
	ds_read_b128 v[142:145], v192 offset:3072
	ds_read_b128 v[146:149], v193
	ds_read_b128 v[150:153], v193 offset:1024
	ds_read_b128 v[154:157], v193 offset:2048
	ds_read_b128 v[158:161], v193 offset:3072
	s_add_u32 s28, s8, 0xffc00080
	s_addc_u32 s29, s9, -1
	s_cmpk_eq_i32 s51, 0xfc
	s_cselect_b32 s31, s3, s29
	s_cselect_b32 s30, s7, s28
	s_cselect_b32 s29, s21, s50
	s_cselect_b32 s28, s23, s49
	s_add_i32 m0, s38, 0xc000
	ds_read_b128 v[162:165], v194
	ds_read_b128 v[166:169], v194 offset:1024
	ds_read_b128 v[182:185], v194 offset:2048
	ds_read_b128 v[186:189], v194 offset:3072
	ds_read_b128 v[196:199], v194 offset:4096
	ds_read_b128 v[200:203], v194 offset:5120
	ds_read_b128 v[204:207], v194 offset:6144
	ds_read_b128 v[208:211], v194 offset:7168
	global_load_lds_dwordx4 v174, s[8:9]
	s_add_i32 m0, s38, 0xe000
	s_nop 0
	global_load_lds_dwordx4 v176, s[8:9]
	s_waitcnt vmcnt(8)
	s_waitcnt lgkmcnt(0)
	s_barrier
	s_waitcnt lgkmcnt(0)
	v_mfma_f32_16x16x32_bf16 v[126:129], v[130:133], v[162:165], v[126:129]
	v_mfma_f32_16x16x32_bf16 v[122:125], v[138:141], v[162:165], v[122:125]
	v_mfma_f32_16x16x32_bf16 v[110:113], v[130:133], v[182:185], v[110:113]
	v_mfma_f32_16x16x32_bf16 v[106:109], v[138:141], v[182:185], v[106:109]
	v_mfma_f32_16x16x32_bf16 v[94:97], v[130:133], v[196:199], v[94:97]
	v_mfma_f32_16x16x32_bf16 v[90:93], v[138:141], v[196:199], v[90:93]
	v_mfma_f32_16x16x32_bf16 v[78:81], v[130:133], v[204:207], v[78:81]
	v_mfma_f32_16x16x32_bf16 v[74:77], v[138:141], v[204:207], v[74:77]
	v_mfma_f32_16x16x32_bf16 v[126:129], v[134:137], v[166:169], v[126:129]
	v_mfma_f32_16x16x32_bf16 v[122:125], v[142:145], v[166:169], v[122:125]
	v_mfma_f32_16x16x32_bf16 v[110:113], v[134:137], v[186:189], v[110:113]
	v_mfma_f32_16x16x32_bf16 v[106:109], v[142:145], v[186:189], v[106:109]
	v_mfma_f32_16x16x32_bf16 v[94:97], v[134:137], v[200:203], v[94:97]
	v_mfma_f32_16x16x32_bf16 v[90:93], v[142:145], v[200:203], v[90:93]
	v_mfma_f32_16x16x32_bf16 v[78:81], v[134:137], v[208:211], v[78:81]
	v_mfma_f32_16x16x32_bf16 v[74:77], v[142:145], v[208:211], v[74:77]
	v_mfma_f32_16x16x32_bf16 v[118:121], v[146:149], v[162:165], v[118:121]
	v_mfma_f32_16x16x32_bf16 v[114:117], v[154:157], v[162:165], v[114:117]
	v_mfma_f32_16x16x32_bf16 v[102:105], v[146:149], v[182:185], v[102:105]
	v_mfma_f32_16x16x32_bf16 v[98:101], v[154:157], v[182:185], v[98:101]
	v_mfma_f32_16x16x32_bf16 v[86:89], v[146:149], v[196:199], v[86:89]
	v_mfma_f32_16x16x32_bf16 v[82:85], v[154:157], v[196:199], v[82:85]
	v_mfma_f32_16x16x32_bf16 v[70:73], v[146:149], v[204:207], v[70:73]
	v_mfma_f32_16x16x32_bf16 v[66:69], v[154:157], v[204:207], v[66:69]
	v_mfma_f32_16x16x32_bf16 v[118:121], v[150:153], v[166:169], v[118:121]
	v_mfma_f32_16x16x32_bf16 v[114:117], v[158:161], v[166:169], v[114:117]
	v_mfma_f32_16x16x32_bf16 v[102:105], v[150:153], v[186:189], v[102:105]
	v_mfma_f32_16x16x32_bf16 v[98:101], v[158:161], v[186:189], v[98:101]
	v_mfma_f32_16x16x32_bf16 v[86:89], v[150:153], v[200:203], v[86:89]
	v_mfma_f32_16x16x32_bf16 v[82:85], v[158:161], v[200:203], v[82:85]
	v_mfma_f32_16x16x32_bf16 v[70:73], v[150:153], v[208:211], v[70:73]
	v_mfma_f32_16x16x32_bf16 v[66:69], v[158:161], v[208:211], v[66:69]
	s_barrier
	s_add_i32 s52, s47, s33
	s_mov_b64 s[98:99], s[28:29]
	s_mov_b32 m0, s52
	ds_read_b128 v[162:165], v194 offset:16384
	ds_read_b128 v[166:169], v194 offset:17408
	ds_read_b128 v[182:185], v194 offset:18432
	ds_read_b128 v[186:189], v194 offset:19456
	ds_read_b128 v[196:199], v194 offset:20480
	ds_read_b128 v[200:203], v194 offset:21504
	ds_read_b128 v[204:207], v194 offset:22528
	ds_read_b128 v[208:211], v194 offset:23552
	global_load_lds_dwordx4 v170, s[28:29]
	s_add_i32 m0, s52, 0x2000
	s_add_u32 s52, s28, 0x400000
	s_mov_b64 s[98:99], s[28:29]
	s_addc_u32 s53, s29, 0
	s_add_i32 s54, s48, s33
	global_load_lds_dwordx4 v172, s[28:29]
	s_mov_b32 m0, s54
	s_mov_b64 s[100:101], s[30:31]
	global_load_lds_dwordx4 v170, s[52:53]
	s_add_i32 m0, s54, 0x2000
	s_nop 0
	global_load_lds_dwordx4 v172, s[52:53]
	s_mov_b64 s[100:101], s[30:31]
	s_mov_b32 m0, s38
	s_nop 0
	global_load_lds_dwordx4 v170, s[30:31]
	s_mov_b32 m0, s39
	s_nop 0
	global_load_lds_dwordx4 v172, s[30:31]
	s_waitcnt vmcnt(8)
	s_waitcnt lgkmcnt(0)
	s_barrier
	s_waitcnt lgkmcnt(0)
	v_mfma_f32_16x16x32_bf16 v[62:65], v[130:133], v[162:165], v[62:65]
	v_mfma_f32_16x16x32_bf16 v[58:61], v[138:141], v[162:165], v[58:61]
	v_mfma_f32_16x16x32_bf16 v[46:49], v[130:133], v[182:185], v[46:49]
	v_mfma_f32_16x16x32_bf16 v[42:45], v[138:141], v[182:185], v[42:45]
	v_mfma_f32_16x16x32_bf16 v[30:33], v[130:133], v[196:199], v[30:33]
	v_mfma_f32_16x16x32_bf16 v[26:29], v[138:141], v[196:199], v[26:29]
	v_mfma_f32_16x16x32_bf16 v[22:25], v[130:133], v[204:207], v[22:25]
	v_mfma_f32_16x16x32_bf16 v[10:13], v[138:141], v[204:207], v[10:13]
	v_mfma_f32_16x16x32_bf16 v[62:65], v[134:137], v[166:169], v[62:65]
	v_mfma_f32_16x16x32_bf16 v[58:61], v[142:145], v[166:169], v[58:61]
	v_mfma_f32_16x16x32_bf16 v[46:49], v[134:137], v[186:189], v[46:49]
	v_mfma_f32_16x16x32_bf16 v[42:45], v[142:145], v[186:189], v[42:45]
	v_mfma_f32_16x16x32_bf16 v[30:33], v[134:137], v[200:203], v[30:33]
	v_mfma_f32_16x16x32_bf16 v[26:29], v[142:145], v[200:203], v[26:29]
	v_mfma_f32_16x16x32_bf16 v[22:25], v[134:137], v[208:211], v[22:25]
	v_mfma_f32_16x16x32_bf16 v[10:13], v[142:145], v[208:211], v[10:13]
	v_mfma_f32_16x16x32_bf16 v[54:57], v[146:149], v[162:165], v[54:57]
	v_mfma_f32_16x16x32_bf16 v[50:53], v[154:157], v[162:165], v[50:53]
	v_mfma_f32_16x16x32_bf16 v[38:41], v[146:149], v[182:185], v[38:41]
	v_mfma_f32_16x16x32_bf16 v[34:37], v[154:157], v[182:185], v[34:37]
	v_mfma_f32_16x16x32_bf16 v[18:21], v[146:149], v[196:199], v[18:21]
	v_mfma_f32_16x16x32_bf16 v[14:17], v[154:157], v[196:199], v[14:17]
	v_mfma_f32_16x16x32_bf16 v[6:9], v[146:149], v[204:207], v[6:9]
	v_mfma_f32_16x16x32_bf16 v[2:5], v[154:157], v[204:207], v[2:5]
	v_mfma_f32_16x16x32_bf16 v[54:57], v[150:153], v[166:169], v[54:57]
	v_mfma_f32_16x16x32_bf16 v[50:53], v[158:161], v[166:169], v[50:53]
	v_mfma_f32_16x16x32_bf16 v[38:41], v[150:153], v[186:189], v[38:41]
	v_mfma_f32_16x16x32_bf16 v[34:37], v[158:161], v[186:189], v[34:37]
	v_mfma_f32_16x16x32_bf16 v[18:21], v[150:153], v[200:203], v[18:21]
	v_mfma_f32_16x16x32_bf16 v[14:17], v[158:161], v[200:203], v[14:17]
	v_mfma_f32_16x16x32_bf16 v[6:9], v[150:153], v[208:211], v[6:9]
	v_mfma_f32_16x16x32_bf16 v[2:5], v[158:161], v[208:211], v[2:5]
	s_barrier
; #define PG8_STAGE(bufoff, gbase, voff) do { _Pragma("unroll") for (int _i = 0; _i < 2; ++_i) \
;         __builtin_amdgcn_global_load_lds((const unsigned*)((const char*)(gbase) + (voff)[_i]), (PG8_LAS unsigned*)(lds + (bufoff) + ldsw + _i * 8192), 16, 0, 0); } while (0)
; #define PG8_LDA(dst, b, h) do { _Pragma("unroll") for (int m = 0; m < 4; ++m) _Pragma("unroll") for (int k = 0; k < 2; ++k) dst[m][k] = *(const PG8_LAS bf16x8*)(lds + PG8_SA(b, h) + aoff + m * 2048 + k * 1024); } while (0)
; #define PG8_LDB(dst, b, h) do { _Pragma("unroll") for (int n = 0; n < 2; ++n) _Pragma("unroll") for (int k = 0; k < 2; ++k) dst[n][k] = *(const PG8_LAS bf16x8*)(lds + PG8_SB(b, h) + boff + n * 2048 + k * 1024); } while (0)
; #define PG8_MMA(ai, bj, At, Bt) do { __builtin_amdgcn_s_setprio(1); _Pragma("unroll") for (int m = 0; m < 4; ++m) _Pragma("unroll") for (int n = 0; n < 2; ++n) _Pragma("unroll") for (int k = 0; k < 2; ++k) \
;         acc[ai][bj][m][n] = mma_<I8>(Bt[n][k], At[m][k], acc[ai][bj][m][n]); __builtin_amdgcn_s_setprio(0); } while (0)
; #define PG8_WAIT_V(n) asm volatile("s_waitcnt vmcnt(" #n ")" ::: "memory")
; #define PG8_WAIT_L(n) asm volatile("s_waitcnt lgkmcnt(" #n ")" ::: "memory")
; #define PG8_BAR __builtin_amdgcn_s_barrier()
; #define PG8_SCHED __builtin_amdgcn_sched_barrier(0)
; template <class Epi, class Sched, bool ALIGN_EPI = false, bool SP2 = false, bool I8 = false>
; __device__ __forceinline__ void gemm_phase(PG8_LAS unsigned char* lds, const Gemm g, const Sched& S, const Epi& E) {
;     ...
;         for (int t = 0; t < nt; t += 2) {
;     ...
;             PG8_LDB(B0, 1, 0); PG8_LDB(B1, 1, 1); PG8_SCHED; PG8_LDA(At, 1, 0); PG8_STAGE(PG8_SA(0, 1), a2 + hstepA, voffA);
;             PG8_WAIT_V(8); PG8_WAIT_L(0); PG8_BAR; PG8_MMA(0, 0, At, B0); PG8_MMA(0, 1, At, B1); PG8_BAR; PG8_SCHED;
;             PG8_LDA(At, 1, 1); PG8_STAGE(PG8_SB(1, 0), b3, voffB); PG8_STAGE(PG8_SB(1, 1), b3 + hstepB, voffB); PG8_STAGE(PG8_SA(1, 0), a3, voffA);
;             PG8_WAIT_V(8); PG8_WAIT_L(0); PG8_BAR; PG8_MMA(1, 0, At, B0); PG8_MMA(1, 1, At, B1); PG8_BAR; PG8_SCHED;
	s_add_i32 s52, 0, 0x18000
	s_add_i32 s53, 0, 0x1c000
	ds_read_b128 v[130:133], v193 offset:16384
	ds_read_b128 v[134:137], v193 offset:17408
	ds_read_b128 v[138:141], v193 offset:18432
	ds_read_b128 v[142:145], v193 offset:19456
	ds_read_b128 v[146:149], v193 offset:32768
	ds_read_b128 v[150:153], v193 offset:33792
	ds_read_b128 v[154:157], v193 offset:34816
	ds_read_b128 v[158:161], v193 offset:35840
	s_add_u32 s30, s30, 0x400000
	s_addc_u32 s31, s31, 0
	s_mov_b32 m0, s40
	ds_read_b128 v[162:165], v194 offset:32768
	ds_read_b128 v[166:169], v194 offset:33792
	ds_read_b128 v[182:185], v194 offset:34816
	ds_read_b128 v[186:189], v194 offset:35840
	ds_read_b128 v[196:199], v194 offset:36864
	ds_read_b128 v[200:203], v194 offset:37888
	ds_read_b128 v[204:207], v194 offset:38912
	ds_read_b128 v[208:211], v194 offset:39936
	global_load_lds_dwordx4 v170, s[30:31]
	s_mov_b32 m0, s41
	s_nop 0
	global_load_lds_dwordx4 v172, s[30:31]
	s_waitcnt vmcnt(8)
	s_waitcnt lgkmcnt(0)
	s_barrier
	s_waitcnt lgkmcnt(0)
	v_mfma_f32_16x16x32_bf16 v[126:129], v[130:133], v[162:165], v[126:129]
	v_mfma_f32_16x16x32_bf16 v[122:125], v[138:141], v[162:165], v[122:125]
	v_mfma_f32_16x16x32_bf16 v[110:113], v[130:133], v[182:185], v[110:113]
	v_mfma_f32_16x16x32_bf16 v[106:109], v[138:141], v[182:185], v[106:109]
	v_mfma_f32_16x16x32_bf16 v[94:97], v[130:133], v[196:199], v[94:97]
	v_mfma_f32_16x16x32_bf16 v[90:93], v[138:141], v[196:199], v[90:93]
	v_mfma_f32_16x16x32_bf16 v[78:81], v[130:133], v[204:207], v[78:81]
	v_mfma_f32_16x16x32_bf16 v[74:77], v[138:141], v[204:207], v[74:77]
	v_mfma_f32_16x16x32_bf16 v[126:129], v[134:137], v[166:169], v[126:129]
	v_mfma_f32_16x16x32_bf16 v[122:125], v[142:145], v[166:169], v[122:125]
	v_mfma_f32_16x16x32_bf16 v[110:113], v[134:137], v[186:189], v[110:113]
	v_mfma_f32_16x16x32_bf16 v[106:109], v[142:145], v[186:189], v[106:109]
	v_mfma_f32_16x16x32_bf16 v[94:97], v[134:137], v[200:203], v[94:97]
	v_mfma_f32_16x16x32_bf16 v[90:93], v[142:145], v[200:203], v[90:93]
	v_mfma_f32_16x16x32_bf16 v[78:81], v[134:137], v[208:211], v[78:81]
	v_mfma_f32_16x16x32_bf16 v[74:77], v[142:145], v[208:211], v[74:77]
	v_mfma_f32_16x16x32_bf16 v[118:121], v[146:149], v[162:165], v[118:121]
	v_mfma_f32_16x16x32_bf16 v[114:117], v[154:157], v[162:165], v[114:117]
	v_mfma_f32_16x16x32_bf16 v[102:105], v[146:149], v[182:185], v[102:105]
	v_mfma_f32_16x16x32_bf16 v[98:101], v[154:157], v[182:185], v[98:101]
	v_mfma_f32_16x16x32_bf16 v[86:89], v[146:149], v[196:199], v[86:89]
	v_mfma_f32_16x16x32_bf16 v[82:85], v[154:157], v[196:199], v[82:85]
	v_mfma_f32_16x16x32_bf16 v[70:73], v[146:149], v[204:207], v[70:73]
	v_mfma_f32_16x16x32_bf16 v[66:69], v[154:157], v[204:207], v[66:69]
	v_mfma_f32_16x16x32_bf16 v[118:121], v[150:153], v[166:169], v[118:121]
	v_mfma_f32_16x16x32_bf16 v[114:117], v[158:161], v[166:169], v[114:117]
	v_mfma_f32_16x16x32_bf16 v[102:105], v[150:153], v[186:189], v[102:105]
	v_mfma_f32_16x16x32_bf16 v[98:101], v[158:161], v[186:189], v[98:101]
	v_mfma_f32_16x16x32_bf16 v[86:89], v[150:153], v[200:203], v[86:89]
	v_mfma_f32_16x16x32_bf16 v[82:85], v[158:161], v[200:203], v[82:85]
	v_mfma_f32_16x16x32_bf16 v[70:73], v[150:153], v[208:211], v[70:73]
	v_mfma_f32_16x16x32_bf16 v[66:69], v[158:161], v[208:211], v[66:69]
	s_barrier
	s_add_i32 s30, s52, s33
	s_add_i32 m0, s30, 0xffffff80
	ds_read_b128 v[162:165], v194 offset:49152
	ds_read_b128 v[166:169], v194 offset:50176
	ds_read_b128 v[182:185], v194 offset:51200
	ds_read_b128 v[186:189], v194 offset:52224
	ds_read_b128 v[196:199], v194 offset:53248
	ds_read_b128 v[200:203], v194 offset:54272
	ds_read_b128 v[204:207], v194 offset:55296
	ds_read_b128 v[208:211], v194 offset:56320
	global_load_lds_dwordx4 v170, s[98:99] offset:128
	s_add_i32 m0, s30, 0x1f80
	s_add_u32 s28, s28, 0x400080
	s_addc_u32 s29, s29, 0
	s_add_i32 s30, s53, s33
	global_load_lds_dwordx4 v172, s[98:99] offset:128
	s_mov_b32 m0, s30
	s_nop 0
	global_load_lds_dwordx4 v170, s[28:29]
	s_add_i32 m0, s30, 0x2000
	s_nop 0
	global_load_lds_dwordx4 v172, s[28:29]
	s_add_i32 m0, s43, 0xffffff80
	s_nop 0
	global_load_lds_dwordx4 v170, s[100:101] offset:128
	s_add_i32 m0, s44, 0xffffff80
	s_nop 0
	global_load_lds_dwordx4 v172, s[100:101] offset:128
	s_waitcnt vmcnt(8)
	s_waitcnt lgkmcnt(0)
	s_barrier
	s_waitcnt lgkmcnt(0)
	v_mfma_f32_16x16x32_bf16 v[62:65], v[130:133], v[162:165], v[62:65]
	v_mfma_f32_16x16x32_bf16 v[58:61], v[138:141], v[162:165], v[58:61]
	v_mfma_f32_16x16x32_bf16 v[46:49], v[130:133], v[182:185], v[46:49]
	v_mfma_f32_16x16x32_bf16 v[42:45], v[138:141], v[182:185], v[42:45]
	v_mfma_f32_16x16x32_bf16 v[30:33], v[130:133], v[196:199], v[30:33]
	v_mfma_f32_16x16x32_bf16 v[26:29], v[138:141], v[196:199], v[26:29]
	v_mfma_f32_16x16x32_bf16 v[22:25], v[130:133], v[204:207], v[22:25]
	v_mfma_f32_16x16x32_bf16 v[10:13], v[138:141], v[204:207], v[10:13]
	v_mfma_f32_16x16x32_bf16 v[62:65], v[134:137], v[166:169], v[62:65]
	v_mfma_f32_16x16x32_bf16 v[58:61], v[142:145], v[166:169], v[58:61]
	v_mfma_f32_16x16x32_bf16 v[46:49], v[134:137], v[186:189], v[46:49]
	v_mfma_f32_16x16x32_bf16 v[42:45], v[142:145], v[186:189], v[42:45]
	v_mfma_f32_16x16x32_bf16 v[30:33], v[134:137], v[200:203], v[30:33]
	v_mfma_f32_16x16x32_bf16 v[26:29], v[142:145], v[200:203], v[26:29]
	v_mfma_f32_16x16x32_bf16 v[22:25], v[134:137], v[208:211], v[22:25]
	v_mfma_f32_16x16x32_bf16 v[10:13], v[142:145], v[208:211], v[10:13]
	v_mfma_f32_16x16x32_bf16 v[54:57], v[146:149], v[162:165], v[54:57]
	v_mfma_f32_16x16x32_bf16 v[50:53], v[154:157], v[162:165], v[50:53]
	v_mfma_f32_16x16x32_bf16 v[38:41], v[146:149], v[182:185], v[38:41]
	v_mfma_f32_16x16x32_bf16 v[34:37], v[154:157], v[182:185], v[34:37]
	v_mfma_f32_16x16x32_bf16 v[18:21], v[146:149], v[196:199], v[18:21]
	v_mfma_f32_16x16x32_bf16 v[14:17], v[154:157], v[196:199], v[14:17]
	v_mfma_f32_16x16x32_bf16 v[6:9], v[146:149], v[204:207], v[6:9]
	v_mfma_f32_16x16x32_bf16 v[2:5], v[154:157], v[204:207], v[2:5]
	v_mfma_f32_16x16x32_bf16 v[54:57], v[150:153], v[166:169], v[54:57]
	v_mfma_f32_16x16x32_bf16 v[50:53], v[158:161], v[166:169], v[50:53]
	v_mfma_f32_16x16x32_bf16 v[38:41], v[150:153], v[186:189], v[38:41]
	v_mfma_f32_16x16x32_bf16 v[34:37], v[158:161], v[186:189], v[34:37]
	v_mfma_f32_16x16x32_bf16 v[18:21], v[150:153], v[200:203], v[18:21]
	v_mfma_f32_16x16x32_bf16 v[14:17], v[158:161], v[200:203], v[14:17]
	v_mfma_f32_16x16x32_bf16 v[6:9], v[150:153], v[208:211], v[6:9]
	v_mfma_f32_16x16x32_bf16 v[2:5], v[158:161], v[208:211], v[2:5]
	s_barrier
	s_add_i32 s51, s51, 2
	s_add_u32 s8, s8, 0x100
	s_addc_u32 s9, s9, 0
	s_add_u32 s49, s49, 0x100
	s_addc_u32 s50, s50, 0
	s_cmpk_gt_u32 s51, 0xfd
	s_cbranch_scc0 .LBB0_2092
	s_and_b64 vcc, exec, s[16:17]
	s_cbranch_vccz .LBB0_2095
	s_barrier

; #define PG8_STAGE(bufoff, gbase, voff) do { _Pragma("unroll") for (int _i = 0; _i < 2; ++_i) \
;         __builtin_amdgcn_global_load_lds((const unsigned*)((const char*)(gbase) + (voff)[_i]), (PG8_LAS unsigned*)(lds + (bufoff) + ldsw + _i * 8192), 16, 0, 0); } while (0)
; #define PG8_LDA(dst, b, h) do { _Pragma("unroll") for (int m = 0; m < 4; ++m) _Pragma("unroll") for (int k = 0; k < 2; ++k) dst[m][k] = *(const PG8_LAS bf16x8*)(lds + PG8_SA(b, h) + aoff + m * 2048 + k * 1024); } while (0)
; #define PG8_LDB(dst, b, h) do { _Pragma("unroll") for (int n = 0; n < 2; ++n) _Pragma("unroll") for (int k = 0; k < 2; ++k) dst[n][k] = *(const PG8_LAS bf16x8*)(lds + PG8_SB(b, h) + boff + n * 2048 + k * 1024); } while (0)
; #define PG8_MMA(ai, bj, At, Bt) do { __builtin_amdgcn_s_setprio(1); _Pragma("unroll") for (int m = 0; m < 4; ++m) _Pragma("unroll") for (int n = 0; n < 2; ++n) _Pragma("unroll") for (int k = 0; k < 2; ++k) \
;         acc[ai][bj][m][n] = mma_<I8>(Bt[n][k], At[m][k], acc[ai][bj][m][n]); __builtin_amdgcn_s_setprio(0); } while (0)
; #define PG8_WAIT_V(n) asm volatile("s_waitcnt vmcnt(" #n ")" ::: "memory")
; #define PG8_WAIT_L(n) asm volatile("s_waitcnt lgkmcnt(" #n ")" ::: "memory")
; #define PG8_BAR __builtin_amdgcn_s_barrier()
; template <class Epi, class Sched, bool ALIGN_EPI = false, bool SP2 = false, bool I8 = false>
; __device__ __forceinline__ void gemm_phase(PG8_LAS unsigned char* lds, const Gemm g, const Sched& S, const Epi& E) {
;     ...
;             const bool last = (t == nt - 2);
;             const char* a1 = cA + (size_t)(t + 1) * kstep;
;             const char* a2 = last ? nA : cA + (size_t)(t + 2) * kstep; const char* b2 = last ? nB : cB + (size_t)(t + 2) * kstep;
;             const char* a3 = a2 + kstep; const char* b3 = b2 + kstep;
;             if (last && has_next) S.a_ready(nxt);
;             if constexpr (SP2) {
;             PG8_LDB(B0, 0, 0); PG8_LDB(B1, 0, 1); PG8_SCHED; PG8_LDA(At, 0, 0); PG8_STAGE(PG8_SA(1, 1), a1 + hstepA, voffA);
;             PG8_WAIT_V(8); PG8_WAIT_L(0); PG8_BAR; PG8_MMA(0, 0, At, B0); PG8_MMA(0, 1, At, B1); PG8_BAR; PG8_SCHED;
;             PG8_LDA(At, 0, 1); PG8_STAGE(PG8_SB(0, 0), b2, voffB); PG8_STAGE(PG8_SB(0, 1), b2 + hstepB, voffB); PG8_STAGE(PG8_SA(0, 0), a2, voffA);
;             PG8_WAIT_V(8); PG8_WAIT_L(0); PG8_BAR; PG8_MMA(1, 0, At, B0); PG8_MMA(1, 1, At, B1); PG8_BAR; PG8_SCHED;
.LBB0_2322:
	ds_read_b128 v[58:61], v183
	ds_read_b128 v[66:69], v183 offset:1024
	ds_read_b128 v[74:77], v183 offset:2048
	ds_read_b128 v[78:81], v183 offset:3072
	ds_read_b128 v[146:149], v189
	ds_read_b128 v[150:153], v189 offset:1024
	ds_read_b128 v[154:157], v189 offset:2048
	ds_read_b128 v[158:161], v189 offset:3072
	s_add_u32 s28, s26, 0xfff80080
	s_addc_u32 s29, s27, -1
	s_cmp_eq_u32 s53, 28
	s_cselect_b32 s31, s21, s29
	s_cselect_b32 s30, s49, s28
	s_cselect_b32 s29, s19, s52
	s_cselect_b32 s28, s50, s51
	s_add_i32 m0, s3, 0xc000
	ds_read_b128 v[162:165], v193
	ds_read_b128 v[178:181], v193 offset:1024
	ds_read_b128 v[184:187], v193 offset:2048
	ds_read_b128 v[198:201], v193 offset:3072
	ds_read_b128 v[202:205], v193 offset:4096
	ds_read_b128 v[206:209], v193 offset:5120
	ds_read_b128 v[210:213], v193 offset:6144
	ds_read_b128 v[214:217], v193 offset:7168
	global_load_lds_dwordx4 v170, s[26:27]
	s_add_i32 m0, s3, 0xe000
	s_nop 0
	global_load_lds_dwordx4 v172, s[26:27]
	s_waitcnt vmcnt(8)
	s_waitcnt lgkmcnt(0)
	s_barrier
	s_waitcnt lgkmcnt(0)
	v_mfma_i32_16x16x64_i8 v[142:145], v[58:61], v[162:165], v[142:145]
	v_mfma_i32_16x16x64_i8 v[138:141], v[74:77], v[162:165], v[138:141]
	v_mfma_i32_16x16x64_i8 v[126:129], v[58:61], v[184:187], v[126:129]
	v_mfma_i32_16x16x64_i8 v[122:125], v[74:77], v[184:187], v[122:125]
	v_mfma_i32_16x16x64_i8 v[110:113], v[58:61], v[202:205], v[110:113]
	v_mfma_i32_16x16x64_i8 v[106:109], v[74:77], v[202:205], v[106:109]
	v_mfma_i32_16x16x64_i8 v[94:97], v[58:61], v[210:213], v[94:97]
	v_mfma_i32_16x16x64_i8 v[90:93], v[74:77], v[210:213], v[90:93]
	v_mfma_i32_16x16x64_i8 v[142:145], v[66:69], v[178:181], v[142:145]
	v_mfma_i32_16x16x64_i8 v[138:141], v[78:81], v[178:181], v[138:141]
	v_mfma_i32_16x16x64_i8 v[126:129], v[66:69], v[198:201], v[126:129]
	v_mfma_i32_16x16x64_i8 v[122:125], v[78:81], v[198:201], v[122:125]
	v_mfma_i32_16x16x64_i8 v[110:113], v[66:69], v[206:209], v[110:113]
	v_mfma_i32_16x16x64_i8 v[106:109], v[78:81], v[206:209], v[106:109]
	v_mfma_i32_16x16x64_i8 v[94:97], v[66:69], v[214:217], v[94:97]
	v_mfma_i32_16x16x64_i8 v[90:93], v[78:81], v[214:217], v[90:93]
	v_mfma_i32_16x16x64_i8 v[134:137], v[146:149], v[162:165], v[134:137]
	v_mfma_i32_16x16x64_i8 v[130:133], v[154:157], v[162:165], v[130:133]
	v_mfma_i32_16x16x64_i8 v[118:121], v[146:149], v[184:187], v[118:121]
	v_mfma_i32_16x16x64_i8 v[114:117], v[154:157], v[184:187], v[114:117]
	v_mfma_i32_16x16x64_i8 v[102:105], v[146:149], v[202:205], v[102:105]
	v_mfma_i32_16x16x64_i8 v[98:101], v[154:157], v[202:205], v[98:101]
	v_mfma_i32_16x16x64_i8 v[86:89], v[146:149], v[210:213], v[86:89]
	v_mfma_i32_16x16x64_i8 v[82:85], v[154:157], v[210:213], v[82:85]
	v_mfma_i32_16x16x64_i8 v[134:137], v[150:153], v[178:181], v[134:137]
	v_mfma_i32_16x16x64_i8 v[130:133], v[158:161], v[178:181], v[130:133]
	v_mfma_i32_16x16x64_i8 v[118:121], v[150:153], v[198:201], v[118:121]
	v_mfma_i32_16x16x64_i8 v[114:117], v[158:161], v[198:201], v[114:117]
	v_mfma_i32_16x16x64_i8 v[102:105], v[150:153], v[206:209], v[102:105]
	v_mfma_i32_16x16x64_i8 v[98:101], v[158:161], v[206:209], v[98:101]
	v_mfma_i32_16x16x64_i8 v[86:89], v[150:153], v[214:217], v[86:89]
	v_mfma_i32_16x16x64_i8 v[82:85], v[158:161], v[214:217], v[82:85]
	s_barrier
	s_add_i32 s54, s46, s38
	s_mov_b64 s[98:99], s[28:29]
	s_mov_b32 m0, s54
	ds_read_b128 v[162:165], v193 offset:16384
	ds_read_b128 v[178:181], v193 offset:17408
	ds_read_b128 v[184:187], v193 offset:18432
	ds_read_b128 v[198:201], v193 offset:19456
	ds_read_b128 v[202:205], v193 offset:20480
	ds_read_b128 v[206:209], v193 offset:21504
	ds_read_b128 v[210:213], v193 offset:22528
	ds_read_b128 v[214:217], v193 offset:23552
	global_load_lds_dwordx4 v166, s[28:29]
	s_add_i32 m0, s54, 0x2000
	s_add_u32 s54, s28, 0x80000
	s_mov_b64 s[98:99], s[28:29]
	s_addc_u32 s55, s29, 0
	s_add_i32 s56, s47, s38
	global_load_lds_dwordx4 v168, s[28:29]
	s_mov_b32 m0, s56
	s_mov_b64 s[100:101], s[30:31]
	global_load_lds_dwordx4 v166, s[54:55]
	s_add_i32 m0, s56, 0x2000
	s_nop 0
	global_load_lds_dwordx4 v168, s[54:55]
	s_mov_b64 s[100:101], s[30:31]
	s_mov_b32 m0, s3
	s_nop 0
	global_load_lds_dwordx4 v166, s[30:31]
	s_mov_b32 m0, s39
	s_nop 0
	global_load_lds_dwordx4 v168, s[30:31]
	s_waitcnt vmcnt(8)
	s_waitcnt lgkmcnt(0)
	s_barrier
	s_waitcnt lgkmcnt(0)
	v_mfma_i32_16x16x64_i8 v[70:73], v[58:61], v[162:165], v[70:73]
	v_mfma_i32_16x16x64_i8 v[62:65], v[74:77], v[162:165], v[62:65]
	v_mfma_i32_16x16x64_i8 v[46:49], v[58:61], v[184:187], v[46:49]
	v_mfma_i32_16x16x64_i8 v[42:45], v[74:77], v[184:187], v[42:45]
	v_mfma_i32_16x16x64_i8 v[30:33], v[58:61], v[202:205], v[30:33]
	v_mfma_i32_16x16x64_i8 v[26:29], v[74:77], v[202:205], v[26:29]
	v_mfma_i32_16x16x64_i8 v[14:17], v[58:61], v[210:213], v[14:17]
	v_mfma_i32_16x16x64_i8 v[10:13], v[74:77], v[210:213], v[10:13]
	v_mfma_i32_16x16x64_i8 v[70:73], v[66:69], v[178:181], v[70:73]
	v_mfma_i32_16x16x64_i8 v[62:65], v[78:81], v[178:181], v[62:65]
	v_mfma_i32_16x16x64_i8 v[46:49], v[66:69], v[198:201], v[46:49]
	v_mfma_i32_16x16x64_i8 v[42:45], v[78:81], v[198:201], v[42:45]
	v_mfma_i32_16x16x64_i8 v[30:33], v[66:69], v[206:209], v[30:33]
	v_mfma_i32_16x16x64_i8 v[26:29], v[78:81], v[206:209], v[26:29]
	v_mfma_i32_16x16x64_i8 v[14:17], v[66:69], v[214:217], v[14:17]
	v_mfma_i32_16x16x64_i8 v[10:13], v[78:81], v[214:217], v[10:13]
	v_mfma_i32_16x16x64_i8 v[54:57], v[146:149], v[162:165], v[54:57]
	v_mfma_i32_16x16x64_i8 v[50:53], v[154:157], v[162:165], v[50:53]
	v_mfma_i32_16x16x64_i8 v[38:41], v[146:149], v[184:187], v[38:41]
	v_mfma_i32_16x16x64_i8 v[34:37], v[154:157], v[184:187], v[34:37]
	v_mfma_i32_16x16x64_i8 v[22:25], v[146:149], v[202:205], v[22:25]
	v_mfma_i32_16x16x64_i8 v[18:21], v[154:157], v[202:205], v[18:21]
	v_mfma_i32_16x16x64_i8 v[6:9], v[146:149], v[210:213], v[6:9]
	v_mfma_i32_16x16x64_i8 v[2:5], v[154:157], v[210:213], v[2:5]
	v_mfma_i32_16x16x64_i8 v[54:57], v[150:153], v[178:181], v[54:57]
	v_mfma_i32_16x16x64_i8 v[50:53], v[158:161], v[178:181], v[50:53]
	v_mfma_i32_16x16x64_i8 v[38:41], v[150:153], v[198:201], v[38:41]
	v_mfma_i32_16x16x64_i8 v[34:37], v[158:161], v[198:201], v[34:37]
	v_mfma_i32_16x16x64_i8 v[22:25], v[150:153], v[206:209], v[22:25]
	v_mfma_i32_16x16x64_i8 v[18:21], v[158:161], v[206:209], v[18:21]
	v_mfma_i32_16x16x64_i8 v[6:9], v[150:153], v[214:217], v[6:9]
	v_mfma_i32_16x16x64_i8 v[2:5], v[158:161], v[214:217], v[2:5]
	s_barrier
; #define PG8_STAGE(bufoff, gbase, voff) do { _Pragma("unroll") for (int _i = 0; _i < 2; ++_i) \
;         __builtin_amdgcn_global_load_lds((const unsigned*)((const char*)(gbase) + (voff)[_i]), (PG8_LAS unsigned*)(lds + (bufoff) + ldsw + _i * 8192), 16, 0, 0); } while (0)
; #define PG8_LDA(dst, b, h) do { _Pragma("unroll") for (int m = 0; m < 4; ++m) _Pragma("unroll") for (int k = 0; k < 2; ++k) dst[m][k] = *(const PG8_LAS bf16x8*)(lds + PG8_SA(b, h) + aoff + m * 2048 + k * 1024); } while (0)
; #define PG8_LDB(dst, b, h) do { _Pragma("unroll") for (int n = 0; n < 2; ++n) _Pragma("unroll") for (int k = 0; k < 2; ++k) dst[n][k] = *(const PG8_LAS bf16x8*)(lds + PG8_SB(b, h) + boff + n * 2048 + k * 1024); } while (0)
; #define PG8_MMA(ai, bj, At, Bt) do { __builtin_amdgcn_s_setprio(1); _Pragma("unroll") for (int m = 0; m < 4; ++m) _Pragma("unroll") for (int n = 0; n < 2; ++n) _Pragma("unroll") for (int k = 0; k < 2; ++k) \
;         acc[ai][bj][m][n] = mma_<I8>(Bt[n][k], At[m][k], acc[ai][bj][m][n]); __builtin_amdgcn_s_setprio(0); } while (0)
; #define PG8_WAIT_V(n) asm volatile("s_waitcnt vmcnt(" #n ")" ::: "memory")
; #define PG8_WAIT_L(n) asm volatile("s_waitcnt lgkmcnt(" #n ")" ::: "memory")
; #define PG8_BAR __builtin_amdgcn_s_barrier()
; #define PG8_SCHED __builtin_amdgcn_sched_barrier(0)
; template <class Epi, class Sched, bool ALIGN_EPI = false, bool SP2 = false, bool I8 = false>
; __device__ __forceinline__ void gemm_phase(PG8_LAS unsigned char* lds, const Gemm g, const Sched& S, const Epi& E) {
;     ...
;         for (int t = 0; t < nt; t += 2) {
;     ...
;             PG8_LDB(B0, 1, 0); PG8_LDB(B1, 1, 1); PG8_SCHED; PG8_LDA(At, 1, 0); PG8_STAGE(PG8_SA(0, 1), a2 + hstepA, voffA);
;             PG8_WAIT_V(8); PG8_WAIT_L(0); PG8_BAR; PG8_MMA(0, 0, At, B0); PG8_MMA(0, 1, At, B1); PG8_BAR; PG8_SCHED;
;             PG8_LDA(At, 1, 1); PG8_STAGE(PG8_SB(1, 0), b3, voffB); PG8_STAGE(PG8_SB(1, 1), b3 + hstepB, voffB); PG8_STAGE(PG8_SA(1, 0), a3, voffA);
;             PG8_WAIT_V(8); PG8_WAIT_L(0); PG8_BAR; PG8_MMA(1, 0, At, B0); PG8_MMA(1, 1, At, B1); PG8_BAR; PG8_SCHED;
	s_add_i32 s54, 0, 0x18000
	s_add_i32 s55, 0, 0x1c000
	ds_read_b128 v[58:61], v189 offset:16384
	ds_read_b128 v[66:69], v189 offset:17408
	ds_read_b128 v[74:77], v189 offset:18432
	ds_read_b128 v[78:81], v189 offset:19456
	ds_read_b128 v[146:149], v189 offset:32768
	ds_read_b128 v[150:153], v189 offset:33792
	ds_read_b128 v[154:157], v189 offset:34816
	ds_read_b128 v[158:161], v189 offset:35840
	s_add_u32 s30, s30, 0x80000
	s_addc_u32 s31, s31, 0
	s_mov_b32 m0, s40
	ds_read_b128 v[162:165], v193 offset:32768
	ds_read_b128 v[178:181], v193 offset:33792
	ds_read_b128 v[184:187], v193 offset:34816
	ds_read_b128 v[198:201], v193 offset:35840
	ds_read_b128 v[202:205], v193 offset:36864
	ds_read_b128 v[206:209], v193 offset:37888
	ds_read_b128 v[210:213], v193 offset:38912
	ds_read_b128 v[214:217], v193 offset:39936
	global_load_lds_dwordx4 v166, s[30:31]
	s_mov_b32 m0, s41
	s_nop 0
	global_load_lds_dwordx4 v168, s[30:31]
	s_waitcnt vmcnt(8)
	s_waitcnt lgkmcnt(0)
	s_barrier
	s_waitcnt lgkmcnt(0)
	v_mfma_i32_16x16x64_i8 v[142:145], v[58:61], v[162:165], v[142:145]
	v_mfma_i32_16x16x64_i8 v[138:141], v[74:77], v[162:165], v[138:141]
	v_mfma_i32_16x16x64_i8 v[126:129], v[58:61], v[184:187], v[126:129]
	v_mfma_i32_16x16x64_i8 v[122:125], v[74:77], v[184:187], v[122:125]
	v_mfma_i32_16x16x64_i8 v[110:113], v[58:61], v[202:205], v[110:113]
	v_mfma_i32_16x16x64_i8 v[106:109], v[74:77], v[202:205], v[106:109]
	v_mfma_i32_16x16x64_i8 v[94:97], v[58:61], v[210:213], v[94:97]
	v_mfma_i32_16x16x64_i8 v[90:93], v[74:77], v[210:213], v[90:93]
	v_mfma_i32_16x16x64_i8 v[142:145], v[66:69], v[178:181], v[142:145]
	v_mfma_i32_16x16x64_i8 v[138:141], v[78:81], v[178:181], v[138:141]
	v_mfma_i32_16x16x64_i8 v[126:129], v[66:69], v[198:201], v[126:129]
	v_mfma_i32_16x16x64_i8 v[122:125], v[78:81], v[198:201], v[122:125]
	v_mfma_i32_16x16x64_i8 v[110:113], v[66:69], v[206:209], v[110:113]
	v_mfma_i32_16x16x64_i8 v[106:109], v[78:81], v[206:209], v[106:109]
	v_mfma_i32_16x16x64_i8 v[94:97], v[66:69], v[214:217], v[94:97]
	v_mfma_i32_16x16x64_i8 v[90:93], v[78:81], v[214:217], v[90:93]
	v_mfma_i32_16x16x64_i8 v[134:137], v[146:149], v[162:165], v[134:137]
	v_mfma_i32_16x16x64_i8 v[130:133], v[154:157], v[162:165], v[130:133]
	v_mfma_i32_16x16x64_i8 v[118:121], v[146:149], v[184:187], v[118:121]
	v_mfma_i32_16x16x64_i8 v[114:117], v[154:157], v[184:187], v[114:117]
	v_mfma_i32_16x16x64_i8 v[102:105], v[146:149], v[202:205], v[102:105]
	v_mfma_i32_16x16x64_i8 v[98:101], v[154:157], v[202:205], v[98:101]
	v_mfma_i32_16x16x64_i8 v[86:89], v[146:149], v[210:213], v[86:89]
	v_mfma_i32_16x16x64_i8 v[82:85], v[154:157], v[210:213], v[82:85]
	v_mfma_i32_16x16x64_i8 v[134:137], v[150:153], v[178:181], v[134:137]
	v_mfma_i32_16x16x64_i8 v[130:133], v[158:161], v[178:181], v[130:133]
	v_mfma_i32_16x16x64_i8 v[118:121], v[150:153], v[198:201], v[118:121]
	v_mfma_i32_16x16x64_i8 v[114:117], v[158:161], v[198:201], v[114:117]
	v_mfma_i32_16x16x64_i8 v[102:105], v[150:153], v[206:209], v[102:105]
	v_mfma_i32_16x16x64_i8 v[98:101], v[158:161], v[206:209], v[98:101]
	v_mfma_i32_16x16x64_i8 v[86:89], v[150:153], v[214:217], v[86:89]
	v_mfma_i32_16x16x64_i8 v[82:85], v[158:161], v[214:217], v[82:85]
	s_barrier
	s_add_i32 s30, s54, s38
	s_add_i32 m0, s30, 0xffffff80
	ds_read_b128 v[162:165], v193 offset:49152
	ds_read_b128 v[178:181], v193 offset:50176
	ds_read_b128 v[184:187], v193 offset:51200
	ds_read_b128 v[198:201], v193 offset:52224
	ds_read_b128 v[202:205], v193 offset:53248
	ds_read_b128 v[206:209], v193 offset:54272
	ds_read_b128 v[210:213], v193 offset:55296
	ds_read_b128 v[214:217], v193 offset:56320
	global_load_lds_dwordx4 v166, s[98:99] offset:128
	s_add_i32 m0, s30, 0x1f80
	s_add_u32 s28, s28, 0x80080
	s_addc_u32 s29, s29, 0
	s_add_i32 s30, s55, s38
	global_load_lds_dwordx4 v168, s[98:99] offset:128
	s_mov_b32 m0, s30
	s_nop 0
	global_load_lds_dwordx4 v166, s[28:29]
	s_add_i32 m0, s30, 0x2000
	s_nop 0
	global_load_lds_dwordx4 v168, s[28:29]
	s_add_i32 m0, s43, 0xffffff80
	s_nop 0
	global_load_lds_dwordx4 v166, s[100:101] offset:128
	s_add_i32 m0, s44, 0xffffff80
	s_nop 0
	global_load_lds_dwordx4 v168, s[100:101] offset:128
	s_waitcnt vmcnt(8)
	s_waitcnt lgkmcnt(0)
	s_barrier
	s_waitcnt lgkmcnt(0)
	v_mfma_i32_16x16x64_i8 v[70:73], v[58:61], v[162:165], v[70:73]
	v_mfma_i32_16x16x64_i8 v[62:65], v[74:77], v[162:165], v[62:65]
	v_mfma_i32_16x16x64_i8 v[46:49], v[58:61], v[184:187], v[46:49]
	v_mfma_i32_16x16x64_i8 v[42:45], v[74:77], v[184:187], v[42:45]
	v_mfma_i32_16x16x64_i8 v[30:33], v[58:61], v[202:205], v[30:33]
	v_mfma_i32_16x16x64_i8 v[26:29], v[74:77], v[202:205], v[26:29]
	v_mfma_i32_16x16x64_i8 v[14:17], v[58:61], v[210:213], v[14:17]
	v_mfma_i32_16x16x64_i8 v[10:13], v[74:77], v[210:213], v[10:13]
	v_mfma_i32_16x16x64_i8 v[70:73], v[66:69], v[178:181], v[70:73]
	v_mfma_i32_16x16x64_i8 v[62:65], v[78:81], v[178:181], v[62:65]
	v_mfma_i32_16x16x64_i8 v[46:49], v[66:69], v[198:201], v[46:49]
	v_mfma_i32_16x16x64_i8 v[42:45], v[78:81], v[198:201], v[42:45]
	v_mfma_i32_16x16x64_i8 v[30:33], v[66:69], v[206:209], v[30:33]
	v_mfma_i32_16x16x64_i8 v[26:29], v[78:81], v[206:209], v[26:29]
	v_mfma_i32_16x16x64_i8 v[14:17], v[66:69], v[214:217], v[14:17]
	v_mfma_i32_16x16x64_i8 v[10:13], v[78:81], v[214:217], v[10:13]
	v_mfma_i32_16x16x64_i8 v[54:57], v[146:149], v[162:165], v[54:57]
	v_mfma_i32_16x16x64_i8 v[50:53], v[154:157], v[162:165], v[50:53]
	v_mfma_i32_16x16x64_i8 v[38:41], v[146:149], v[184:187], v[38:41]
	v_mfma_i32_16x16x64_i8 v[34:37], v[154:157], v[184:187], v[34:37]
	v_mfma_i32_16x16x64_i8 v[22:25], v[146:149], v[202:205], v[22:25]
	v_mfma_i32_16x16x64_i8 v[18:21], v[154:157], v[202:205], v[18:21]
	v_mfma_i32_16x16x64_i8 v[6:9], v[146:149], v[210:213], v[6:9]
	v_mfma_i32_16x16x64_i8 v[2:5], v[154:157], v[210:213], v[2:5]
	v_mfma_i32_16x16x64_i8 v[54:57], v[150:153], v[178:181], v[54:57]
	v_mfma_i32_16x16x64_i8 v[50:53], v[158:161], v[178:181], v[50:53]
	v_mfma_i32_16x16x64_i8 v[38:41], v[150:153], v[198:201], v[38:41]
	v_mfma_i32_16x16x64_i8 v[34:37], v[158:161], v[198:201], v[34:37]
	v_mfma_i32_16x16x64_i8 v[22:25], v[150:153], v[206:209], v[22:25]
	v_mfma_i32_16x16x64_i8 v[18:21], v[158:161], v[206:209], v[18:21]
	v_mfma_i32_16x16x64_i8 v[6:9], v[150:153], v[214:217], v[6:9]
	v_mfma_i32_16x16x64_i8 v[2:5], v[158:161], v[214:217], v[2:5]
	s_barrier
	s_add_i32 s53, s53, 2
	s_add_u32 s26, s26, 0x100
	s_addc_u32 s27, s27, 0
	s_add_u32 s51, s51, 0x100
	s_addc_u32 s52, s52, 0
	s_cmp_gt_u32 s53, 29
	s_cbranch_scc0 .LBB0_2322
	s_and_b64 vcc, exec, s[16:17]
	s_cbranch_vccz .LBB0_2325
	s_barrier
